# baseline (speedup 1.0000x reference)
; #define BIG_SYNC(N)                                              \
;   asm volatile("s_waitcnt vmcnt(%0)" ::"n"(N) : "memory");       \
;   __builtin_amdgcn_s_barrier();                                  \
;   asm volatile("" ::: "memory");                                 \
;   __builtin_amdgcn_sched_barrier(0);
; template <int NK, bool BNT = false> ...
;     ...
;   auto kstep = [&](int T, int cur, int nxt, bool do_stage) {
;     const unsigned char* sa = smem + cur * BIG_STAGE;
;     bf16x8 af[4], bfr[4];
; #pragma unroll
;     for (int m = 0; m < 4; ++m) af[m] = *reinterpret_cast<const bf16x8*>(sa + aoff + m * 1024);
; #pragma unroll
;     for (int n = 0; n < 4; ++n) bfr[n] = *reinterpret_cast<const bf16x8*>(sa + boff + n * 1024);
;     __builtin_amdgcn_sched_barrier(0);
;     if (do_stage) stage(T + 3, nxt);
; #pragma unroll
;     for (int m = 0; m < 4; ++m)
; #pragma unroll
;       for (int n = 0; n < 4; ++n) acc[m][n] = __builtin_amdgcn_mfma_f32_16x16x32_bf16(af[m], bfr[n], acc[m][n], 0, 0, 0);
;     if (do_stage) {
; #pragma unroll
;       for (int q = 0; q < NG; ++q) {
;         __builtin_amdgcn_sched_group_barrier(0x008, 3, 0);
;         __builtin_amdgcn_sched_group_barrier(0x010, 1, 0);
;       }
;       __builtin_amdgcn_sched_group_barrier(0x008, 16 - 3 * NG, 0);
;     }
;     __builtin_amdgcn_sched_barrier(0);
; #pragma unroll
;     for (int n = 0; n < 4; ++n) bfr[n] = *reinterpret_cast<const bf16x8*>(sa + boff + (4 + n) * 1024);
; #pragma unroll
;     for (int m = 0; m < 4; ++m)
; #pragma unroll
;       for (int n = 0; n < 4; ++n)
;         acc[m][4 + n] = __builtin_amdgcn_mfma_f32_16x16x32_bf16(af[m], bfr[n], acc[m][4 + n], 0, 0, 0);
;     __builtin_amdgcn_sched_barrier(0);
;   };
;     ...
;   stage(0, 0);
;   stage(1, 1);
;   stage(2, 2);
;   for (int it = 0; it < NK / 4 - 1; ++it) {
;     const int t = it * 4;
;     BIG_SYNC(2 * NG); kstep(t, 0, 3, true);
;     BIG_SYNC(2 * NG); kstep(t + 1, 1, 0, true);
;     BIG_SYNC(2 * NG); kstep(t + 2, 2, 1, true);
;     BIG_SYNC(2 * NG); kstep(t + 3, 3, 2, true);
.LBB0_68:
	v_add_u32_e32 v158, 0x18000, v166
	v_lshl_add_u64 v[144:145], v[138:139], 0, s[36:37]
	v_readfirstlane_b32 s9, v158
	v_add_u32_e32 v159, 0x1a000, v166
	v_lshl_add_u64 v[160:161], v[144:145], 0, s[60:61]
	s_mov_b32 m0, s9
	v_readfirstlane_b32 s9, v159
	s_waitcnt lgkmcnt(3)
	v_mfma_f32_16x16x32_bf16 v[124:127], v[216:219], v[232:235], v[124:127]
	v_lshl_add_u64 v[142:143], v[140:141], 0, s[36:37]
	v_lshl_add_u64 v[182:183], v[142:143], 0, s[60:61]
	v_mfma_f32_16x16x32_bf16 v[108:111], v[220:223], v[232:235], v[108:111]
	v_mfma_f32_16x16x32_bf16 v[88:91], v[224:227], v[232:235], v[88:91]
	s_waitcnt vmcnt(4)
	s_barrier
	global_load_lds_dwordx4 v[160:161], off
	v_lshl_add_u64 v[160:161], v[144:145], 0, s[80:81]
	s_mov_b32 m0, s9
	v_mfma_f32_16x16x32_bf16 v[44:47], v[228:231], v[232:235], v[44:47]
	s_waitcnt lgkmcnt(2)
	v_mfma_f32_16x16x32_bf16 v[120:123], v[216:219], v[236:239], v[120:123]
	ds_read_b128 v[232:235], v168 offset:20480
	v_mfma_f32_16x16x32_bf16 v[104:107], v[220:223], v[236:239], v[104:107]
	global_load_lds_dwordx4 v[160:161], off
	v_add_u32_e32 v160, 0x1c000, v166
	v_add_u32_e32 v161, 0x1e000, v166
	v_readfirstlane_b32 s9, v160
	s_mov_b32 m0, s9
	v_readfirstlane_b32 s9, v161
	v_mfma_f32_16x16x32_bf16 v[76:79], v[224:227], v[236:239], v[76:79]
	v_mfma_f32_16x16x32_bf16 v[40:43], v[228:231], v[236:239], v[40:43]
	s_waitcnt lgkmcnt(2)
	v_mfma_f32_16x16x32_bf16 v[116:119], v[216:219], v[240:243], v[116:119]
	ds_read_b128 v[236:239], v168 offset:21504
	global_load_lds_dwordx4 v[182:183], off
	v_lshl_add_u64 v[182:183], v[142:143], 0, s[80:81]
	s_mov_b32 m0, s9
	v_mfma_f32_16x16x32_bf16 v[100:103], v[220:223], v[240:243], v[100:103]
	v_mfma_f32_16x16x32_bf16 v[68:71], v[224:227], v[240:243], v[68:71]
	v_mfma_f32_16x16x32_bf16 v[36:39], v[228:231], v[240:243], v[36:39]
	global_load_lds_dwordx4 v[182:183], off
	s_waitcnt lgkmcnt(2)
	v_mfma_f32_16x16x32_bf16 v[112:115], v[216:219], v[244:247], v[112:115]
	ds_read_b128 v[240:243], v168 offset:22528
	v_mfma_f32_16x16x32_bf16 v[96:99], v[220:223], v[244:247], v[96:99]
	v_mfma_f32_16x16x32_bf16 v[64:67], v[224:227], v[244:247], v[64:67]
	v_mfma_f32_16x16x32_bf16 v[32:35], v[228:231], v[244:247], v[32:35]
	s_waitcnt lgkmcnt(2)
	v_mfma_f32_16x16x32_bf16 v[92:95], v[216:219], v[232:235], v[92:95]
	ds_read_b128 v[244:247], v168 offset:23552
	v_mfma_f32_16x16x32_bf16 v[60:63], v[220:223], v[232:235], v[60:63]
	ds_read_b128 v[186:189], v167 offset:32768
	v_mfma_f32_16x16x32_bf16 v[28:31], v[224:227], v[232:235], v[28:31]
	ds_read_b128 v[190:193], v167 offset:33792
	v_mfma_f32_16x16x32_bf16 v[12:15], v[228:231], v[232:235], v[12:15]
	ds_read_b128 v[194:197], v167 offset:34816
	s_waitcnt lgkmcnt(5)
	v_mfma_f32_16x16x32_bf16 v[84:87], v[216:219], v[236:239], v[84:87]
	ds_read_b128 v[202:205], v167 offset:35840
	ds_read_b128 v[232:235], v168 offset:49152
	v_mfma_f32_16x16x32_bf16 v[56:59], v[220:223], v[236:239], v[56:59]
	v_mfma_f32_16x16x32_bf16 v[24:27], v[224:227], v[236:239], v[24:27]
	v_mfma_f32_16x16x32_bf16 v[8:11], v[228:231], v[236:239], v[8:11]
	s_waitcnt lgkmcnt(6)
	v_mfma_f32_16x16x32_bf16 v[80:83], v[216:219], v[240:243], v[80:83]
	ds_read_b128 v[236:239], v168 offset:50176
	v_mfma_f32_16x16x32_bf16 v[52:55], v[220:223], v[240:243], v[52:55]
	v_mfma_f32_16x16x32_bf16 v[20:23], v[224:227], v[240:243], v[20:23]
	v_mfma_f32_16x16x32_bf16 v[4:7], v[228:231], v[240:243], v[4:7]
	s_waitcnt lgkmcnt(6)
	v_mfma_f32_16x16x32_bf16 v[72:75], v[216:219], v[244:247], v[72:75]
	ds_read_b128 v[240:243], v168 offset:51200
	v_mfma_f32_16x16x32_bf16 v[48:51], v[220:223], v[244:247], v[48:51]
	v_mfma_f32_16x16x32_bf16 v[16:19], v[224:227], v[244:247], v[16:19]
	v_mfma_f32_16x16x32_bf16 v[0:3], v[228:231], v[244:247], v[0:3]
	ds_read_b128 v[244:247], v168 offset:52224
	v_readfirstlane_b32 s9, v166
	v_lshl_add_u64 v[182:183], v[144:145], 0, s[62:63]
	s_mov_b32 m0, s9
	v_readfirstlane_b32 s9, v146
	s_waitcnt lgkmcnt(3)
	v_mfma_f32_16x16x32_bf16 v[124:127], v[186:189], v[232:235], v[124:127]
	v_lshl_add_u64 v[198:199], v[142:143], 0, s[62:63]
	v_mfma_f32_16x16x32_bf16 v[108:111], v[190:193], v[232:235], v[108:111]
	v_mfma_f32_16x16x32_bf16 v[88:91], v[194:197], v[232:235], v[88:91]
	s_waitcnt vmcnt(4)
	s_barrier
	global_load_lds_dwordx4 v[182:183], off
	v_lshl_add_u64 v[182:183], v[144:145], 0, s[0:1]
	s_mov_b32 m0, s9
	v_readfirstlane_b32 s9, v147
	v_mfma_f32_16x16x32_bf16 v[44:47], v[202:205], v[232:235], v[44:47]
	s_waitcnt lgkmcnt(2)
	v_mfma_f32_16x16x32_bf16 v[120:123], v[186:189], v[236:239], v[120:123]
	ds_read_b128 v[232:235], v168 offset:53248
	v_mfma_f32_16x16x32_bf16 v[104:107], v[190:193], v[236:239], v[104:107]
	global_load_lds_dwordx4 v[182:183], off
	s_mov_b32 m0, s9
	v_readfirstlane_b32 s9, v148
	v_lshl_add_u64 v[182:183], v[142:143], 0, s[0:1]
	v_mfma_f32_16x16x32_bf16 v[76:79], v[194:197], v[236:239], v[76:79]
	v_mfma_f32_16x16x32_bf16 v[40:43], v[202:205], v[236:239], v[40:43]
	s_waitcnt lgkmcnt(2)
	v_mfma_f32_16x16x32_bf16 v[116:119], v[186:189], v[240:243], v[116:119]
	ds_read_b128 v[236:239], v168 offset:54272
	global_load_lds_dwordx4 v[198:199], off
	s_mov_b32 m0, s9
	v_mfma_f32_16x16x32_bf16 v[100:103], v[190:193], v[240:243], v[100:103]
	v_mfma_f32_16x16x32_bf16 v[68:71], v[194:197], v[240:243], v[68:71]
	v_mfma_f32_16x16x32_bf16 v[36:39], v[202:205], v[240:243], v[36:39]
	global_load_lds_dwordx4 v[182:183], off
	s_waitcnt lgkmcnt(2)
	v_mfma_f32_16x16x32_bf16 v[112:115], v[186:189], v[244:247], v[112:115]
	ds_read_b128 v[240:243], v168 offset:55296
	v_mfma_f32_16x16x32_bf16 v[96:99], v[190:193], v[244:247], v[96:99]
	v_mfma_f32_16x16x32_bf16 v[64:67], v[194:197], v[244:247], v[64:67]
	v_mfma_f32_16x16x32_bf16 v[32:35], v[202:205], v[244:247], v[32:35]
	v_add_u32_e32 v162, 0x10000, v167
	v_or_b32_e32 v163, 0x10000, v169
	s_waitcnt lgkmcnt(2)
; #define BIG_SYNC(N)                                              \
;   asm volatile("s_waitcnt vmcnt(%0)" ::"n"(N) : "memory");       \
;   __builtin_amdgcn_s_barrier();                                  \
;   asm volatile("" ::: "memory");                                 \
;   __builtin_amdgcn_sched_barrier(0);
; template <int NK, bool BNT = false> ...
;     ...
;   auto kstep = [&](int T, int cur, int nxt, bool do_stage) {
;     const unsigned char* sa = smem + cur * BIG_STAGE;
;     bf16x8 af[4], bfr[4];
; #pragma unroll
;     for (int m = 0; m < 4; ++m) af[m] = *reinterpret_cast<const bf16x8*>(sa + aoff + m * 1024);
; #pragma unroll
;     for (int n = 0; n < 4; ++n) bfr[n] = *reinterpret_cast<const bf16x8*>(sa + boff + n * 1024);
;     __builtin_amdgcn_sched_barrier(0);
;     if (do_stage) stage(T + 3, nxt);
; #pragma unroll
;     for (int m = 0; m < 4; ++m)
; #pragma unroll
;       for (int n = 0; n < 4; ++n) acc[m][n] = __builtin_amdgcn_mfma_f32_16x16x32_bf16(af[m], bfr[n], acc[m][n], 0, 0, 0);
;     if (do_stage) {
; #pragma unroll
;       for (int q = 0; q < NG; ++q) {
;         __builtin_amdgcn_sched_group_barrier(0x008, 3, 0);
;         __builtin_amdgcn_sched_group_barrier(0x010, 1, 0);
;       }
;       __builtin_amdgcn_sched_group_barrier(0x008, 16 - 3 * NG, 0);
;     }
;     __builtin_amdgcn_sched_barrier(0);
; #pragma unroll
;     for (int n = 0; n < 4; ++n) bfr[n] = *reinterpret_cast<const bf16x8*>(sa + boff + (4 + n) * 1024);
; #pragma unroll
;     for (int m = 0; m < 4; ++m)
; #pragma unroll
;       for (int n = 0; n < 4; ++n)
;         acc[m][4 + n] = __builtin_amdgcn_mfma_f32_16x16x32_bf16(af[m], bfr[n], acc[m][4 + n], 0, 0, 0);
;     __builtin_amdgcn_sched_barrier(0);
;   };
;     ...
;   stage(0, 0);
;   stage(1, 1);
;   stage(2, 2);
;   for (int it = 0; it < NK / 4 - 1; ++it) {
;     const int t = it * 4;
;     BIG_SYNC(2 * NG); kstep(t, 0, 3, true);
;     BIG_SYNC(2 * NG); kstep(t + 1, 1, 0, true);
;     BIG_SYNC(2 * NG); kstep(t + 2, 2, 1, true);
;     BIG_SYNC(2 * NG); kstep(t + 3, 3, 2, true);
	v_mfma_f32_16x16x32_bf16 v[92:95], v[186:189], v[232:235], v[92:95]
	ds_read_b128 v[244:247], v168 offset:56320
	v_mfma_f32_16x16x32_bf16 v[60:63], v[190:193], v[232:235], v[60:63]
	ds_read_b128 v[216:219], v162
	v_mfma_f32_16x16x32_bf16 v[28:31], v[194:197], v[232:235], v[28:31]
	ds_read_b128 v[220:223], v162 offset:1024
	v_mfma_f32_16x16x32_bf16 v[12:15], v[202:205], v[232:235], v[12:15]
	ds_read_b128 v[224:227], v162 offset:2048
	s_waitcnt lgkmcnt(5)
	v_mfma_f32_16x16x32_bf16 v[84:87], v[186:189], v[236:239], v[84:87]
	ds_read_b128 v[228:231], v162 offset:3072
	ds_read_b128 v[232:235], v163
	v_mfma_f32_16x16x32_bf16 v[56:59], v[190:193], v[236:239], v[56:59]
	v_mfma_f32_16x16x32_bf16 v[24:27], v[194:197], v[236:239], v[24:27]
	v_mfma_f32_16x16x32_bf16 v[8:11], v[202:205], v[236:239], v[8:11]
	s_waitcnt lgkmcnt(6)
	v_mfma_f32_16x16x32_bf16 v[80:83], v[186:189], v[240:243], v[80:83]
	ds_read_b128 v[236:239], v163 offset:1024
	v_mfma_f32_16x16x32_bf16 v[52:55], v[190:193], v[240:243], v[52:55]
	v_mfma_f32_16x16x32_bf16 v[20:23], v[194:197], v[240:243], v[20:23]
	v_mfma_f32_16x16x32_bf16 v[4:7], v[202:205], v[240:243], v[4:7]
	s_waitcnt lgkmcnt(6)
	v_mfma_f32_16x16x32_bf16 v[72:75], v[186:189], v[244:247], v[72:75]
	ds_read_b128 v[240:243], v163 offset:2048
	v_mfma_f32_16x16x32_bf16 v[48:51], v[190:193], v[244:247], v[48:51]
	v_mfma_f32_16x16x32_bf16 v[16:19], v[194:197], v[244:247], v[16:19]
	v_mfma_f32_16x16x32_bf16 v[0:3], v[202:205], v[244:247], v[0:3]
	ds_read_b128 v[244:247], v163 offset:3072
	v_add_u32_e32 v162, 0x10000, v167
	v_or_b32_e32 v163, 0x10000, v169
	v_add_u32_e32 v164, 0x10400, v169
	v_add_u32_e32 v165, 0x10800, v169
	v_add_u32_e32 v172, 0x10c00, v169
	v_readfirstlane_b32 s9, v149
	v_lshl_add_u64 v[174:175], v[144:145], 0, s[2:3]
	s_mov_b32 m0, s9
	v_readfirstlane_b32 s9, v150
	s_waitcnt lgkmcnt(3)
	v_mfma_f32_16x16x32_bf16 v[124:127], v[216:219], v[232:235], v[124:127]
	v_lshl_add_u64 v[178:179], v[142:143], 0, s[2:3]
	v_mfma_f32_16x16x32_bf16 v[108:111], v[220:223], v[232:235], v[108:111]
	v_mfma_f32_16x16x32_bf16 v[88:91], v[224:227], v[232:235], v[88:91]
	s_waitcnt vmcnt(4)
	s_barrier
	global_load_lds_dwordx4 v[174:175], off
	v_lshl_add_u64 v[174:175], v[144:145], 0, s[52:53]
	s_mov_b32 m0, s9
	v_readfirstlane_b32 s9, v151
	v_mfma_f32_16x16x32_bf16 v[44:47], v[228:231], v[232:235], v[44:47]
	s_waitcnt lgkmcnt(2)
	v_mfma_f32_16x16x32_bf16 v[120:123], v[216:219], v[236:239], v[120:123]
	ds_read_b128 v[232:235], v163 offset:4096
	v_mfma_f32_16x16x32_bf16 v[104:107], v[220:223], v[236:239], v[104:107]
	global_load_lds_dwordx4 v[174:175], off
	s_mov_b32 m0, s9
	v_readfirstlane_b32 s9, v152
	v_lshl_add_u64 v[174:175], v[142:143], 0, s[52:53]
	v_mfma_f32_16x16x32_bf16 v[76:79], v[224:227], v[236:239], v[76:79]
	v_mfma_f32_16x16x32_bf16 v[40:43], v[228:231], v[236:239], v[40:43]
	s_waitcnt lgkmcnt(2)
	v_mfma_f32_16x16x32_bf16 v[116:119], v[216:219], v[240:243], v[116:119]
	ds_read_b128 v[236:239], v163 offset:5120
	global_load_lds_dwordx4 v[178:179], off
	s_mov_b32 m0, s9
	v_mfma_f32_16x16x32_bf16 v[100:103], v[220:223], v[240:243], v[100:103]
	v_mfma_f32_16x16x32_bf16 v[68:71], v[224:227], v[240:243], v[68:71]
	v_mfma_f32_16x16x32_bf16 v[36:39], v[228:231], v[240:243], v[36:39]
	global_load_lds_dwordx4 v[174:175], off
	s_waitcnt lgkmcnt(2)
	v_mfma_f32_16x16x32_bf16 v[112:115], v[216:219], v[244:247], v[112:115]
	ds_read_b128 v[240:243], v163 offset:6144
	v_mfma_f32_16x16x32_bf16 v[96:99], v[220:223], v[244:247], v[96:99]
	v_mfma_f32_16x16x32_bf16 v[64:67], v[224:227], v[244:247], v[64:67]
	v_mfma_f32_16x16x32_bf16 v[32:35], v[228:231], v[244:247], v[32:35]
	v_add_u32_e32 v173, 0x11000, v169
	v_add_u32_e32 v174, 0x11400, v169
	v_add_u32_e32 v175, 0x11800, v169
	v_add_u32_e32 v178, 0x11c00, v169
	v_add_u32_e32 v162, 0x10000, v167
	v_or_b32_e32 v163, 0x10000, v169
	s_waitcnt lgkmcnt(2)
	v_mfma_f32_16x16x32_bf16 v[92:95], v[216:219], v[232:235], v[92:95]
	ds_read_b128 v[244:247], v163 offset:7168
	v_mfma_f32_16x16x32_bf16 v[60:63], v[220:223], v[232:235], v[60:63]
	ds_read_b128 v[186:189], v162 offset:32768
	v_mfma_f32_16x16x32_bf16 v[28:31], v[224:227], v[232:235], v[28:31]
	ds_read_b128 v[190:193], v162 offset:33792
	v_mfma_f32_16x16x32_bf16 v[12:15], v[228:231], v[232:235], v[12:15]
	ds_read_b128 v[194:197], v162 offset:34816
	s_waitcnt lgkmcnt(5)
	v_mfma_f32_16x16x32_bf16 v[84:87], v[216:219], v[236:239], v[84:87]
	ds_read_b128 v[202:205], v162 offset:35840
	ds_read_b128 v[232:235], v163 offset:32768
	v_mfma_f32_16x16x32_bf16 v[56:59], v[220:223], v[236:239], v[56:59]
	v_mfma_f32_16x16x32_bf16 v[24:27], v[224:227], v[236:239], v[24:27]
	v_mfma_f32_16x16x32_bf16 v[8:11], v[228:231], v[236:239], v[8:11]
	s_waitcnt lgkmcnt(6)
	v_mfma_f32_16x16x32_bf16 v[80:83], v[216:219], v[240:243], v[80:83]
	ds_read_b128 v[236:239], v163 offset:33792
	v_mfma_f32_16x16x32_bf16 v[52:55], v[220:223], v[240:243], v[52:55]
	v_mfma_f32_16x16x32_bf16 v[20:23], v[224:227], v[240:243], v[20:23]
	v_mfma_f32_16x16x32_bf16 v[4:7], v[228:231], v[240:243], v[4:7]
	s_waitcnt lgkmcnt(6)
	v_mfma_f32_16x16x32_bf16 v[72:75], v[216:219], v[244:247], v[72:75]
	ds_read_b128 v[240:243], v163 offset:34816
	v_mfma_f32_16x16x32_bf16 v[48:51], v[220:223], v[244:247], v[48:51]
	v_mfma_f32_16x16x32_bf16 v[16:19], v[224:227], v[244:247], v[16:19]
	v_mfma_f32_16x16x32_bf16 v[0:3], v[228:231], v[244:247], v[0:3]
	ds_read_b128 v[244:247], v163 offset:35840
	v_add_u32_e32 v176, 0x18000, v167
	v_or_b32_e32 v179, 0x18000, v169
	v_add_u32_e32 v180, 0x18400, v169
	v_add_u32_e32 v181, 0x18800, v169
	v_add_u32_e32 v182, 0x18c00, v169
	v_readfirstlane_b32 s9, v154
	v_lshl_add_u64 v[248:249], v[144:145], 0, s[54:55]
	s_mov_b32 m0, s9
	v_readfirstlane_b32 s9, v155
	v_lshl_add_u64 v[144:145], v[144:145], 0, s[56:57]
	s_waitcnt lgkmcnt(3)
	v_mfma_f32_16x16x32_bf16 v[124:127], v[186:189], v[232:235], v[124:127]
	v_lshl_add_u64 v[250:251], v[142:143], 0, s[54:55]
	v_lshl_add_u64 v[142:143], v[142:143], 0, s[56:57]
	v_mfma_f32_16x16x32_bf16 v[108:111], v[190:193], v[232:235], v[108:111]
	v_mfma_f32_16x16x32_bf16 v[88:91], v[194:197], v[232:235], v[88:91]
	s_waitcnt vmcnt(4)
	s_barrier
; #define BIG_SYNC(N)                                              \
;   asm volatile("s_waitcnt vmcnt(%0)" ::"n"(N) : "memory");       \
;   __builtin_amdgcn_s_barrier();                                  \
;   asm volatile("" ::: "memory");                                 \
;   __builtin_amdgcn_sched_barrier(0);
; template <int NK, bool BNT = false> ...
;     ...
;   auto kstep = [&](int T, int cur, int nxt, bool do_stage) {
;     const unsigned char* sa = smem + cur * BIG_STAGE;
;     bf16x8 af[4], bfr[4];
; #pragma unroll
;     for (int m = 0; m < 4; ++m) af[m] = *reinterpret_cast<const bf16x8*>(sa + aoff + m * 1024);
; #pragma unroll
;     for (int n = 0; n < 4; ++n) bfr[n] = *reinterpret_cast<const bf16x8*>(sa + boff + n * 1024);
;     __builtin_amdgcn_sched_barrier(0);
;     if (do_stage) stage(T + 3, nxt);
; #pragma unroll
;     for (int m = 0; m < 4; ++m)
; #pragma unroll
;       for (int n = 0; n < 4; ++n) acc[m][n] = __builtin_amdgcn_mfma_f32_16x16x32_bf16(af[m], bfr[n], acc[m][n], 0, 0, 0);
;     if (do_stage) {
; #pragma unroll
;       for (int q = 0; q < NG; ++q) {
;         __builtin_amdgcn_sched_group_barrier(0x008, 3, 0);
;         __builtin_amdgcn_sched_group_barrier(0x010, 1, 0);
;       }
;       __builtin_amdgcn_sched_group_barrier(0x008, 16 - 3 * NG, 0);
;     }
;     __builtin_amdgcn_sched_barrier(0);
; #pragma unroll
;     for (int n = 0; n < 4; ++n) bfr[n] = *reinterpret_cast<const bf16x8*>(sa + boff + (4 + n) * 1024);
; #pragma unroll
;     for (int m = 0; m < 4; ++m)
; #pragma unroll
;       for (int n = 0; n < 4; ++n)
;         acc[m][4 + n] = __builtin_amdgcn_mfma_f32_16x16x32_bf16(af[m], bfr[n], acc[m][4 + n], 0, 0, 0);
;     __builtin_amdgcn_sched_barrier(0);
;   };
;     ...
;   stage(0, 0);
;   stage(1, 1);
;   stage(2, 2);
;   for (int it = 0; it < NK / 4 - 1; ++it) {
;     const int t = it * 4;
;     BIG_SYNC(2 * NG); kstep(t, 0, 3, true);
;     BIG_SYNC(2 * NG); kstep(t + 1, 1, 0, true);
;     BIG_SYNC(2 * NG); kstep(t + 2, 2, 1, true);
;     BIG_SYNC(2 * NG); kstep(t + 3, 3, 2, true);
;   }
;   BIG_SYNC(2 * NG); kstep(NK - 4, 0, 3, true);
	global_load_lds_dwordx4 v[248:249], off
	s_mov_b32 m0, s9
	v_readfirstlane_b32 s9, v156
	v_mfma_f32_16x16x32_bf16 v[44:47], v[202:205], v[232:235], v[44:47]
	s_waitcnt lgkmcnt(2)
	v_mfma_f32_16x16x32_bf16 v[120:123], v[186:189], v[236:239], v[120:123]
	ds_read_b128 v[232:235], v163 offset:36864
	v_mfma_f32_16x16x32_bf16 v[104:107], v[190:193], v[236:239], v[104:107]
	global_load_lds_dwordx4 v[144:145], off
	s_mov_b32 m0, s9
	v_readfirstlane_b32 s9, v157
	v_mfma_f32_16x16x32_bf16 v[76:79], v[194:197], v[236:239], v[76:79]
	v_mfma_f32_16x16x32_bf16 v[40:43], v[202:205], v[236:239], v[40:43]
	s_waitcnt lgkmcnt(2)
	v_mfma_f32_16x16x32_bf16 v[116:119], v[186:189], v[240:243], v[116:119]
	ds_read_b128 v[236:239], v163 offset:37888
	global_load_lds_dwordx4 v[250:251], off
	s_mov_b32 m0, s9
	v_mfma_f32_16x16x32_bf16 v[100:103], v[190:193], v[240:243], v[100:103]
	v_mfma_f32_16x16x32_bf16 v[68:71], v[194:197], v[240:243], v[68:71]
	v_mfma_f32_16x16x32_bf16 v[36:39], v[202:205], v[240:243], v[36:39]
	global_load_lds_dwordx4 v[142:143], off
	s_waitcnt lgkmcnt(2)
	v_mfma_f32_16x16x32_bf16 v[112:115], v[186:189], v[244:247], v[112:115]
	ds_read_b128 v[240:243], v163 offset:38912
	v_mfma_f32_16x16x32_bf16 v[96:99], v[190:193], v[244:247], v[96:99]
	v_mfma_f32_16x16x32_bf16 v[64:67], v[194:197], v[244:247], v[64:67]
	v_mfma_f32_16x16x32_bf16 v[32:35], v[202:205], v[244:247], v[32:35]
	v_add_u32_e32 v142, 0x19000, v169
	v_add_u32_e32 v143, 0x19400, v169
	v_add_u32_e32 v144, 0x19800, v169
	v_add_u32_e32 v145, 0x19c00, v169
	s_waitcnt lgkmcnt(2)
	v_mfma_f32_16x16x32_bf16 v[92:95], v[186:189], v[232:235], v[92:95]
	ds_read_b128 v[244:247], v163 offset:39936
	v_mfma_f32_16x16x32_bf16 v[60:63], v[190:193], v[232:235], v[60:63]
	ds_read_b128 v[216:219], v167
	v_mfma_f32_16x16x32_bf16 v[28:31], v[194:197], v[232:235], v[28:31]
	ds_read_b128 v[220:223], v167 offset:1024
	v_mfma_f32_16x16x32_bf16 v[12:15], v[202:205], v[232:235], v[12:15]
	ds_read_b128 v[224:227], v167 offset:2048
	s_waitcnt lgkmcnt(5)
	v_mfma_f32_16x16x32_bf16 v[84:87], v[186:189], v[236:239], v[84:87]
	ds_read_b128 v[228:231], v167 offset:3072
	ds_read_b128 v[232:235], v168 offset:16384
	v_mfma_f32_16x16x32_bf16 v[56:59], v[190:193], v[236:239], v[56:59]
	v_mfma_f32_16x16x32_bf16 v[24:27], v[194:197], v[236:239], v[24:27]
	v_mfma_f32_16x16x32_bf16 v[8:11], v[202:205], v[236:239], v[8:11]
	s_waitcnt lgkmcnt(6)
	v_mfma_f32_16x16x32_bf16 v[80:83], v[186:189], v[240:243], v[80:83]
	ds_read_b128 v[236:239], v168 offset:17408
	v_mfma_f32_16x16x32_bf16 v[52:55], v[190:193], v[240:243], v[52:55]
	v_mfma_f32_16x16x32_bf16 v[20:23], v[194:197], v[240:243], v[20:23]
	v_mfma_f32_16x16x32_bf16 v[4:7], v[202:205], v[240:243], v[4:7]
	s_waitcnt lgkmcnt(6)
	v_mfma_f32_16x16x32_bf16 v[72:75], v[186:189], v[244:247], v[72:75]
	ds_read_b128 v[240:243], v168 offset:18432
	v_mfma_f32_16x16x32_bf16 v[48:51], v[190:193], v[244:247], v[48:51]
	v_mfma_f32_16x16x32_bf16 v[16:19], v[194:197], v[244:247], v[16:19]
	v_mfma_f32_16x16x32_bf16 v[0:3], v[202:205], v[244:247], v[0:3]
	ds_read_b128 v[244:247], v168 offset:19456
	s_add_u32 s36, s36, 0x8000
	s_addc_u32 s37, s37, 0
	s_cmp_lg_u32 s36, 0x38000
	s_cbranch_scc1 .LBB0_68
	s_sext_i32_i8 s9, s14
	s_mov_b64 s[18:19], 0x3e000
	v_readfirstlane_b32 s11, v158
	v_lshl_add_u64 v[150:151], v[130:131], 0, s[18:19]
	v_lshl_add_u64 v[198:199], v[128:129], 0, s[18:19]
	s_mov_b32 m0, s11
	s_mov_b64 s[18:19], 0x7e000
	v_readfirstlane_b32 s11, v159
	v_lshl_add_u64 v[130:131], v[130:131], 0, s[18:19]
	s_waitcnt lgkmcnt(3)
	v_mfma_f32_16x16x32_bf16 v[124:127], v[216:219], v[232:235], v[124:127]
	v_lshl_add_u64 v[128:129], v[128:129], 0, s[18:19]
	v_mfma_f32_16x16x32_bf16 v[108:111], v[220:223], v[232:235], v[108:111]
	v_mfma_f32_16x16x32_bf16 v[88:91], v[224:227], v[232:235], v[88:91]
	s_waitcnt vmcnt(4)
	s_barrier
	global_load_lds_dwordx4 v[150:151], off
	s_mov_b32 m0, s11
	v_readfirstlane_b32 s11, v160
	v_mfma_f32_16x16x32_bf16 v[44:47], v[228:231], v[232:235], v[44:47]
	s_waitcnt lgkmcnt(2)
	v_mfma_f32_16x16x32_bf16 v[120:123], v[216:219], v[236:239], v[120:123]
	ds_read_b128 v[232:235], v168 offset:20480
	v_mfma_f32_16x16x32_bf16 v[104:107], v[220:223], v[236:239], v[104:107]
	global_load_lds_dwordx4 v[130:131], off
	s_mov_b32 m0, s11
	v_readfirstlane_b32 s11, v161
	v_mfma_f32_16x16x32_bf16 v[76:79], v[224:227], v[236:239], v[76:79]
	v_mfma_f32_16x16x32_bf16 v[40:43], v[228:231], v[236:239], v[40:43]
	s_waitcnt lgkmcnt(2)
	v_mfma_f32_16x16x32_bf16 v[116:119], v[216:219], v[240:243], v[116:119]
	ds_read_b128 v[236:239], v168 offset:21504
	global_load_lds_dwordx4 v[198:199], off
	s_mov_b32 m0, s11
	v_mfma_f32_16x16x32_bf16 v[100:103], v[220:223], v[240:243], v[100:103]
	v_mfma_f32_16x16x32_bf16 v[68:71], v[224:227], v[240:243], v[68:71]
	v_mfma_f32_16x16x32_bf16 v[36:39], v[228:231], v[240:243], v[36:39]
	global_load_lds_dwordx4 v[128:129], off
	s_waitcnt lgkmcnt(2)
	v_mfma_f32_16x16x32_bf16 v[112:115], v[216:219], v[244:247], v[112:115]
	ds_read_b128 v[240:243], v168 offset:22528
	v_mfma_f32_16x16x32_bf16 v[96:99], v[220:223], v[244:247], v[96:99]
	v_mfma_f32_16x16x32_bf16 v[64:67], v[224:227], v[244:247], v[64:67]
	v_mfma_f32_16x16x32_bf16 v[32:35], v[228:231], v[244:247], v[32:35]
	s_waitcnt lgkmcnt(2)
	v_mfma_f32_16x16x32_bf16 v[92:95], v[216:219], v[232:235], v[92:95]
	ds_read_b128 v[244:247], v168 offset:23552
	v_mfma_f32_16x16x32_bf16 v[60:63], v[220:223], v[232:235], v[60:63]
	ds_read_b128 v[186:189], v167 offset:32768
	v_mfma_f32_16x16x32_bf16 v[28:31], v[224:227], v[232:235], v[28:31]
	ds_read_b128 v[190:193], v167 offset:33792
	v_mfma_f32_16x16x32_bf16 v[12:15], v[228:231], v[232:235], v[12:15]
	ds_read_b128 v[194:197], v167 offset:34816
	s_waitcnt lgkmcnt(5)
; #define BIG_SYNC(N)                                              \
;   asm volatile("s_waitcnt vmcnt(%0)" ::"n"(N) : "memory");       \
;   __builtin_amdgcn_s_barrier();                                  \
;   asm volatile("" ::: "memory");                                 \
;   __builtin_amdgcn_sched_barrier(0);
; template <int NK, bool BNT = false> ...
;     ...
;   BIG_SYNC(2 * NG); kstep(NK - 4, 0, 3, true);
;   BIG_SYNC(2 * NG); kstep(NK - 3, 1, 0, false);
;   BIG_SYNC(NG);     kstep(NK - 2, 2, 0, false);
;   BIG_SYNC(0);      kstep(NK - 1, 3, 0, false);
	v_mfma_f32_16x16x32_bf16 v[84:87], v[216:219], v[236:239], v[84:87]
	ds_read_b128 v[202:205], v167 offset:35840
	ds_read_b128 v[232:235], v168 offset:49152
	v_mfma_f32_16x16x32_bf16 v[56:59], v[220:223], v[236:239], v[56:59]
	v_mfma_f32_16x16x32_bf16 v[24:27], v[224:227], v[236:239], v[24:27]
	v_mfma_f32_16x16x32_bf16 v[8:11], v[228:231], v[236:239], v[8:11]
	s_waitcnt lgkmcnt(6)
	v_mfma_f32_16x16x32_bf16 v[80:83], v[216:219], v[240:243], v[80:83]
	ds_read_b128 v[236:239], v168 offset:50176
	v_mfma_f32_16x16x32_bf16 v[52:55], v[220:223], v[240:243], v[52:55]
	v_mfma_f32_16x16x32_bf16 v[20:23], v[224:227], v[240:243], v[20:23]
	v_mfma_f32_16x16x32_bf16 v[4:7], v[228:231], v[240:243], v[4:7]
	s_waitcnt lgkmcnt(6)
	v_mfma_f32_16x16x32_bf16 v[72:75], v[216:219], v[244:247], v[72:75]
	ds_read_b128 v[240:243], v168 offset:51200
	v_mfma_f32_16x16x32_bf16 v[48:51], v[220:223], v[244:247], v[48:51]
	v_mfma_f32_16x16x32_bf16 v[16:19], v[224:227], v[244:247], v[16:19]
	v_mfma_f32_16x16x32_bf16 v[0:3], v[228:231], v[244:247], v[0:3]
	ds_read_b128 v[244:247], v168 offset:52224
	s_waitcnt lgkmcnt(3)
	v_mfma_f32_16x16x32_bf16 v[124:127], v[186:189], v[232:235], v[124:127]
	v_mfma_f32_16x16x32_bf16 v[108:111], v[190:193], v[232:235], v[108:111]
	v_mfma_f32_16x16x32_bf16 v[88:91], v[194:197], v[232:235], v[88:91]
	v_mfma_f32_16x16x32_bf16 v[44:47], v[202:205], v[232:235], v[44:47]
	s_waitcnt vmcnt(4)
	s_barrier
	s_waitcnt lgkmcnt(2)
	v_mfma_f32_16x16x32_bf16 v[120:123], v[186:189], v[236:239], v[120:123]
	ds_read_b128 v[232:235], v168 offset:53248
	v_mfma_f32_16x16x32_bf16 v[104:107], v[190:193], v[236:239], v[104:107]
	v_mfma_f32_16x16x32_bf16 v[76:79], v[194:197], v[236:239], v[76:79]
	v_mfma_f32_16x16x32_bf16 v[40:43], v[202:205], v[236:239], v[40:43]
	s_waitcnt lgkmcnt(2)
	v_mfma_f32_16x16x32_bf16 v[116:119], v[186:189], v[240:243], v[116:119]
	ds_read_b128 v[236:239], v168 offset:54272
	v_mfma_f32_16x16x32_bf16 v[100:103], v[190:193], v[240:243], v[100:103]
	v_mfma_f32_16x16x32_bf16 v[68:71], v[194:197], v[240:243], v[68:71]
	v_mfma_f32_16x16x32_bf16 v[36:39], v[202:205], v[240:243], v[36:39]
	s_waitcnt lgkmcnt(2)
	v_mfma_f32_16x16x32_bf16 v[112:115], v[186:189], v[244:247], v[112:115]
	ds_read_b128 v[240:243], v168 offset:55296
	v_mfma_f32_16x16x32_bf16 v[96:99], v[190:193], v[244:247], v[96:99]
	v_mfma_f32_16x16x32_bf16 v[64:67], v[194:197], v[244:247], v[64:67]
	v_mfma_f32_16x16x32_bf16 v[32:35], v[202:205], v[244:247], v[32:35]
	s_waitcnt lgkmcnt(2)
	v_mfma_f32_16x16x32_bf16 v[92:95], v[186:189], v[232:235], v[92:95]
	ds_read_b128 v[244:247], v168 offset:56320
	v_mfma_f32_16x16x32_bf16 v[60:63], v[190:193], v[232:235], v[60:63]
	v_mfma_f32_16x16x32_bf16 v[28:31], v[194:197], v[232:235], v[28:31]
	v_mfma_f32_16x16x32_bf16 v[12:15], v[202:205], v[232:235], v[12:15]
	s_waitcnt lgkmcnt(2)
	v_mfma_f32_16x16x32_bf16 v[84:87], v[186:189], v[236:239], v[84:87]
	v_mfma_f32_16x16x32_bf16 v[56:59], v[190:193], v[236:239], v[56:59]
	v_mfma_f32_16x16x32_bf16 v[24:27], v[194:197], v[236:239], v[24:27]
	v_mfma_f32_16x16x32_bf16 v[8:11], v[202:205], v[236:239], v[8:11]
	s_waitcnt lgkmcnt(1)
	v_mfma_f32_16x16x32_bf16 v[80:83], v[186:189], v[240:243], v[80:83]
	v_mfma_f32_16x16x32_bf16 v[52:55], v[190:193], v[240:243], v[52:55]
	v_mfma_f32_16x16x32_bf16 v[20:23], v[194:197], v[240:243], v[20:23]
	v_mfma_f32_16x16x32_bf16 v[4:7], v[202:205], v[240:243], v[4:7]
	s_waitcnt lgkmcnt(0)
	v_mfma_f32_16x16x32_bf16 v[72:75], v[186:189], v[244:247], v[72:75]
	v_mfma_f32_16x16x32_bf16 v[48:51], v[190:193], v[244:247], v[48:51]
	v_mfma_f32_16x16x32_bf16 v[16:19], v[194:197], v[244:247], v[16:19]
	v_mfma_f32_16x16x32_bf16 v[0:3], v[202:205], v[244:247], v[0:3]
	v_mov_b32_e32 v186, 0xf149f2ca
	v_mov_b32_e32 v187, 0x3c0881c4
	v_mov_b32_e32 v188, 0xbab64f3b
	v_mov_b32_e32 v189, 0x24800
	v_mov_b32_e32 v190, 1
	v_mov_b32_e32 v191, 0x24804
	v_mov_b32_e32 v192, 0xfcf
	v_mov_b32_e32 v193, 0x7cf
	v_mov_b32_e32 v194, 0xfdf
	v_mov_b32_e32 v195, 0x7df
	v_mov_b32_e32 v196, 0xfef
	v_mov_b32_e32 v197, 0x7ef
	v_mov_b32_e32 v198, 0xfff
	v_mov_b32_e32 v199, 0x7ff
	v_mov_b32_e32 v200, 0x20000
	v_mov_b32_e32 v201, 0xf8f
	v_mov_b32_e32 v202, 0x78f
	v_mov_b32_e32 v203, 0xf9f
	v_mov_b32_e32 v204, 0x79f
	v_mov_b32_e32 v205, 0xfaf
	s_waitcnt vmcnt(4)
	s_barrier
; #define BIG_SYNC(N)                                              \
;   asm volatile("s_waitcnt vmcnt(%0)" ::"n"(N) : "memory");       \
;   __builtin_amdgcn_s_barrier();                                  \
;   asm volatile("" ::: "memory");                                 \
;   __builtin_amdgcn_sched_barrier(0);
; template <int NK, bool BNT = false> ...
;     ...
; #pragma unroll
;     for (int n = 0; n < 4; ++n) bfr[n] = *reinterpret_cast<const bf16x8*>(sa + boff + (4 + n) * 1024);
; #pragma unroll
;     for (int m = 0; m < 4; ++m)
; #pragma unroll
;       for (int n = 0; n < 4; ++n)
;         acc[m][4 + n] = __builtin_amdgcn_mfma_f32_16x16x32_bf16(af[m], bfr[n], acc[m][4 + n], 0, 0, 0);
;     __builtin_amdgcn_sched_barrier(0);
;   };
;     ...
;   stage(0, 0);
;   stage(1, 1);
;   stage(2, 2);
;   for (int it = 0; it < NK / 4 - 1; ++it) {
;     const int t = it * 4;
;     BIG_SYNC(2 * NG); kstep(t, 0, 3, true);
;     BIG_SYNC(2 * NG); kstep(t + 1, 1, 0, true);
;     BIG_SYNC(2 * NG); kstep(t + 2, 2, 1, true);
;     BIG_SYNC(2 * NG); kstep(t + 3, 3, 2, true);
;   }
;   BIG_SYNC(2 * NG); kstep(NK - 4, 0, 3, true);
;   BIG_SYNC(2 * NG); kstep(NK - 3, 1, 0, false);
;   BIG_SYNC(NG);     kstep(NK - 2, 2, 0, false);
;   BIG_SYNC(0);      kstep(NK - 1, 3, 0, false);
	ds_read_b128 v[128:131], v162
	ds_read_b128 v[138:141], v162 offset:1024
	ds_read_b128 v[146:149], v162 offset:2048
	ds_read_b128 v[154:157], v162 offset:3072
	ds_read_b128 v[158:161], v163
	ds_read_b128 v[216:219], v164
	ds_read_b128 v[162:165], v165
	ds_read_b128 v[220:223], v172
	s_waitcnt lgkmcnt(0)
	v_mfma_f32_16x16x32_bf16 v[124:127], v[128:131], v[158:161], v[124:127]
	v_mfma_f32_16x16x32_bf16 v[116:119], v[128:131], v[162:165], v[116:119]
	v_mfma_f32_16x16x32_bf16 v[112:115], v[128:131], v[220:223], v[112:115]
	v_mfma_f32_16x16x32_bf16 v[104:107], v[138:141], v[216:219], v[104:107]
	v_mfma_f32_16x16x32_bf16 v[100:103], v[138:141], v[162:165], v[100:103]
	v_mfma_f32_16x16x32_bf16 v[96:99], v[138:141], v[220:223], v[96:99]
	v_mfma_f32_16x16x32_bf16 v[68:71], v[146:149], v[162:165], v[68:71]
	v_mfma_f32_16x16x32_bf16 v[64:67], v[146:149], v[220:223], v[64:67]
	v_mfma_f32_16x16x32_bf16 v[44:47], v[154:157], v[158:161], v[44:47]
	v_mfma_f32_16x16x32_bf16 v[40:43], v[154:157], v[216:219], v[40:43]
	v_mfma_f32_16x16x32_bf16 v[36:39], v[154:157], v[162:165], v[36:39]
	v_mfma_f32_16x16x32_bf16 v[32:35], v[154:157], v[220:223], v[32:35]
	v_mfma_f32_16x16x32_bf16 v[120:123], v[128:131], v[216:219], v[120:123]
	v_mfma_f32_16x16x32_bf16 v[224:227], v[138:141], v[158:161], v[108:111]
	v_mfma_f32_16x16x32_bf16 v[228:231], v[146:149], v[158:161], v[88:91]
	v_mfma_f32_16x16x32_bf16 v[232:235], v[146:149], v[216:219], v[76:79]
	s_nop 2
	ds_read_b128 v[76:79], v173
	ds_read_b128 v[88:91], v174
	s_waitcnt lgkmcnt(0)
	v_mfma_f32_16x16x32_bf16 v[158:161], v[128:131], v[76:79], v[92:95]
	s_nop 2
	ds_read_b128 v[92:95], v178
	v_mfma_f32_16x16x32_bf16 v[162:165], v[128:131], v[88:91], v[84:87]
	s_nop 2
	ds_read_b128 v[84:87], v175
	s_waitcnt lgkmcnt(0)
	v_mfma_f32_16x16x32_bf16 v[172:175], v[128:131], v[84:87], v[80:83]
	v_mfma_f32_16x16x32_bf16 v[128:131], v[128:131], v[92:95], v[72:75]
	v_mfma_f32_16x16x32_bf16 v[216:219], v[138:141], v[76:79], v[60:63]
	v_mfma_f32_16x16x32_bf16 v[220:223], v[138:141], v[88:91], v[56:59]
	v_mfma_f32_16x16x32_bf16 v[52:55], v[138:141], v[84:87], v[52:55]
	v_mfma_f32_16x16x32_bf16 v[48:51], v[138:141], v[92:95], v[48:51]
	v_mfma_f32_16x16x32_bf16 v[138:141], v[146:149], v[76:79], v[28:31]
	v_mfma_f32_16x16x32_bf16 v[236:239], v[146:149], v[88:91], v[24:27]
	v_mfma_f32_16x16x32_bf16 v[20:23], v[146:149], v[84:87], v[20:23]
	v_mfma_f32_16x16x32_bf16 v[16:19], v[146:149], v[92:95], v[16:19]
	v_mfma_f32_16x16x32_bf16 v[146:149], v[154:157], v[76:79], v[12:15]
	v_mfma_f32_16x16x32_bf16 v[0:3], v[154:157], v[92:95], v[0:3]
	v_mfma_f32_16x16x32_bf16 v[240:243], v[154:157], v[88:91], v[8:11]
	v_mfma_f32_16x16x32_bf16 v[244:247], v[154:157], v[84:87], v[4:7]
	s_waitcnt vmcnt(0)
	s_barrier
	s_nop 1
	ds_read_b128 v[4:7], v176
	ds_read_b128 v[8:11], v176 offset:1024
	ds_read_b128 v[154:157], v176 offset:2048
	ds_read_b128 v[12:15], v179
	ds_read_b128 v[24:27], v180
	ds_read_b128 v[28:31], v181
	ds_read_b128 v[56:59], v182
	ds_read_b128 v[248:251], v176 offset:3072
	s_waitcnt lgkmcnt(0)
	v_mfma_f32_16x16x32_bf16 v[108:111], v[4:7], v[24:27], v[120:123]
	v_mfma_f32_16x16x32_bf16 v[92:95], v[4:7], v[28:31], v[116:119]
	v_mfma_f32_16x16x32_bf16 v[76:79], v[4:7], v[56:59], v[112:115]
	v_mfma_f32_16x16x32_bf16 v[104:107], v[8:11], v[24:27], v[104:107]
	v_mfma_f32_16x16x32_bf16 v[88:91], v[8:11], v[28:31], v[100:103]
	v_mfma_f32_16x16x32_bf16 v[72:75], v[8:11], v[56:59], v[96:99]
	v_mfma_f32_16x16x32_bf16 v[100:103], v[154:157], v[24:27], v[232:235]
	v_mfma_f32_16x16x32_bf16 v[84:87], v[154:157], v[28:31], v[68:71]
	v_mfma_f32_16x16x32_bf16 v[68:71], v[154:157], v[56:59], v[64:67]
	v_mfma_f32_16x16x32_bf16 v[116:119], v[248:251], v[12:15], v[44:47]
	v_mfma_f32_16x16x32_bf16 v[96:99], v[248:251], v[24:27], v[40:43]
	v_mfma_f32_16x16x32_bf16 v[80:83], v[248:251], v[28:31], v[36:39]
	v_mfma_f32_16x16x32_bf16 v[64:67], v[248:251], v[56:59], v[32:35]
	v_mfma_f32_16x16x32_bf16 v[178:181], v[4:7], v[12:15], v[124:127]
	v_mfma_f32_16x16x32_bf16 v[224:227], v[8:11], v[12:15], v[224:227]
	v_mfma_f32_16x16x32_bf16 v[120:123], v[154:157], v[12:15], v[228:231]
	ds_read_b128 v[32:35], v142
	ds_read_b128 v[112:115], v143
	ds_read_b128 v[124:127], v144
	ds_read_b128 v[142:145], v145
	s_waitcnt lgkmcnt(0)
; __device__ __forceinline__ float bf2f(bf16_t b) { return __uint_as_float(((unsigned)b) << 16); }
; __device__ __forceinline__ int widen_off(int fq) { return ((fq & 1) << 4) + ((fq >> 1) << 3); }
; template <int MODE, int NSUB>
; __device__ __forceinline__ void epilogue(const Params& p, int layer, f32x4 (&acc)[4][NSUB], int tm, int tn, int g,
;                                          const float* s_rstd, const int tid_in) {
;     ...
;   } else if constexpr (MODE == EPI_RES) {
;     const int fb = tm * 128 + wr * 64 + fq * 4;
;     const int tb = tn * (NSUB * 32) + wc * (NSUB * 16) + fr;
;     const int fw = tm * 128 + wr * 64 + widen_off(fq);
;     u32x4 curw[2], nxtw[2];
; #pragma unroll
;     for (int mp = 0; mp < 2; ++mp) curw[mp] = *reinterpret_cast<const u32x4*>(p.xb + blk(tb, fw + mp * 32, 32));
; #pragma unroll
;     for (int n = 0; n < NSUB; ++n) {
;       if (n + 1 < NSUB) {
; #pragma unroll
;         for (int mp = 0; mp < 2; ++mp) nxtw[mp] = *reinterpret_cast<const u32x4*>(p.xb + blk(tb + (n + 1) * 16, fw + mp * 32, 32));
;       }
;       bf16x4 cur[4];
;       unwiden_pair(curw[0], cur[0], cur[1]);
;       unwiden_pair(curw[1], cur[2], cur[3]);
;       const int t = tb + n * 16;
;       float ss = 0.f;
; #pragma unroll
;       for (int mp = 0; mp < 2; ++mp) {
;         bf16x4 pk[2];
; #pragma unroll
;         for (int h2 = 0; h2 < 2; ++h2) {
;           const int m = mp * 2 + h2;
;           const float x0 = bf2f((bf16_t)cur[m][0]) + acc[m][n][0], x1 = bf2f((bf16_t)cur[m][1]) + acc[m][n][1];
;           const float x2 = bf2f((bf16_t)cur[m][2]) + acc[m][n][2], x3 = bf2f((bf16_t)cur[m][3]) + acc[m][n][3];
;           ss += x0 * x0 + x1 * x1 + x2 * x2 + x3 * x3;
;           pk[h2] = pack4(x0, x1, x2, x3);
;         }
;         const int f = tm * 128 + wr * 64 + mp * 32 + widen_off(fq);
;         *reinterpret_cast<u32x4*>(p.xb + blk(t, f, 32)) = widen_pair(pk[0], pk[1]);
;       }
;       ss = red_fq(ss);
;       if (fq == 0) p.part[(long)t * 16 + tm * 2 + wr] = ss;
;       curw[0] = nxtw[0];
;       curw[1] = nxtw[1];
;     }
	v_mfma_f32_16x16x32_bf16 v[60:63], v[4:7], v[32:35], v[158:161]
	v_mfma_f32_16x16x32_bf16 v[44:47], v[4:7], v[112:115], v[162:165]
	v_mfma_f32_16x16x32_bf16 v[28:31], v[4:7], v[124:127], v[172:175]
	v_mfma_f32_16x16x32_bf16 v[12:15], v[4:7], v[142:145], v[128:131]
	v_mfma_f32_16x16x32_bf16 v[56:59], v[8:11], v[32:35], v[216:219]
	v_mfma_f32_16x16x32_bf16 v[40:43], v[8:11], v[112:115], v[220:223]
	v_mfma_f32_16x16x32_bf16 v[24:27], v[8:11], v[124:127], v[52:55]
	v_mfma_f32_16x16x32_bf16 v[8:11], v[8:11], v[142:145], v[48:51]
	v_mfma_f32_16x16x32_bf16 v[52:55], v[154:157], v[32:35], v[138:141]
	v_mfma_f32_16x16x32_bf16 v[36:39], v[154:157], v[112:115], v[236:239]
	v_mfma_f32_16x16x32_bf16 v[20:23], v[154:157], v[124:127], v[20:23]
	v_mfma_f32_16x16x32_bf16 v[4:7], v[154:157], v[142:145], v[16:19]
	v_mfma_f32_16x16x32_bf16 v[48:51], v[248:251], v[32:35], v[146:149]
	v_mfma_f32_16x16x32_bf16 v[32:35], v[248:251], v[112:115], v[240:243]
	v_mfma_f32_16x16x32_bf16 v[16:19], v[248:251], v[124:127], v[244:247]
	v_mfma_f32_16x16x32_bf16 v[0:3], v[248:251], v[142:145], v[0:3]
	v_lshl_add_u32 v124, s9, 1, v170
	v_mov_b32_e32 v112, v215
	v_lshlrev_b32_e32 v113, 7, v124
	v_ashrrev_i32_e32 v138, 7, v112
	v_lshl_add_u32 v114, v138, 6, v113
	v_lshlrev_b32_e32 v113, 1, v112
	v_and_b32_e32 v113, 0x80, v113
	v_lshl_or_b32 v127, s10, 8, v113
	v_lshrrev_b32_e32 v113, 2, v112
	v_and_b32_e32 v125, 15, v112
	v_and_b32_e32 v113, 8, v113
	v_ashrrev_i32_e32 v115, 2, v127
	v_readlane_b32 s80, v253, 25
	v_ashrrev_i32_e32 v114, 5, v114
	v_bfe_u32 v126, v112, 4, 2
	v_and_or_b32 v112, v112, 16, v113
	v_lshlrev_b32_e32 v156, 6, v125
	v_mov_b32_e32 v157, v153
	v_readlane_b32 s84, v253, 29
	v_readlane_b32 s85, v253, 30
	v_add_u32_e32 v114, v114, v115
	v_lshlrev_b32_e32 v152, 1, v112
	v_lshl_add_u64 v[144:145], s[84:85], 0, v[156:157]
	v_ashrrev_i32_e32 v115, 31, v114
	v_lshl_add_u64 v[112:113], v[144:145], 0, v[152:153]
	v_lshlrev_b64 v[146:147], 13, v[114:115]
	v_or_b32_e32 v114, 1, v114
	v_lshl_add_u64 v[150:151], v[112:113], 0, v[146:147]
	v_ashrrev_i32_e32 v115, 31, v114
	global_load_dwordx4 v[158:161], v[150:151], off
	v_lshlrev_b64 v[148:149], 13, v[114:115]
	v_lshl_add_u64 v[154:155], v[112:113], 0, v[148:149]
	global_load_dwordx4 v[128:131], v[154:155], off
	v_and_b32_e32 v113, 64, v185
	v_xor_b32_e32 v112, 16, v185
	v_add_u32_e32 v113, 64, v113
	v_cmp_lt_i32_e32 vcc, v112, v113
	v_or_b32_e32 v142, v127, v125
	v_lshlrev_b32_e32 v140, 1, v124
	v_cndmask_b32_e32 v112, v185, v112, vcc
	v_lshlrev_b32_e32 v172, 2, v112
	v_xor_b32_e32 v112, 32, v185
	v_cmp_lt_i32_e32 vcc, v112, v113
	v_ashrrev_i32_e32 v141, 31, v140
	v_ashrrev_i32_e32 v139, 31, v138
	v_cndmask_b32_e32 v112, v185, v112, vcc
	v_lshlrev_b32_e32 v173, 2, v112
	v_cmp_eq_u32_e32 vcc, 0, v126
	global_load_dwordx4 v[124:127], v[150:151], off offset:1024
	global_load_dwordx4 v[112:115], v[154:155], off offset:1024
	v_readlane_b32 s81, v253, 26
	v_readlane_b32 s82, v253, 27
	v_readlane_b32 s83, v253, 28
	v_readlane_b32 s86, v253, 31
	v_readlane_b32 s87, v253, 32
	v_readlane_b32 s88, v253, 33
	v_readlane_b32 s89, v253, 34
	v_readlane_b32 s90, v253, 35
	v_readlane_b32 s91, v253, 36
	v_readlane_b32 s92, v253, 37
	v_readlane_b32 s93, v253, 38
	v_readlane_b32 s94, v253, 39
	v_readlane_b32 s95, v253, 40
	s_waitcnt vmcnt(0)
	v_mov_b32_e32 v143, v160
	s_nop 1
	v_permlane16_swap_b32_e32 v158, v143
	v_mov_b32_e32 v164, v161
	s_nop 1
	v_permlane16_swap_b32_e32 v159, v164
	v_mov_b32_e32 v176, v130
	v_mov_b32_e32 v182, v131
	v_and_b32_e32 v131, 0xffff0000, v158
	v_lshlrev_b32_e32 v130, 16, v158
	v_pk_add_f32 v[130:131], v[178:179], v[130:131]
	v_and_b32_e32 v161, 0xffff0000, v159
	v_lshlrev_b32_e32 v160, 16, v159
	v_pk_add_f32 v[162:163], v[180:181], v[160:161]
	v_pk_mul_f32 v[160:161], v[130:131], v[130:131]
	v_cvt_pk_bf16_f32 v178, v130, v131
	v_and_b32_e32 v131, 0xffff0000, v143
	v_lshlrev_b32_e32 v130, 16, v143
	v_pk_mul_f32 v[158:159], v[162:163], v[162:163]
	v_cvt_pk_bf16_f32 v179, v162, v163
	v_pk_add_f32 v[130:131], v[224:225], v[130:131]
	v_and_b32_e32 v163, 0xffff0000, v164
	v_lshlrev_b32_e32 v162, 16, v164
	v_pk_add_f32 v[174:175], v[226:227], v[162:163]
	v_pk_mul_f32 v[164:165], v[130:131], v[130:131]
	v_cvt_pk_bf16_f32 v180, v130, v131
	v_lshl_add_u64 v[130:131], s[84:85], 0, v[146:147]
	v_pk_mul_f32 v[162:163], v[174:175], v[174:175]
	v_cvt_pk_bf16_f32 v181, v174, v175
	v_lshl_add_u64 v[174:175], v[130:131], 0, v[156:157]
	v_permlane16_swap_b32_e32 v128, v176
	v_permlane16_swap_b32_e32 v178, v180
	v_permlane16_swap_b32_e32 v179, v181
	v_lshl_add_u64 v[174:175], v[174:175], 0, v[152:153]
	v_permlane16_swap_b32_e32 v129, v182
	global_store_dwordx4 v[174:175], v[178:181], off
	v_and_b32_e32 v175, 0xffff0000, v128
	v_lshlrev_b32_e32 v174, 16, v128
	v_pk_add_f32 v[120:121], v[120:121], v[174:175]
	v_and_b32_e32 v175, 0xffff0000, v129
	v_lshlrev_b32_e32 v174, 16, v129
	v_pk_add_f32 v[122:123], v[122:123], v[174:175]
	v_pk_mul_f32 v[128:129], v[120:121], v[120:121]
	v_pk_mul_f32 v[174:175], v[122:123], v[122:123]
	v_cvt_pk_bf16_f32 v120, v120, v121
	v_cvt_pk_bf16_f32 v121, v122, v123
	v_and_b32_e32 v123, 0xffff0000, v176
	v_lshlrev_b32_e32 v122, 16, v176
	v_pk_add_f32 v[116:117], v[116:117], v[122:123]
	v_and_b32_e32 v123, 0xffff0000, v182
	v_lshlrev_b32_e32 v122, 16, v182
	v_add_f32_e32 v143, v164, v165
	v_add_f32_e32 v160, v160, v161
	v_pk_add_f32 v[118:119], v[118:119], v[122:123]
	v_pk_mul_f32 v[122:123], v[116:117], v[116:117]
	v_add_f32_e32 v143, v162, v143
	v_add_f32_e32 v158, v158, v160
	v_add_f32_e32 v128, v128, v129
	v_pk_mul_f32 v[178:179], v[118:119], v[118:119]
	v_add_f32_e32 v143, v163, v143
	v_add_f32_e32 v158, v159, v158
	v_add_f32_e32 v128, v174, v128
	v_add_f32_e32 v122, v122, v123
	v_add_f32_e32 v143, v158, v143
	v_add_f32_e32 v128, v175, v128
	v_add_f32_e32 v122, v178, v122
	v_add_f32_e32 v128, v143, v128
	v_add_f32_e32 v122, v179, v122
	v_add_f32_e32 v143, v122, v128
	v_lshl_add_u64 v[128:129], s[84:85], 0, v[148:149]
	v_cvt_pk_bf16_f32 v122, v116, v117
	v_cvt_pk_bf16_f32 v123, v118, v119
	v_lshl_add_u64 v[116:117], v[128:129], 0, v[156:157]
	v_permlane16_swap_b32_e32 v120, v122
	v_permlane16_swap_b32_e32 v121, v123
	v_lshl_add_u64 v[116:117], v[116:117], 0, v[152:153]
	global_store_dwordx4 v[116:117], v[120:123], off
	ds_bpermute_b32 v116, v172, v143
	s_waitcnt lgkmcnt(0)
	v_add_f32_e32 v116, v143, v116
	ds_bpermute_b32 v117, v173, v116
	s_and_saveexec_b64 s[10:11], vcc
	s_cbranch_execz .LBB0_71
; template <int MODE, int NSUB>
; __device__ __forceinline__ void epilogue(const Params& p, int layer, f32x4 (&acc)[4][NSUB], int tm, int tn, int g,
;                                          const float* s_rstd, const int tid_in) {
;     ...
;       ss = red_fq(ss);
;       if (fq == 0) p.part[(long)t * 16 + tm * 2 + wr] = ss;
	v_ashrrev_i32_e32 v143, 31, v142
	v_readlane_b32 s64, v253, 25
	v_lshlrev_b64 v[118:119], 6, v[142:143]
	v_readlane_b32 s70, v253, 31
	v_readlane_b32 s71, v253, 32
	s_waitcnt lgkmcnt(0)
	v_add_f32_e32 v116, v116, v117
	v_readlane_b32 s65, v253, 26
	v_lshl_add_u64 v[118:119], s[70:71], 0, v[118:119]
	v_lshl_add_u64 v[118:119], v[140:141], 2, v[118:119]
	v_lshl_add_u64 v[118:119], v[138:139], 2, v[118:119]
	v_readlane_b32 s66, v253, 27
	v_readlane_b32 s67, v253, 28
	v_readlane_b32 s68, v253, 29
	v_readlane_b32 s69, v253, 30
	v_readlane_b32 s72, v253, 33
	v_readlane_b32 s73, v253, 34
	v_readlane_b32 s74, v253, 35
	v_readlane_b32 s75, v253, 36
	v_readlane_b32 s76, v253, 37
	v_readlane_b32 s77, v253, 38
	v_readlane_b32 s78, v253, 39
	v_readlane_b32 s79, v253, 40
	global_store_dword v[118:119], v116, off

; #define BIG_SYNC(N)                                              \
;   asm volatile("s_waitcnt vmcnt(%0)" ::"n"(N) : "memory");       \
;   __builtin_amdgcn_s_barrier();                                  \
;   asm volatile("" ::: "memory");                                 \
;   __builtin_amdgcn_sched_barrier(0);
; template <int NK, bool BNT = false> ...
;     ...
;   auto kstep = [&](int T, int cur, int nxt, bool do_stage) {
;     const unsigned char* sa = smem + cur * BIG_STAGE;
;     bf16x8 af[4], bfr[4];
; #pragma unroll
;     for (int m = 0; m < 4; ++m) af[m] = *reinterpret_cast<const bf16x8*>(sa + aoff + m * 1024);
; #pragma unroll
;     for (int n = 0; n < 4; ++n) bfr[n] = *reinterpret_cast<const bf16x8*>(sa + boff + n * 1024);
;     __builtin_amdgcn_sched_barrier(0);
;     if (do_stage) stage(T + 3, nxt);
; #pragma unroll
;     for (int m = 0; m < 4; ++m)
; #pragma unroll
;       for (int n = 0; n < 4; ++n) acc[m][n] = __builtin_amdgcn_mfma_f32_16x16x32_bf16(af[m], bfr[n], acc[m][n], 0, 0, 0);
;     if (do_stage) {
; #pragma unroll
;       for (int q = 0; q < NG; ++q) {
;         __builtin_amdgcn_sched_group_barrier(0x008, 3, 0);
;         __builtin_amdgcn_sched_group_barrier(0x010, 1, 0);
;       }
;       __builtin_amdgcn_sched_group_barrier(0x008, 16 - 3 * NG, 0);
;     }
;     __builtin_amdgcn_sched_barrier(0);
; #pragma unroll
;     for (int n = 0; n < 4; ++n) bfr[n] = *reinterpret_cast<const bf16x8*>(sa + boff + (4 + n) * 1024);
; #pragma unroll
;     for (int m = 0; m < 4; ++m)
; #pragma unroll
;       for (int n = 0; n < 4; ++n)
;         acc[m][4 + n] = __builtin_amdgcn_mfma_f32_16x16x32_bf16(af[m], bfr[n], acc[m][4 + n], 0, 0, 0);
;     __builtin_amdgcn_sched_barrier(0);
;   };
;     ...
;   stage(0, 0);
;   stage(1, 1);
;   stage(2, 2);
;   for (int it = 0; it < NK / 4 - 1; ++it) {
;     const int t = it * 4;
;     BIG_SYNC(2 * NG); kstep(t, 0, 3, true);
;     BIG_SYNC(2 * NG); kstep(t + 1, 1, 0, true);
;     BIG_SYNC(2 * NG); kstep(t + 2, 2, 1, true);
;     BIG_SYNC(2 * NG); kstep(t + 3, 3, 2, true);
.LBB0_264:
	v_add_u32_e32 v158, 0x18000, v166
	v_lshl_add_u64 v[144:145], v[138:139], 0, s[36:37]
	v_readfirstlane_b32 s13, v158
	v_add_u32_e32 v159, 0x1a000, v166
	v_lshl_add_u64 v[160:161], v[144:145], 0, s[60:61]
	s_mov_b32 m0, s13
	v_readfirstlane_b32 s13, v159
	s_waitcnt lgkmcnt(3)
	v_mfma_f32_16x16x32_bf16 v[124:127], v[216:219], v[232:235], v[124:127]
	v_lshl_add_u64 v[142:143], v[140:141], 0, s[36:37]
	v_lshl_add_u64 v[182:183], v[142:143], 0, s[60:61]
	v_mfma_f32_16x16x32_bf16 v[108:111], v[220:223], v[232:235], v[108:111]
	v_mfma_f32_16x16x32_bf16 v[88:91], v[224:227], v[232:235], v[88:91]
	s_waitcnt vmcnt(4)
	s_barrier
	global_load_lds_dwordx4 v[160:161], off
	v_lshl_add_u64 v[160:161], v[144:145], 0, s[18:19]
	s_mov_b32 m0, s13
	v_mfma_f32_16x16x32_bf16 v[44:47], v[228:231], v[232:235], v[44:47]
	s_waitcnt lgkmcnt(2)
	v_mfma_f32_16x16x32_bf16 v[120:123], v[216:219], v[236:239], v[120:123]
	ds_read_b128 v[232:235], v168 offset:20480
	v_mfma_f32_16x16x32_bf16 v[104:107], v[220:223], v[236:239], v[104:107]
	global_load_lds_dwordx4 v[160:161], off
	v_add_u32_e32 v160, 0x1c000, v166
	v_add_u32_e32 v161, 0x1e000, v166
	v_readfirstlane_b32 s13, v160
	s_mov_b32 m0, s13
	v_readfirstlane_b32 s13, v161
	v_mfma_f32_16x16x32_bf16 v[76:79], v[224:227], v[236:239], v[76:79]
	v_mfma_f32_16x16x32_bf16 v[40:43], v[228:231], v[236:239], v[40:43]
	s_waitcnt lgkmcnt(2)
	v_mfma_f32_16x16x32_bf16 v[116:119], v[216:219], v[240:243], v[116:119]
	ds_read_b128 v[236:239], v168 offset:21504
	global_load_lds_dwordx4 v[182:183], off nt
	v_lshl_add_u64 v[182:183], v[142:143], 0, s[18:19]
	s_mov_b32 m0, s13
	v_mfma_f32_16x16x32_bf16 v[100:103], v[220:223], v[240:243], v[100:103]
	v_mfma_f32_16x16x32_bf16 v[68:71], v[224:227], v[240:243], v[68:71]
	v_mfma_f32_16x16x32_bf16 v[36:39], v[228:231], v[240:243], v[36:39]
	global_load_lds_dwordx4 v[182:183], off nt
	s_waitcnt lgkmcnt(2)
	v_mfma_f32_16x16x32_bf16 v[112:115], v[216:219], v[244:247], v[112:115]
	ds_read_b128 v[240:243], v168 offset:22528
	v_mfma_f32_16x16x32_bf16 v[96:99], v[220:223], v[244:247], v[96:99]
	v_mfma_f32_16x16x32_bf16 v[64:67], v[224:227], v[244:247], v[64:67]
	v_mfma_f32_16x16x32_bf16 v[32:35], v[228:231], v[244:247], v[32:35]
	s_waitcnt lgkmcnt(2)
	v_mfma_f32_16x16x32_bf16 v[92:95], v[216:219], v[232:235], v[92:95]
	ds_read_b128 v[244:247], v168 offset:23552
	v_mfma_f32_16x16x32_bf16 v[60:63], v[220:223], v[232:235], v[60:63]
	ds_read_b128 v[186:189], v167 offset:32768
	v_mfma_f32_16x16x32_bf16 v[28:31], v[224:227], v[232:235], v[28:31]
	ds_read_b128 v[190:193], v167 offset:33792
	v_mfma_f32_16x16x32_bf16 v[12:15], v[228:231], v[232:235], v[12:15]
	ds_read_b128 v[194:197], v167 offset:34816
	s_waitcnt lgkmcnt(5)
	v_mfma_f32_16x16x32_bf16 v[84:87], v[216:219], v[236:239], v[84:87]
	ds_read_b128 v[202:205], v167 offset:35840
	ds_read_b128 v[232:235], v168 offset:49152
	v_mfma_f32_16x16x32_bf16 v[56:59], v[220:223], v[236:239], v[56:59]
	v_mfma_f32_16x16x32_bf16 v[24:27], v[224:227], v[236:239], v[24:27]
	v_mfma_f32_16x16x32_bf16 v[8:11], v[228:231], v[236:239], v[8:11]
	s_waitcnt lgkmcnt(6)
	v_mfma_f32_16x16x32_bf16 v[80:83], v[216:219], v[240:243], v[80:83]
	ds_read_b128 v[236:239], v168 offset:50176
	v_mfma_f32_16x16x32_bf16 v[52:55], v[220:223], v[240:243], v[52:55]
	v_mfma_f32_16x16x32_bf16 v[20:23], v[224:227], v[240:243], v[20:23]
	v_mfma_f32_16x16x32_bf16 v[4:7], v[228:231], v[240:243], v[4:7]
	s_waitcnt lgkmcnt(6)
	v_mfma_f32_16x16x32_bf16 v[72:75], v[216:219], v[244:247], v[72:75]
	ds_read_b128 v[240:243], v168 offset:51200
	v_mfma_f32_16x16x32_bf16 v[48:51], v[220:223], v[244:247], v[48:51]
	v_mfma_f32_16x16x32_bf16 v[16:19], v[224:227], v[244:247], v[16:19]
	v_mfma_f32_16x16x32_bf16 v[0:3], v[228:231], v[244:247], v[0:3]
	ds_read_b128 v[244:247], v168 offset:52224
	v_readfirstlane_b32 s13, v166
	v_lshl_add_u64 v[182:183], v[144:145], 0, s[62:63]
	s_mov_b32 m0, s13
	v_readfirstlane_b32 s13, v146
	s_waitcnt lgkmcnt(3)
	v_mfma_f32_16x16x32_bf16 v[124:127], v[186:189], v[232:235], v[124:127]
	v_lshl_add_u64 v[198:199], v[142:143], 0, s[62:63]
	v_mfma_f32_16x16x32_bf16 v[108:111], v[190:193], v[232:235], v[108:111]
	v_mfma_f32_16x16x32_bf16 v[88:91], v[194:197], v[232:235], v[88:91]
	s_waitcnt vmcnt(4)
	s_barrier
; #define BIG_SYNC(N)                                              \
;   asm volatile("s_waitcnt vmcnt(%0)" ::"n"(N) : "memory");       \
;   __builtin_amdgcn_s_barrier();                                  \
;   asm volatile("" ::: "memory");                                 \
;   __builtin_amdgcn_sched_barrier(0);
; template <int NK, bool BNT = false> ...
;     ...
;   auto kstep = [&](int T, int cur, int nxt, bool do_stage) {
;     const unsigned char* sa = smem + cur * BIG_STAGE;
;     bf16x8 af[4], bfr[4];
; #pragma unroll
;     for (int m = 0; m < 4; ++m) af[m] = *reinterpret_cast<const bf16x8*>(sa + aoff + m * 1024);
; #pragma unroll
;     for (int n = 0; n < 4; ++n) bfr[n] = *reinterpret_cast<const bf16x8*>(sa + boff + n * 1024);
;     __builtin_amdgcn_sched_barrier(0);
;     if (do_stage) stage(T + 3, nxt);
; #pragma unroll
;     for (int m = 0; m < 4; ++m)
; #pragma unroll
;       for (int n = 0; n < 4; ++n) acc[m][n] = __builtin_amdgcn_mfma_f32_16x16x32_bf16(af[m], bfr[n], acc[m][n], 0, 0, 0);
;     if (do_stage) {
; #pragma unroll
;       for (int q = 0; q < NG; ++q) {
;         __builtin_amdgcn_sched_group_barrier(0x008, 3, 0);
;         __builtin_amdgcn_sched_group_barrier(0x010, 1, 0);
;       }
;       __builtin_amdgcn_sched_group_barrier(0x008, 16 - 3 * NG, 0);
;     }
;     __builtin_amdgcn_sched_barrier(0);
; #pragma unroll
;     for (int n = 0; n < 4; ++n) bfr[n] = *reinterpret_cast<const bf16x8*>(sa + boff + (4 + n) * 1024);
; #pragma unroll
;     for (int m = 0; m < 4; ++m)
; #pragma unroll
;       for (int n = 0; n < 4; ++n)
;         acc[m][4 + n] = __builtin_amdgcn_mfma_f32_16x16x32_bf16(af[m], bfr[n], acc[m][4 + n], 0, 0, 0);
;     __builtin_amdgcn_sched_barrier(0);
;   };
;     ...
;   stage(0, 0);
;   stage(1, 1);
;   stage(2, 2);
;   for (int it = 0; it < NK / 4 - 1; ++it) {
;     const int t = it * 4;
;     BIG_SYNC(2 * NG); kstep(t, 0, 3, true);
;     BIG_SYNC(2 * NG); kstep(t + 1, 1, 0, true);
;     BIG_SYNC(2 * NG); kstep(t + 2, 2, 1, true);
;     BIG_SYNC(2 * NG); kstep(t + 3, 3, 2, true);
	global_load_lds_dwordx4 v[182:183], off
	v_lshl_add_u64 v[182:183], v[144:145], 0, s[20:21]
	s_mov_b32 m0, s13
	v_readfirstlane_b32 s13, v147
	v_mfma_f32_16x16x32_bf16 v[44:47], v[202:205], v[232:235], v[44:47]
	s_waitcnt lgkmcnt(2)
	v_mfma_f32_16x16x32_bf16 v[120:123], v[186:189], v[236:239], v[120:123]
	ds_read_b128 v[232:235], v168 offset:53248
	v_mfma_f32_16x16x32_bf16 v[104:107], v[190:193], v[236:239], v[104:107]
	global_load_lds_dwordx4 v[182:183], off
	s_mov_b32 m0, s13
	v_readfirstlane_b32 s13, v148
	v_lshl_add_u64 v[182:183], v[142:143], 0, s[20:21]
	v_mfma_f32_16x16x32_bf16 v[76:79], v[194:197], v[236:239], v[76:79]
	v_mfma_f32_16x16x32_bf16 v[40:43], v[202:205], v[236:239], v[40:43]
	s_waitcnt lgkmcnt(2)
	v_mfma_f32_16x16x32_bf16 v[116:119], v[186:189], v[240:243], v[116:119]
	ds_read_b128 v[236:239], v168 offset:54272
	global_load_lds_dwordx4 v[198:199], off nt
	s_mov_b32 m0, s13
	v_mfma_f32_16x16x32_bf16 v[100:103], v[190:193], v[240:243], v[100:103]
	v_mfma_f32_16x16x32_bf16 v[68:71], v[194:197], v[240:243], v[68:71]
	v_mfma_f32_16x16x32_bf16 v[36:39], v[202:205], v[240:243], v[36:39]
	global_load_lds_dwordx4 v[182:183], off nt
	s_waitcnt lgkmcnt(2)
	v_mfma_f32_16x16x32_bf16 v[112:115], v[186:189], v[244:247], v[112:115]
	ds_read_b128 v[240:243], v168 offset:55296
	v_mfma_f32_16x16x32_bf16 v[96:99], v[190:193], v[244:247], v[96:99]
	v_mfma_f32_16x16x32_bf16 v[64:67], v[194:197], v[244:247], v[64:67]
	v_mfma_f32_16x16x32_bf16 v[32:35], v[202:205], v[244:247], v[32:35]
	v_add_u32_e32 v162, 0x10000, v167
	v_or_b32_e32 v163, 0x10000, v169
	s_waitcnt lgkmcnt(2)
	v_mfma_f32_16x16x32_bf16 v[92:95], v[186:189], v[232:235], v[92:95]
	ds_read_b128 v[244:247], v168 offset:56320
	v_mfma_f32_16x16x32_bf16 v[60:63], v[190:193], v[232:235], v[60:63]
	ds_read_b128 v[216:219], v162
	v_mfma_f32_16x16x32_bf16 v[28:31], v[194:197], v[232:235], v[28:31]
	ds_read_b128 v[220:223], v162 offset:1024
	v_mfma_f32_16x16x32_bf16 v[12:15], v[202:205], v[232:235], v[12:15]
	ds_read_b128 v[224:227], v162 offset:2048
	s_waitcnt lgkmcnt(5)
	v_mfma_f32_16x16x32_bf16 v[84:87], v[186:189], v[236:239], v[84:87]
	ds_read_b128 v[228:231], v162 offset:3072
	ds_read_b128 v[232:235], v163
	v_mfma_f32_16x16x32_bf16 v[56:59], v[190:193], v[236:239], v[56:59]
	v_mfma_f32_16x16x32_bf16 v[24:27], v[194:197], v[236:239], v[24:27]
	v_mfma_f32_16x16x32_bf16 v[8:11], v[202:205], v[236:239], v[8:11]
	s_waitcnt lgkmcnt(6)
	v_mfma_f32_16x16x32_bf16 v[80:83], v[186:189], v[240:243], v[80:83]
	ds_read_b128 v[236:239], v163 offset:1024
	v_mfma_f32_16x16x32_bf16 v[52:55], v[190:193], v[240:243], v[52:55]
	v_mfma_f32_16x16x32_bf16 v[20:23], v[194:197], v[240:243], v[20:23]
	v_mfma_f32_16x16x32_bf16 v[4:7], v[202:205], v[240:243], v[4:7]
	s_waitcnt lgkmcnt(6)
	v_mfma_f32_16x16x32_bf16 v[72:75], v[186:189], v[244:247], v[72:75]
	ds_read_b128 v[240:243], v163 offset:2048
	v_mfma_f32_16x16x32_bf16 v[48:51], v[190:193], v[244:247], v[48:51]
	v_mfma_f32_16x16x32_bf16 v[16:19], v[194:197], v[244:247], v[16:19]
	v_mfma_f32_16x16x32_bf16 v[0:3], v[202:205], v[244:247], v[0:3]
	ds_read_b128 v[244:247], v163 offset:3072
	v_add_u32_e32 v162, 0x10000, v167
	v_or_b32_e32 v163, 0x10000, v169
	v_add_u32_e32 v164, 0x10400, v169
	v_add_u32_e32 v165, 0x10800, v169
	v_add_u32_e32 v172, 0x10c00, v169
	v_readfirstlane_b32 s13, v149
	v_lshl_add_u64 v[174:175], v[144:145], 0, s[2:3]
	s_mov_b32 m0, s13
	v_readfirstlane_b32 s13, v150
	s_waitcnt lgkmcnt(3)
	v_mfma_f32_16x16x32_bf16 v[124:127], v[216:219], v[232:235], v[124:127]
	v_lshl_add_u64 v[178:179], v[142:143], 0, s[2:3]
	v_mfma_f32_16x16x32_bf16 v[108:111], v[220:223], v[232:235], v[108:111]
	v_mfma_f32_16x16x32_bf16 v[88:91], v[224:227], v[232:235], v[88:91]
	s_waitcnt vmcnt(4)
	s_barrier
	global_load_lds_dwordx4 v[174:175], off
	v_lshl_add_u64 v[174:175], v[144:145], 0, s[22:23]
	s_mov_b32 m0, s13
	v_readfirstlane_b32 s13, v151
	v_mfma_f32_16x16x32_bf16 v[44:47], v[228:231], v[232:235], v[44:47]
	s_waitcnt lgkmcnt(2)
	v_mfma_f32_16x16x32_bf16 v[120:123], v[216:219], v[236:239], v[120:123]
	ds_read_b128 v[232:235], v163 offset:4096
	v_mfma_f32_16x16x32_bf16 v[104:107], v[220:223], v[236:239], v[104:107]
	global_load_lds_dwordx4 v[174:175], off
	s_mov_b32 m0, s13
	v_readfirstlane_b32 s13, v152
	v_lshl_add_u64 v[174:175], v[142:143], 0, s[22:23]
	v_mfma_f32_16x16x32_bf16 v[76:79], v[224:227], v[236:239], v[76:79]
	v_mfma_f32_16x16x32_bf16 v[40:43], v[228:231], v[236:239], v[40:43]
	s_waitcnt lgkmcnt(2)
	v_mfma_f32_16x16x32_bf16 v[116:119], v[216:219], v[240:243], v[116:119]
	ds_read_b128 v[236:239], v163 offset:5120
	global_load_lds_dwordx4 v[178:179], off nt
	s_mov_b32 m0, s13
	v_mfma_f32_16x16x32_bf16 v[100:103], v[220:223], v[240:243], v[100:103]
	v_mfma_f32_16x16x32_bf16 v[68:71], v[224:227], v[240:243], v[68:71]
	v_mfma_f32_16x16x32_bf16 v[36:39], v[228:231], v[240:243], v[36:39]
	global_load_lds_dwordx4 v[174:175], off nt
	s_waitcnt lgkmcnt(2)
	v_mfma_f32_16x16x32_bf16 v[112:115], v[216:219], v[244:247], v[112:115]
	ds_read_b128 v[240:243], v163 offset:6144
	v_mfma_f32_16x16x32_bf16 v[96:99], v[220:223], v[244:247], v[96:99]
	v_mfma_f32_16x16x32_bf16 v[64:67], v[224:227], v[244:247], v[64:67]
	v_mfma_f32_16x16x32_bf16 v[32:35], v[228:231], v[244:247], v[32:35]
	v_add_u32_e32 v173, 0x11000, v169
	v_add_u32_e32 v174, 0x11400, v169
	v_add_u32_e32 v175, 0x11800, v169
	v_add_u32_e32 v178, 0x11c00, v169
	v_add_u32_e32 v162, 0x10000, v167
	v_or_b32_e32 v163, 0x10000, v169
	s_waitcnt lgkmcnt(2)
; #define BIG_SYNC(N)                                              \
;   asm volatile("s_waitcnt vmcnt(%0)" ::"n"(N) : "memory");       \
;   __builtin_amdgcn_s_barrier();                                  \
;   asm volatile("" ::: "memory");                                 \
;   __builtin_amdgcn_sched_barrier(0);
; template <int NK, bool BNT = false> ...
;     ...
;   auto kstep = [&](int T, int cur, int nxt, bool do_stage) {
;     const unsigned char* sa = smem + cur * BIG_STAGE;
;     bf16x8 af[4], bfr[4];
; #pragma unroll
;     for (int m = 0; m < 4; ++m) af[m] = *reinterpret_cast<const bf16x8*>(sa + aoff + m * 1024);
; #pragma unroll
;     for (int n = 0; n < 4; ++n) bfr[n] = *reinterpret_cast<const bf16x8*>(sa + boff + n * 1024);
;     __builtin_amdgcn_sched_barrier(0);
;     if (do_stage) stage(T + 3, nxt);
; #pragma unroll
;     for (int m = 0; m < 4; ++m)
; #pragma unroll
;       for (int n = 0; n < 4; ++n) acc[m][n] = __builtin_amdgcn_mfma_f32_16x16x32_bf16(af[m], bfr[n], acc[m][n], 0, 0, 0);
;     if (do_stage) {
; #pragma unroll
;       for (int q = 0; q < NG; ++q) {
;         __builtin_amdgcn_sched_group_barrier(0x008, 3, 0);
;         __builtin_amdgcn_sched_group_barrier(0x010, 1, 0);
;       }
;       __builtin_amdgcn_sched_group_barrier(0x008, 16 - 3 * NG, 0);
;     }
;     __builtin_amdgcn_sched_barrier(0);
; #pragma unroll
;     for (int n = 0; n < 4; ++n) bfr[n] = *reinterpret_cast<const bf16x8*>(sa + boff + (4 + n) * 1024);
; #pragma unroll
;     for (int m = 0; m < 4; ++m)
; #pragma unroll
;       for (int n = 0; n < 4; ++n)
;         acc[m][4 + n] = __builtin_amdgcn_mfma_f32_16x16x32_bf16(af[m], bfr[n], acc[m][4 + n], 0, 0, 0);
;     __builtin_amdgcn_sched_barrier(0);
;   };
;     ...
;   stage(0, 0);
;   stage(1, 1);
;   stage(2, 2);
;   for (int it = 0; it < NK / 4 - 1; ++it) {
;     const int t = it * 4;
;     BIG_SYNC(2 * NG); kstep(t, 0, 3, true);
;     BIG_SYNC(2 * NG); kstep(t + 1, 1, 0, true);
;     BIG_SYNC(2 * NG); kstep(t + 2, 2, 1, true);
;     BIG_SYNC(2 * NG); kstep(t + 3, 3, 2, true);
	v_mfma_f32_16x16x32_bf16 v[92:95], v[216:219], v[232:235], v[92:95]
	ds_read_b128 v[244:247], v163 offset:7168
	v_mfma_f32_16x16x32_bf16 v[60:63], v[220:223], v[232:235], v[60:63]
	ds_read_b128 v[186:189], v162 offset:32768
	v_mfma_f32_16x16x32_bf16 v[28:31], v[224:227], v[232:235], v[28:31]
	ds_read_b128 v[190:193], v162 offset:33792
	v_mfma_f32_16x16x32_bf16 v[12:15], v[228:231], v[232:235], v[12:15]
	ds_read_b128 v[194:197], v162 offset:34816
	s_waitcnt lgkmcnt(5)
	v_mfma_f32_16x16x32_bf16 v[84:87], v[216:219], v[236:239], v[84:87]
	ds_read_b128 v[202:205], v162 offset:35840
	ds_read_b128 v[232:235], v163 offset:32768
	v_mfma_f32_16x16x32_bf16 v[56:59], v[220:223], v[236:239], v[56:59]
	v_mfma_f32_16x16x32_bf16 v[24:27], v[224:227], v[236:239], v[24:27]
	v_mfma_f32_16x16x32_bf16 v[8:11], v[228:231], v[236:239], v[8:11]
	s_waitcnt lgkmcnt(6)
	v_mfma_f32_16x16x32_bf16 v[80:83], v[216:219], v[240:243], v[80:83]
	ds_read_b128 v[236:239], v163 offset:33792
	v_mfma_f32_16x16x32_bf16 v[52:55], v[220:223], v[240:243], v[52:55]
	v_mfma_f32_16x16x32_bf16 v[20:23], v[224:227], v[240:243], v[20:23]
	v_mfma_f32_16x16x32_bf16 v[4:7], v[228:231], v[240:243], v[4:7]
	s_waitcnt lgkmcnt(6)
	v_mfma_f32_16x16x32_bf16 v[72:75], v[216:219], v[244:247], v[72:75]
	ds_read_b128 v[240:243], v163 offset:34816
	v_mfma_f32_16x16x32_bf16 v[48:51], v[220:223], v[244:247], v[48:51]
	v_mfma_f32_16x16x32_bf16 v[16:19], v[224:227], v[244:247], v[16:19]
	v_mfma_f32_16x16x32_bf16 v[0:3], v[228:231], v[244:247], v[0:3]
	ds_read_b128 v[244:247], v163 offset:35840
	v_add_u32_e32 v176, 0x18000, v167
	v_or_b32_e32 v179, 0x18000, v169
	v_add_u32_e32 v180, 0x18400, v169
	v_add_u32_e32 v181, 0x18800, v169
	v_add_u32_e32 v182, 0x18c00, v169
	v_readfirstlane_b32 s13, v154
	v_lshl_add_u64 v[248:249], v[144:145], 0, s[54:55]
	s_mov_b32 m0, s13
	v_readfirstlane_b32 s13, v155
	v_lshl_add_u64 v[144:145], v[144:145], 0, s[24:25]
	s_waitcnt lgkmcnt(3)
	v_mfma_f32_16x16x32_bf16 v[124:127], v[186:189], v[232:235], v[124:127]
	v_lshl_add_u64 v[250:251], v[142:143], 0, s[54:55]
	v_lshl_add_u64 v[142:143], v[142:143], 0, s[24:25]
	v_mfma_f32_16x16x32_bf16 v[108:111], v[190:193], v[232:235], v[108:111]
	v_mfma_f32_16x16x32_bf16 v[88:91], v[194:197], v[232:235], v[88:91]
	s_waitcnt vmcnt(4)
	s_barrier
	global_load_lds_dwordx4 v[248:249], off
	s_mov_b32 m0, s13
	v_readfirstlane_b32 s13, v156
	v_mfma_f32_16x16x32_bf16 v[44:47], v[202:205], v[232:235], v[44:47]
	s_waitcnt lgkmcnt(2)
	v_mfma_f32_16x16x32_bf16 v[120:123], v[186:189], v[236:239], v[120:123]
	ds_read_b128 v[232:235], v163 offset:36864
	v_mfma_f32_16x16x32_bf16 v[104:107], v[190:193], v[236:239], v[104:107]
	global_load_lds_dwordx4 v[144:145], off
	s_mov_b32 m0, s13
	v_readfirstlane_b32 s13, v157
	v_mfma_f32_16x16x32_bf16 v[76:79], v[194:197], v[236:239], v[76:79]
	v_mfma_f32_16x16x32_bf16 v[40:43], v[202:205], v[236:239], v[40:43]
	s_waitcnt lgkmcnt(2)
	v_mfma_f32_16x16x32_bf16 v[116:119], v[186:189], v[240:243], v[116:119]
	ds_read_b128 v[236:239], v163 offset:37888
	global_load_lds_dwordx4 v[250:251], off nt
	s_mov_b32 m0, s13
	v_mfma_f32_16x16x32_bf16 v[100:103], v[190:193], v[240:243], v[100:103]
	v_mfma_f32_16x16x32_bf16 v[68:71], v[194:197], v[240:243], v[68:71]
	v_mfma_f32_16x16x32_bf16 v[36:39], v[202:205], v[240:243], v[36:39]
	global_load_lds_dwordx4 v[142:143], off nt
	s_waitcnt lgkmcnt(2)
	v_mfma_f32_16x16x32_bf16 v[112:115], v[186:189], v[244:247], v[112:115]
	ds_read_b128 v[240:243], v163 offset:38912
	v_mfma_f32_16x16x32_bf16 v[96:99], v[190:193], v[244:247], v[96:99]
	v_mfma_f32_16x16x32_bf16 v[64:67], v[194:197], v[244:247], v[64:67]
	v_mfma_f32_16x16x32_bf16 v[32:35], v[202:205], v[244:247], v[32:35]
	v_add_u32_e32 v142, 0x19000, v169
	v_add_u32_e32 v143, 0x19400, v169
	v_add_u32_e32 v144, 0x19800, v169
	v_add_u32_e32 v145, 0x19c00, v169
	s_waitcnt lgkmcnt(2)
	v_mfma_f32_16x16x32_bf16 v[92:95], v[186:189], v[232:235], v[92:95]
	ds_read_b128 v[244:247], v163 offset:39936
	v_mfma_f32_16x16x32_bf16 v[60:63], v[190:193], v[232:235], v[60:63]
	ds_read_b128 v[216:219], v167
	v_mfma_f32_16x16x32_bf16 v[28:31], v[194:197], v[232:235], v[28:31]
	ds_read_b128 v[220:223], v167 offset:1024
	v_mfma_f32_16x16x32_bf16 v[12:15], v[202:205], v[232:235], v[12:15]
	ds_read_b128 v[224:227], v167 offset:2048
	s_waitcnt lgkmcnt(5)
	v_mfma_f32_16x16x32_bf16 v[84:87], v[186:189], v[236:239], v[84:87]
	ds_read_b128 v[228:231], v167 offset:3072
	ds_read_b128 v[232:235], v168 offset:16384
	v_mfma_f32_16x16x32_bf16 v[56:59], v[190:193], v[236:239], v[56:59]
	v_mfma_f32_16x16x32_bf16 v[24:27], v[194:197], v[236:239], v[24:27]
	v_mfma_f32_16x16x32_bf16 v[8:11], v[202:205], v[236:239], v[8:11]
	s_waitcnt lgkmcnt(6)
	v_mfma_f32_16x16x32_bf16 v[80:83], v[186:189], v[240:243], v[80:83]
	ds_read_b128 v[236:239], v168 offset:17408
	v_mfma_f32_16x16x32_bf16 v[52:55], v[190:193], v[240:243], v[52:55]
	v_mfma_f32_16x16x32_bf16 v[20:23], v[194:197], v[240:243], v[20:23]
	v_mfma_f32_16x16x32_bf16 v[4:7], v[202:205], v[240:243], v[4:7]
	s_waitcnt lgkmcnt(6)
	v_mfma_f32_16x16x32_bf16 v[72:75], v[186:189], v[244:247], v[72:75]
	ds_read_b128 v[240:243], v168 offset:18432
	v_mfma_f32_16x16x32_bf16 v[48:51], v[190:193], v[244:247], v[48:51]
	v_mfma_f32_16x16x32_bf16 v[16:19], v[194:197], v[244:247], v[16:19]
	v_mfma_f32_16x16x32_bf16 v[0:3], v[202:205], v[244:247], v[0:3]
	ds_read_b128 v[244:247], v168 offset:19456
	s_add_u32 s36, s36, 0x8000
	s_addc_u32 s37, s37, 0
	s_cmp_lg_u32 s36, 0xf8000
	s_cbranch_scc1 .LBB0_264
; #define BIG_SYNC(N)                                              \
;   asm volatile("s_waitcnt vmcnt(%0)" ::"n"(N) : "memory");       \
;   __builtin_amdgcn_s_barrier();                                  \
;   asm volatile("" ::: "memory");                                 \
;   __builtin_amdgcn_sched_barrier(0);
; template <int NK, bool BNT = false> ...
;     ...
;   BIG_SYNC(2 * NG); kstep(NK - 4, 0, 3, true);
;   BIG_SYNC(2 * NG); kstep(NK - 3, 1, 0, false);
;   BIG_SYNC(NG);     kstep(NK - 2, 2, 0, false);
;   BIG_SYNC(0);      kstep(NK - 1, 3, 0, false);
	s_sext_i32_i8 s13, s14
	s_mov_b64 s[18:19], 0xfe000
	v_readfirstlane_b32 s14, v158
	v_lshl_add_u64 v[150:151], v[130:131], 0, s[18:19]
	v_lshl_add_u64 v[198:199], v[128:129], 0, s[18:19]
	s_mov_b32 m0, s14
	s_mov_b64 s[18:19], 0x1fe000
	v_readfirstlane_b32 s14, v159
	v_lshl_add_u64 v[130:131], v[130:131], 0, s[18:19]
	s_waitcnt lgkmcnt(3)
	v_mfma_f32_16x16x32_bf16 v[124:127], v[216:219], v[232:235], v[124:127]
	v_lshl_add_u64 v[128:129], v[128:129], 0, s[18:19]
	v_mfma_f32_16x16x32_bf16 v[108:111], v[220:223], v[232:235], v[108:111]
	v_mfma_f32_16x16x32_bf16 v[88:91], v[224:227], v[232:235], v[88:91]
	s_waitcnt vmcnt(4)
	s_barrier
	global_load_lds_dwordx4 v[150:151], off
	s_mov_b32 m0, s14
	v_readfirstlane_b32 s14, v160
	v_mfma_f32_16x16x32_bf16 v[44:47], v[228:231], v[232:235], v[44:47]
	s_waitcnt lgkmcnt(2)
	v_mfma_f32_16x16x32_bf16 v[120:123], v[216:219], v[236:239], v[120:123]
	ds_read_b128 v[232:235], v168 offset:20480
	v_mfma_f32_16x16x32_bf16 v[104:107], v[220:223], v[236:239], v[104:107]
	global_load_lds_dwordx4 v[130:131], off
	s_mov_b32 m0, s14
	v_readfirstlane_b32 s14, v161
	v_mfma_f32_16x16x32_bf16 v[76:79], v[224:227], v[236:239], v[76:79]
	v_mfma_f32_16x16x32_bf16 v[40:43], v[228:231], v[236:239], v[40:43]
	s_waitcnt lgkmcnt(2)
	v_mfma_f32_16x16x32_bf16 v[116:119], v[216:219], v[240:243], v[116:119]
	ds_read_b128 v[236:239], v168 offset:21504
	global_load_lds_dwordx4 v[198:199], off nt
	s_mov_b32 m0, s14
	v_mfma_f32_16x16x32_bf16 v[100:103], v[220:223], v[240:243], v[100:103]
	v_mfma_f32_16x16x32_bf16 v[68:71], v[224:227], v[240:243], v[68:71]
	v_mfma_f32_16x16x32_bf16 v[36:39], v[228:231], v[240:243], v[36:39]
	global_load_lds_dwordx4 v[128:129], off nt
	s_waitcnt lgkmcnt(2)
	v_mfma_f32_16x16x32_bf16 v[112:115], v[216:219], v[244:247], v[112:115]
	ds_read_b128 v[240:243], v168 offset:22528
	v_mfma_f32_16x16x32_bf16 v[96:99], v[220:223], v[244:247], v[96:99]
	v_mfma_f32_16x16x32_bf16 v[64:67], v[224:227], v[244:247], v[64:67]
	v_mfma_f32_16x16x32_bf16 v[32:35], v[228:231], v[244:247], v[32:35]
	s_waitcnt lgkmcnt(2)
	v_mfma_f32_16x16x32_bf16 v[92:95], v[216:219], v[232:235], v[92:95]
	ds_read_b128 v[244:247], v168 offset:23552
	v_mfma_f32_16x16x32_bf16 v[60:63], v[220:223], v[232:235], v[60:63]
	ds_read_b128 v[186:189], v167 offset:32768
	v_mfma_f32_16x16x32_bf16 v[28:31], v[224:227], v[232:235], v[28:31]
	ds_read_b128 v[190:193], v167 offset:33792
	v_mfma_f32_16x16x32_bf16 v[12:15], v[228:231], v[232:235], v[12:15]
	ds_read_b128 v[194:197], v167 offset:34816
	s_waitcnt lgkmcnt(5)
	v_mfma_f32_16x16x32_bf16 v[84:87], v[216:219], v[236:239], v[84:87]
	ds_read_b128 v[202:205], v167 offset:35840
	ds_read_b128 v[232:235], v168 offset:49152
	v_mfma_f32_16x16x32_bf16 v[56:59], v[220:223], v[236:239], v[56:59]
	v_mfma_f32_16x16x32_bf16 v[24:27], v[224:227], v[236:239], v[24:27]
	v_mfma_f32_16x16x32_bf16 v[8:11], v[228:231], v[236:239], v[8:11]
	s_waitcnt lgkmcnt(6)
	v_mfma_f32_16x16x32_bf16 v[80:83], v[216:219], v[240:243], v[80:83]
	ds_read_b128 v[236:239], v168 offset:50176
	v_mfma_f32_16x16x32_bf16 v[52:55], v[220:223], v[240:243], v[52:55]
	v_mfma_f32_16x16x32_bf16 v[20:23], v[224:227], v[240:243], v[20:23]
	v_mfma_f32_16x16x32_bf16 v[4:7], v[228:231], v[240:243], v[4:7]
	s_waitcnt lgkmcnt(6)
	v_mfma_f32_16x16x32_bf16 v[72:75], v[216:219], v[244:247], v[72:75]
	ds_read_b128 v[240:243], v168 offset:51200
	v_mfma_f32_16x16x32_bf16 v[48:51], v[220:223], v[244:247], v[48:51]
	v_mfma_f32_16x16x32_bf16 v[16:19], v[224:227], v[244:247], v[16:19]
	v_mfma_f32_16x16x32_bf16 v[0:3], v[228:231], v[244:247], v[0:3]
	ds_read_b128 v[244:247], v168 offset:52224
	s_waitcnt lgkmcnt(3)
	v_mfma_f32_16x16x32_bf16 v[124:127], v[186:189], v[232:235], v[124:127]
	v_mfma_f32_16x16x32_bf16 v[108:111], v[190:193], v[232:235], v[108:111]
	v_mfma_f32_16x16x32_bf16 v[88:91], v[194:197], v[232:235], v[88:91]
	v_mfma_f32_16x16x32_bf16 v[44:47], v[202:205], v[232:235], v[44:47]
	s_waitcnt vmcnt(4)
	s_barrier
	s_waitcnt lgkmcnt(2)
	v_mfma_f32_16x16x32_bf16 v[120:123], v[186:189], v[236:239], v[120:123]
	ds_read_b128 v[232:235], v168 offset:53248
	v_mfma_f32_16x16x32_bf16 v[104:107], v[190:193], v[236:239], v[104:107]
	v_mfma_f32_16x16x32_bf16 v[76:79], v[194:197], v[236:239], v[76:79]
	v_mfma_f32_16x16x32_bf16 v[40:43], v[202:205], v[236:239], v[40:43]
	s_waitcnt lgkmcnt(2)
	v_mfma_f32_16x16x32_bf16 v[116:119], v[186:189], v[240:243], v[116:119]
	ds_read_b128 v[236:239], v168 offset:54272
	v_mfma_f32_16x16x32_bf16 v[100:103], v[190:193], v[240:243], v[100:103]
	v_mfma_f32_16x16x32_bf16 v[68:71], v[194:197], v[240:243], v[68:71]
	v_mfma_f32_16x16x32_bf16 v[36:39], v[202:205], v[240:243], v[36:39]
	s_waitcnt lgkmcnt(2)
	v_mfma_f32_16x16x32_bf16 v[112:115], v[186:189], v[244:247], v[112:115]
	ds_read_b128 v[240:243], v168 offset:55296
	v_mfma_f32_16x16x32_bf16 v[96:99], v[190:193], v[244:247], v[96:99]
	v_mfma_f32_16x16x32_bf16 v[64:67], v[194:197], v[244:247], v[64:67]
	v_mfma_f32_16x16x32_bf16 v[32:35], v[202:205], v[244:247], v[32:35]
	s_waitcnt lgkmcnt(2)
	v_mfma_f32_16x16x32_bf16 v[92:95], v[186:189], v[232:235], v[92:95]
	ds_read_b128 v[244:247], v168 offset:56320
	v_mfma_f32_16x16x32_bf16 v[60:63], v[190:193], v[232:235], v[60:63]
	v_mfma_f32_16x16x32_bf16 v[28:31], v[194:197], v[232:235], v[28:31]
	v_mfma_f32_16x16x32_bf16 v[12:15], v[202:205], v[232:235], v[12:15]
	s_waitcnt lgkmcnt(2)
	v_mfma_f32_16x16x32_bf16 v[84:87], v[186:189], v[236:239], v[84:87]
	v_mfma_f32_16x16x32_bf16 v[56:59], v[190:193], v[236:239], v[56:59]
	v_mfma_f32_16x16x32_bf16 v[24:27], v[194:197], v[236:239], v[24:27]
	v_mfma_f32_16x16x32_bf16 v[8:11], v[202:205], v[236:239], v[8:11]
	s_waitcnt lgkmcnt(1)
	v_mfma_f32_16x16x32_bf16 v[80:83], v[186:189], v[240:243], v[80:83]
	v_mfma_f32_16x16x32_bf16 v[52:55], v[190:193], v[240:243], v[52:55]
	v_mfma_f32_16x16x32_bf16 v[20:23], v[194:197], v[240:243], v[20:23]
	v_mfma_f32_16x16x32_bf16 v[4:7], v[202:205], v[240:243], v[4:7]
	s_waitcnt lgkmcnt(0)
	v_mfma_f32_16x16x32_bf16 v[72:75], v[186:189], v[244:247], v[72:75]
	v_mfma_f32_16x16x32_bf16 v[48:51], v[190:193], v[244:247], v[48:51]
	v_mfma_f32_16x16x32_bf16 v[16:19], v[194:197], v[244:247], v[16:19]
	v_mfma_f32_16x16x32_bf16 v[0:3], v[202:205], v[244:247], v[0:3]
	v_mov_b32_e32 v186, 0xf149f2ca
	v_mov_b32_e32 v187, 0x3c0881c4
	v_mov_b32_e32 v188, 0xbab64f3b
	v_mov_b32_e32 v189, 0x24800
	v_mov_b32_e32 v190, 1
	v_mov_b32_e32 v191, 0x24804
	v_mov_b32_e32 v192, 0xfcf
	v_mov_b32_e32 v193, 0x7cf
	v_mov_b32_e32 v194, 0xfdf
	v_mov_b32_e32 v195, 0x7df
	v_mov_b32_e32 v196, 0xfef
	v_mov_b32_e32 v197, 0x7ef
	v_mov_b32_e32 v198, 0xfff
	v_mov_b32_e32 v199, 0x7ff
	v_mov_b32_e32 v200, 0x20000
	v_mov_b32_e32 v201, 0xf8f
	v_mov_b32_e32 v202, 0x78f
	v_mov_b32_e32 v203, 0xf9f
	v_mov_b32_e32 v204, 0x79f
	v_mov_b32_e32 v205, 0xfaf
	s_waitcnt vmcnt(4)
	s_barrier
; #define BIG_SYNC(N)                                              \
;   asm volatile("s_waitcnt vmcnt(%0)" ::"n"(N) : "memory");       \
;   __builtin_amdgcn_s_barrier();                                  \
;   asm volatile("" ::: "memory");                                 \
;   __builtin_amdgcn_sched_barrier(0);
; template <int NK, bool BNT = false> ...
;     ...
; #pragma unroll
;     for (int n = 0; n < 4; ++n) bfr[n] = *reinterpret_cast<const bf16x8*>(sa + boff + (4 + n) * 1024);
; #pragma unroll
;     for (int m = 0; m < 4; ++m)
; #pragma unroll
;       for (int n = 0; n < 4; ++n)
;         acc[m][4 + n] = __builtin_amdgcn_mfma_f32_16x16x32_bf16(af[m], bfr[n], acc[m][4 + n], 0, 0, 0);
;     __builtin_amdgcn_sched_barrier(0);
;   };
;     ...
;   stage(0, 0);
;   stage(1, 1);
;   stage(2, 2);
;   for (int it = 0; it < NK / 4 - 1; ++it) {
;     const int t = it * 4;
;     BIG_SYNC(2 * NG); kstep(t, 0, 3, true);
;     BIG_SYNC(2 * NG); kstep(t + 1, 1, 0, true);
;     BIG_SYNC(2 * NG); kstep(t + 2, 2, 1, true);
;     BIG_SYNC(2 * NG); kstep(t + 3, 3, 2, true);
;   }
;   BIG_SYNC(2 * NG); kstep(NK - 4, 0, 3, true);
;   BIG_SYNC(2 * NG); kstep(NK - 3, 1, 0, false);
;   BIG_SYNC(NG);     kstep(NK - 2, 2, 0, false);
;   BIG_SYNC(0);      kstep(NK - 1, 3, 0, false);
	ds_read_b128 v[128:131], v162
	ds_read_b128 v[138:141], v162 offset:1024
	ds_read_b128 v[146:149], v162 offset:2048
	ds_read_b128 v[154:157], v162 offset:3072
	ds_read_b128 v[158:161], v163
	ds_read_b128 v[216:219], v164
	ds_read_b128 v[162:165], v165
	ds_read_b128 v[220:223], v172
	s_waitcnt lgkmcnt(0)
	v_mfma_f32_16x16x32_bf16 v[124:127], v[128:131], v[158:161], v[124:127]
	v_mfma_f32_16x16x32_bf16 v[116:119], v[128:131], v[162:165], v[116:119]
	v_mfma_f32_16x16x32_bf16 v[112:115], v[128:131], v[220:223], v[112:115]
	v_mfma_f32_16x16x32_bf16 v[104:107], v[138:141], v[216:219], v[104:107]
	v_mfma_f32_16x16x32_bf16 v[100:103], v[138:141], v[162:165], v[100:103]
	v_mfma_f32_16x16x32_bf16 v[96:99], v[138:141], v[220:223], v[96:99]
	v_mfma_f32_16x16x32_bf16 v[68:71], v[146:149], v[162:165], v[68:71]
	v_mfma_f32_16x16x32_bf16 v[64:67], v[146:149], v[220:223], v[64:67]
	v_mfma_f32_16x16x32_bf16 v[44:47], v[154:157], v[158:161], v[44:47]
	v_mfma_f32_16x16x32_bf16 v[40:43], v[154:157], v[216:219], v[40:43]
	v_mfma_f32_16x16x32_bf16 v[36:39], v[154:157], v[162:165], v[36:39]
	v_mfma_f32_16x16x32_bf16 v[32:35], v[154:157], v[220:223], v[32:35]
	v_mfma_f32_16x16x32_bf16 v[120:123], v[128:131], v[216:219], v[120:123]
	v_mfma_f32_16x16x32_bf16 v[224:227], v[138:141], v[158:161], v[108:111]
	v_mfma_f32_16x16x32_bf16 v[228:231], v[146:149], v[158:161], v[88:91]
	v_mfma_f32_16x16x32_bf16 v[232:235], v[146:149], v[216:219], v[76:79]
	s_nop 2
	ds_read_b128 v[76:79], v173
	ds_read_b128 v[88:91], v174
	s_waitcnt lgkmcnt(0)
	v_mfma_f32_16x16x32_bf16 v[158:161], v[128:131], v[76:79], v[92:95]
	s_nop 2
	ds_read_b128 v[92:95], v178
	v_mfma_f32_16x16x32_bf16 v[162:165], v[128:131], v[88:91], v[84:87]
	s_nop 2
	ds_read_b128 v[84:87], v175
	s_waitcnt lgkmcnt(0)
	v_mfma_f32_16x16x32_bf16 v[172:175], v[128:131], v[84:87], v[80:83]
	v_mfma_f32_16x16x32_bf16 v[128:131], v[128:131], v[92:95], v[72:75]
	v_mfma_f32_16x16x32_bf16 v[216:219], v[138:141], v[76:79], v[60:63]
	v_mfma_f32_16x16x32_bf16 v[220:223], v[138:141], v[88:91], v[56:59]
	v_mfma_f32_16x16x32_bf16 v[52:55], v[138:141], v[84:87], v[52:55]
	v_mfma_f32_16x16x32_bf16 v[48:51], v[138:141], v[92:95], v[48:51]
	v_mfma_f32_16x16x32_bf16 v[138:141], v[146:149], v[76:79], v[28:31]
	v_mfma_f32_16x16x32_bf16 v[236:239], v[146:149], v[88:91], v[24:27]
	v_mfma_f32_16x16x32_bf16 v[20:23], v[146:149], v[84:87], v[20:23]
	v_mfma_f32_16x16x32_bf16 v[16:19], v[146:149], v[92:95], v[16:19]
	v_mfma_f32_16x16x32_bf16 v[146:149], v[154:157], v[76:79], v[12:15]
	v_mfma_f32_16x16x32_bf16 v[0:3], v[154:157], v[92:95], v[0:3]
	v_mfma_f32_16x16x32_bf16 v[240:243], v[154:157], v[88:91], v[8:11]
	v_mfma_f32_16x16x32_bf16 v[244:247], v[154:157], v[84:87], v[4:7]
	s_waitcnt vmcnt(0)
	s_barrier
	s_nop 1
	ds_read_b128 v[4:7], v176
	ds_read_b128 v[8:11], v176 offset:1024
	ds_read_b128 v[154:157], v176 offset:2048
	ds_read_b128 v[12:15], v179
	ds_read_b128 v[24:27], v180
	ds_read_b128 v[28:31], v181
	ds_read_b128 v[56:59], v182
	ds_read_b128 v[248:251], v176 offset:3072
	s_waitcnt lgkmcnt(0)
	v_mfma_f32_16x16x32_bf16 v[108:111], v[4:7], v[24:27], v[120:123]
	v_mfma_f32_16x16x32_bf16 v[92:95], v[4:7], v[28:31], v[116:119]
	v_mfma_f32_16x16x32_bf16 v[76:79], v[4:7], v[56:59], v[112:115]
	v_mfma_f32_16x16x32_bf16 v[104:107], v[8:11], v[24:27], v[104:107]
	v_mfma_f32_16x16x32_bf16 v[88:91], v[8:11], v[28:31], v[100:103]
	v_mfma_f32_16x16x32_bf16 v[72:75], v[8:11], v[56:59], v[96:99]
	v_mfma_f32_16x16x32_bf16 v[100:103], v[154:157], v[24:27], v[232:235]
	v_mfma_f32_16x16x32_bf16 v[84:87], v[154:157], v[28:31], v[68:71]
	v_mfma_f32_16x16x32_bf16 v[68:71], v[154:157], v[56:59], v[64:67]
	v_mfma_f32_16x16x32_bf16 v[116:119], v[248:251], v[12:15], v[44:47]
	v_mfma_f32_16x16x32_bf16 v[96:99], v[248:251], v[24:27], v[40:43]
	v_mfma_f32_16x16x32_bf16 v[80:83], v[248:251], v[28:31], v[36:39]
	v_mfma_f32_16x16x32_bf16 v[64:67], v[248:251], v[56:59], v[32:35]
	v_mfma_f32_16x16x32_bf16 v[178:181], v[4:7], v[12:15], v[124:127]
	v_mfma_f32_16x16x32_bf16 v[224:227], v[8:11], v[12:15], v[224:227]
	v_mfma_f32_16x16x32_bf16 v[120:123], v[154:157], v[12:15], v[228:231]
	ds_read_b128 v[32:35], v142
	ds_read_b128 v[112:115], v143
	ds_read_b128 v[124:127], v144
	ds_read_b128 v[142:145], v145
	s_waitcnt lgkmcnt(0)
; __device__ __forceinline__ float bf2f(bf16_t b) { return __uint_as_float(((unsigned)b) << 16); }
; __device__ __forceinline__ int widen_off(int fq) { return ((fq & 1) << 4) + ((fq >> 1) << 3); }
; template <int MODE, int NSUB>
; __device__ __forceinline__ void epilogue(const Params& p, int layer, f32x4 (&acc)[4][NSUB], int tm, int tn, int g,
;                                          const float* s_rstd, const int tid_in) {
;     ...
;   } else if constexpr (MODE == EPI_RES) {
;     const int fb = tm * 128 + wr * 64 + fq * 4;
;     const int tb = tn * (NSUB * 32) + wc * (NSUB * 16) + fr;
;     const int fw = tm * 128 + wr * 64 + widen_off(fq);
;     u32x4 curw[2], nxtw[2];
; #pragma unroll
;     for (int mp = 0; mp < 2; ++mp) curw[mp] = *reinterpret_cast<const u32x4*>(p.xb + blk(tb, fw + mp * 32, 32));
; #pragma unroll
;     for (int n = 0; n < NSUB; ++n) {
;       if (n + 1 < NSUB) {
; #pragma unroll
;         for (int mp = 0; mp < 2; ++mp) nxtw[mp] = *reinterpret_cast<const u32x4*>(p.xb + blk(tb + (n + 1) * 16, fw + mp * 32, 32));
;       }
;       bf16x4 cur[4];
;       unwiden_pair(curw[0], cur[0], cur[1]);
;       unwiden_pair(curw[1], cur[2], cur[3]);
;       const int t = tb + n * 16;
;       float ss = 0.f;
; #pragma unroll
;       for (int mp = 0; mp < 2; ++mp) {
;         bf16x4 pk[2];
; #pragma unroll
;         for (int h2 = 0; h2 < 2; ++h2) {
;           const int m = mp * 2 + h2;
;           const float x0 = bf2f((bf16_t)cur[m][0]) + acc[m][n][0], x1 = bf2f((bf16_t)cur[m][1]) + acc[m][n][1];
;           const float x2 = bf2f((bf16_t)cur[m][2]) + acc[m][n][2], x3 = bf2f((bf16_t)cur[m][3]) + acc[m][n][3];
;           ss += x0 * x0 + x1 * x1 + x2 * x2 + x3 * x3;
;           pk[h2] = pack4(x0, x1, x2, x3);
;         }
;         const int f = tm * 128 + wr * 64 + mp * 32 + widen_off(fq);
;         *reinterpret_cast<u32x4*>(p.xb + blk(t, f, 32)) = widen_pair(pk[0], pk[1]);
;       }
;       ss = red_fq(ss);
;       if (fq == 0) p.part[(long)t * 16 + tm * 2 + wr] = ss;
;       curw[0] = nxtw[0];
;       curw[1] = nxtw[1];
;     }
	v_mfma_f32_16x16x32_bf16 v[60:63], v[4:7], v[32:35], v[158:161]
	v_mfma_f32_16x16x32_bf16 v[44:47], v[4:7], v[112:115], v[162:165]
	v_mfma_f32_16x16x32_bf16 v[28:31], v[4:7], v[124:127], v[172:175]
	v_mfma_f32_16x16x32_bf16 v[12:15], v[4:7], v[142:145], v[128:131]
	v_mfma_f32_16x16x32_bf16 v[56:59], v[8:11], v[32:35], v[216:219]
	v_mfma_f32_16x16x32_bf16 v[40:43], v[8:11], v[112:115], v[220:223]
	v_mfma_f32_16x16x32_bf16 v[24:27], v[8:11], v[124:127], v[52:55]
	v_mfma_f32_16x16x32_bf16 v[8:11], v[8:11], v[142:145], v[48:51]
	v_mfma_f32_16x16x32_bf16 v[52:55], v[154:157], v[32:35], v[138:141]
	v_mfma_f32_16x16x32_bf16 v[36:39], v[154:157], v[112:115], v[236:239]
	v_mfma_f32_16x16x32_bf16 v[20:23], v[154:157], v[124:127], v[20:23]
	v_mfma_f32_16x16x32_bf16 v[4:7], v[154:157], v[142:145], v[16:19]
	v_mfma_f32_16x16x32_bf16 v[48:51], v[248:251], v[32:35], v[146:149]
	v_mfma_f32_16x16x32_bf16 v[32:35], v[248:251], v[112:115], v[240:243]
	v_mfma_f32_16x16x32_bf16 v[16:19], v[248:251], v[124:127], v[244:247]
	v_mfma_f32_16x16x32_bf16 v[0:3], v[248:251], v[142:145], v[0:3]
	v_lshl_add_u32 v124, s13, 1, v170
	v_mov_b32_e32 v112, v215
	v_lshlrev_b32_e32 v113, 7, v124
	v_ashrrev_i32_e32 v138, 7, v112
	s_mul_i32 s13, s15, 0x140
	v_lshl_add_u32 v114, v138, 6, v113
	v_lshlrev_b32_e32 v113, 1, v112
	s_add_i32 s12, s12, s13
	v_and_b32_e32 v113, 0x80, v113
	v_lshl_or_b32 v127, s12, 8, v113
	v_lshrrev_b32_e32 v113, 2, v112
	v_and_b32_e32 v125, 15, v112
	v_and_b32_e32 v113, 8, v113
	v_ashrrev_i32_e32 v115, 2, v127
	v_readlane_b32 s80, v253, 25
	v_ashrrev_i32_e32 v114, 5, v114
	v_bfe_u32 v126, v112, 4, 2
	v_and_or_b32 v112, v112, 16, v113
	v_lshlrev_b32_e32 v156, 6, v125
	v_mov_b32_e32 v157, v153
	v_readlane_b32 s84, v253, 29
	v_readlane_b32 s85, v253, 30
	v_add_u32_e32 v114, v114, v115
	v_lshlrev_b32_e32 v152, 1, v112
	v_lshl_add_u64 v[144:145], s[84:85], 0, v[156:157]
	v_ashrrev_i32_e32 v115, 31, v114
	v_lshl_add_u64 v[112:113], v[144:145], 0, v[152:153]
	v_lshlrev_b64 v[146:147], 13, v[114:115]
	v_or_b32_e32 v114, 1, v114
	v_lshl_add_u64 v[150:151], v[112:113], 0, v[146:147]
	v_ashrrev_i32_e32 v115, 31, v114
	global_load_dwordx4 v[158:161], v[150:151], off
	v_lshlrev_b64 v[148:149], 13, v[114:115]
	v_lshl_add_u64 v[154:155], v[112:113], 0, v[148:149]
	global_load_dwordx4 v[128:131], v[154:155], off
	v_and_b32_e32 v113, 64, v185
	v_xor_b32_e32 v112, 16, v185
	v_add_u32_e32 v113, 64, v113
	v_cmp_lt_i32_e32 vcc, v112, v113
	v_or_b32_e32 v142, v127, v125
	v_lshlrev_b32_e32 v140, 1, v124
	v_cndmask_b32_e32 v112, v185, v112, vcc
	v_lshlrev_b32_e32 v172, 2, v112
	v_xor_b32_e32 v112, 32, v185
	v_cmp_lt_i32_e32 vcc, v112, v113
	v_ashrrev_i32_e32 v141, 31, v140
	v_ashrrev_i32_e32 v139, 31, v138
	v_cndmask_b32_e32 v112, v185, v112, vcc
	v_lshlrev_b32_e32 v173, 2, v112
	v_cmp_eq_u32_e32 vcc, 0, v126
	global_load_dwordx4 v[124:127], v[150:151], off offset:1024
	global_load_dwordx4 v[112:115], v[154:155], off offset:1024
	v_readlane_b32 s81, v253, 26
	v_readlane_b32 s82, v253, 27
	v_readlane_b32 s83, v253, 28
	v_readlane_b32 s86, v253, 31
	v_readlane_b32 s87, v253, 32
	v_readlane_b32 s88, v253, 33
	v_readlane_b32 s89, v253, 34
	v_readlane_b32 s90, v253, 35
	v_readlane_b32 s91, v253, 36
	v_readlane_b32 s92, v253, 37
	v_readlane_b32 s93, v253, 38
	v_readlane_b32 s94, v253, 39
	v_readlane_b32 s95, v253, 40
	s_waitcnt vmcnt(0)
	v_mov_b32_e32 v143, v160
	s_nop 1
	v_permlane16_swap_b32_e32 v158, v143
	v_mov_b32_e32 v164, v161
	s_nop 1
	v_permlane16_swap_b32_e32 v159, v164
	v_mov_b32_e32 v176, v130
	v_mov_b32_e32 v182, v131
	v_and_b32_e32 v131, 0xffff0000, v158
	v_lshlrev_b32_e32 v130, 16, v158
	v_pk_add_f32 v[130:131], v[178:179], v[130:131]
	v_and_b32_e32 v161, 0xffff0000, v159
	v_lshlrev_b32_e32 v160, 16, v159
	v_pk_add_f32 v[162:163], v[180:181], v[160:161]
	v_pk_mul_f32 v[160:161], v[130:131], v[130:131]
	v_cvt_pk_bf16_f32 v178, v130, v131
	v_and_b32_e32 v131, 0xffff0000, v143
	v_lshlrev_b32_e32 v130, 16, v143
	v_pk_mul_f32 v[158:159], v[162:163], v[162:163]
	v_cvt_pk_bf16_f32 v179, v162, v163
	v_pk_add_f32 v[130:131], v[224:225], v[130:131]
	v_and_b32_e32 v163, 0xffff0000, v164
	v_lshlrev_b32_e32 v162, 16, v164
	v_pk_add_f32 v[174:175], v[226:227], v[162:163]
	v_pk_mul_f32 v[164:165], v[130:131], v[130:131]
	v_cvt_pk_bf16_f32 v180, v130, v131
	v_lshl_add_u64 v[130:131], s[84:85], 0, v[146:147]
	v_pk_mul_f32 v[162:163], v[174:175], v[174:175]
	v_cvt_pk_bf16_f32 v181, v174, v175
	v_lshl_add_u64 v[174:175], v[130:131], 0, v[156:157]
	v_permlane16_swap_b32_e32 v128, v176
	v_permlane16_swap_b32_e32 v178, v180
	v_permlane16_swap_b32_e32 v179, v181
	v_lshl_add_u64 v[174:175], v[174:175], 0, v[152:153]
	v_permlane16_swap_b32_e32 v129, v182
	global_store_dwordx4 v[174:175], v[178:181], off
	v_and_b32_e32 v175, 0xffff0000, v128
	v_lshlrev_b32_e32 v174, 16, v128
	v_pk_add_f32 v[120:121], v[120:121], v[174:175]
	v_and_b32_e32 v175, 0xffff0000, v129
	v_lshlrev_b32_e32 v174, 16, v129
	v_pk_add_f32 v[122:123], v[122:123], v[174:175]
	v_pk_mul_f32 v[128:129], v[120:121], v[120:121]
	v_pk_mul_f32 v[174:175], v[122:123], v[122:123]
	v_cvt_pk_bf16_f32 v120, v120, v121
	v_cvt_pk_bf16_f32 v121, v122, v123
	v_and_b32_e32 v123, 0xffff0000, v176
	v_lshlrev_b32_e32 v122, 16, v176
	v_pk_add_f32 v[116:117], v[116:117], v[122:123]
	v_and_b32_e32 v123, 0xffff0000, v182
	v_lshlrev_b32_e32 v122, 16, v182
	v_add_f32_e32 v143, v164, v165
	v_add_f32_e32 v160, v160, v161
	v_pk_add_f32 v[118:119], v[118:119], v[122:123]
	v_pk_mul_f32 v[122:123], v[116:117], v[116:117]
	v_add_f32_e32 v143, v162, v143
	v_add_f32_e32 v158, v158, v160
	v_add_f32_e32 v128, v128, v129
	v_pk_mul_f32 v[178:179], v[118:119], v[118:119]
	v_add_f32_e32 v143, v163, v143
	v_add_f32_e32 v158, v159, v158
	v_add_f32_e32 v128, v174, v128
	v_add_f32_e32 v122, v122, v123
	v_add_f32_e32 v143, v158, v143
	v_add_f32_e32 v128, v175, v128
	v_add_f32_e32 v122, v178, v122
	v_add_f32_e32 v128, v143, v128
	v_add_f32_e32 v122, v179, v122
	v_add_f32_e32 v143, v122, v128
	v_lshl_add_u64 v[128:129], s[84:85], 0, v[148:149]
	v_cvt_pk_bf16_f32 v122, v116, v117
	v_cvt_pk_bf16_f32 v123, v118, v119
	v_lshl_add_u64 v[116:117], v[128:129], 0, v[156:157]
	v_permlane16_swap_b32_e32 v120, v122
	v_permlane16_swap_b32_e32 v121, v123
	v_lshl_add_u64 v[116:117], v[116:117], 0, v[152:153]
	global_store_dwordx4 v[116:117], v[120:123], off
	ds_bpermute_b32 v116, v172, v143
	s_waitcnt lgkmcnt(0)
	v_add_f32_e32 v116, v143, v116
	ds_bpermute_b32 v117, v173, v116
	s_and_saveexec_b64 s[12:13], vcc
	s_cbranch_execz .LBB0_267
; template <int MODE, int NSUB>
; __device__ __forceinline__ void epilogue(const Params& p, int layer, f32x4 (&acc)[4][NSUB], int tm, int tn, int g,
;                                          const float* s_rstd, const int tid_in) {
;     ...
;       ss = red_fq(ss);
;       if (fq == 0) p.part[(long)t * 16 + tm * 2 + wr] = ss;
	v_ashrrev_i32_e32 v143, 31, v142
	v_readlane_b32 s64, v253, 25
	v_lshlrev_b64 v[118:119], 6, v[142:143]
	v_readlane_b32 s70, v253, 31
	v_readlane_b32 s71, v253, 32
	s_waitcnt lgkmcnt(0)
	v_add_f32_e32 v116, v116, v117
	v_readlane_b32 s65, v253, 26
	v_lshl_add_u64 v[118:119], s[70:71], 0, v[118:119]
	v_lshl_add_u64 v[118:119], v[140:141], 2, v[118:119]
	v_lshl_add_u64 v[118:119], v[138:139], 2, v[118:119]
	v_readlane_b32 s66, v253, 27
	v_readlane_b32 s67, v253, 28
	v_readlane_b32 s68, v253, 29
	v_readlane_b32 s69, v253, 30
	v_readlane_b32 s72, v253, 33
	v_readlane_b32 s73, v253, 34
	v_readlane_b32 s74, v253, 35
	v_readlane_b32 s75, v253, 36
	v_readlane_b32 s76, v253, 37
	v_readlane_b32 s77, v253, 38
	v_readlane_b32 s78, v253, 39
	v_readlane_b32 s79, v253, 40
	global_store_dword v[118:119], v116, off

; #define BIG_SYNC(N)                                              \
;   asm volatile("s_waitcnt vmcnt(%0)" ::"n"(N) : "memory");       \
;   __builtin_amdgcn_s_barrier();                                  \
;   asm volatile("" ::: "memory");                                 \
;   __builtin_amdgcn_sched_barrier(0);
; template <int NK, bool BNT = false> ...
;     ...
;   auto kstep = [&](int T, int cur, int nxt, bool do_stage) {
;     const unsigned char* sa = smem + cur * BIG_STAGE;
;     bf16x8 af[4], bfr[4];
; #pragma unroll
;     for (int m = 0; m < 4; ++m) af[m] = *reinterpret_cast<const bf16x8*>(sa + aoff + m * 1024);
; #pragma unroll
;     for (int n = 0; n < 4; ++n) bfr[n] = *reinterpret_cast<const bf16x8*>(sa + boff + n * 1024);
;     __builtin_amdgcn_sched_barrier(0);
;     if (do_stage) stage(T + 3, nxt);
; #pragma unroll
;     for (int m = 0; m < 4; ++m)
; #pragma unroll
;       for (int n = 0; n < 4; ++n) acc[m][n] = __builtin_amdgcn_mfma_f32_16x16x32_bf16(af[m], bfr[n], acc[m][n], 0, 0, 0);
;     if (do_stage) {
; #pragma unroll
;       for (int q = 0; q < NG; ++q) {
;         __builtin_amdgcn_sched_group_barrier(0x008, 3, 0);
;         __builtin_amdgcn_sched_group_barrier(0x010, 1, 0);
;       }
;       __builtin_amdgcn_sched_group_barrier(0x008, 16 - 3 * NG, 0);
;     }
;     __builtin_amdgcn_sched_barrier(0);
; #pragma unroll
;     for (int n = 0; n < 4; ++n) bfr[n] = *reinterpret_cast<const bf16x8*>(sa + boff + (4 + n) * 1024);
; #pragma unroll
;     for (int m = 0; m < 4; ++m)
; #pragma unroll
;       for (int n = 0; n < 4; ++n)
;         acc[m][4 + n] = __builtin_amdgcn_mfma_f32_16x16x32_bf16(af[m], bfr[n], acc[m][4 + n], 0, 0, 0);
;     __builtin_amdgcn_sched_barrier(0);
;   };
;     ...
;   stage(0, 0);
;   stage(1, 1);
;   stage(2, 2);
;   for (int it = 0; it < NK / 4 - 1; ++it) {
;     const int t = it * 4;
;     BIG_SYNC(2 * NG); kstep(t, 0, 3, true);
;     BIG_SYNC(2 * NG); kstep(t + 1, 1, 0, true);
;     BIG_SYNC(2 * NG); kstep(t + 2, 2, 1, true);
;     BIG_SYNC(2 * NG); kstep(t + 3, 3, 2, true);
.LBB0_290:
	v_add_u32_e32 v163, 0x18000, v146
	v_lshl_add_u64 v[144:145], v[138:139], 0, s[12:13]
	v_readfirstlane_b32 s11, v163
	v_lshl_add_u64 v[164:165], v[144:145], 0, s[60:61]
	s_mov_b32 m0, s11
	s_waitcnt lgkmcnt(3)
	v_mfma_f32_16x16x32_bf16 v[124:127], v[216:219], v[232:235], v[124:127]
	v_lshl_add_u64 v[142:143], v[140:141], 0, s[12:13]
	v_lshl_add_u64 v[168:169], v[144:145], 0, s[80:81]
	v_lshl_add_u64 v[166:167], v[142:143], 0, s[60:61]
	v_mfma_f32_16x16x32_bf16 v[108:111], v[220:223], v[232:235], v[108:111]
	v_mfma_f32_16x16x32_bf16 v[88:91], v[224:227], v[232:235], v[88:91]
	s_waitcnt vmcnt(4)
	s_barrier
	global_load_lds_dwordx4 v[164:165], off
	v_add_u32_e32 v164, 0x1a000, v146
	v_add_u32_e32 v165, 0x1c000, v146
	v_readfirstlane_b32 s11, v164
	s_mov_b32 m0, s11
	v_readfirstlane_b32 s11, v165
	v_mfma_f32_16x16x32_bf16 v[44:47], v[228:231], v[232:235], v[44:47]
	s_waitcnt lgkmcnt(2)
	v_mfma_f32_16x16x32_bf16 v[120:123], v[216:219], v[236:239], v[120:123]
	ds_read_b128 v[232:235], v148 offset:20480
	v_mfma_f32_16x16x32_bf16 v[104:107], v[220:223], v[236:239], v[104:107]
	global_load_lds_dwordx4 v[168:169], off
	s_mov_b32 m0, s11
	v_mfma_f32_16x16x32_bf16 v[76:79], v[224:227], v[236:239], v[76:79]
	v_lshl_add_u64 v[168:169], v[142:143], 0, s[80:81]
	v_mfma_f32_16x16x32_bf16 v[40:43], v[228:231], v[236:239], v[40:43]
	s_waitcnt lgkmcnt(2)
	v_mfma_f32_16x16x32_bf16 v[116:119], v[216:219], v[240:243], v[116:119]
	ds_read_b128 v[236:239], v148 offset:21504
	global_load_lds_dwordx4 v[166:167], off
	v_add_u32_e32 v166, 0x1e000, v146
	v_mfma_f32_16x16x32_bf16 v[100:103], v[220:223], v[240:243], v[100:103]
	v_readfirstlane_b32 s11, v166
	s_mov_b32 m0, s11
	v_mfma_f32_16x16x32_bf16 v[68:71], v[224:227], v[240:243], v[68:71]
	v_mfma_f32_16x16x32_bf16 v[36:39], v[228:231], v[240:243], v[36:39]
	global_load_lds_dwordx4 v[168:169], off
	s_waitcnt lgkmcnt(2)
	v_mfma_f32_16x16x32_bf16 v[112:115], v[216:219], v[244:247], v[112:115]
	ds_read_b128 v[240:243], v148 offset:22528
	v_mfma_f32_16x16x32_bf16 v[96:99], v[220:223], v[244:247], v[96:99]
	v_mfma_f32_16x16x32_bf16 v[64:67], v[224:227], v[244:247], v[64:67]
	v_mfma_f32_16x16x32_bf16 v[32:35], v[228:231], v[244:247], v[32:35]
	s_waitcnt lgkmcnt(2)
	v_mfma_f32_16x16x32_bf16 v[92:95], v[216:219], v[232:235], v[92:95]
	ds_read_b128 v[244:247], v148 offset:23552
	v_mfma_f32_16x16x32_bf16 v[60:63], v[220:223], v[232:235], v[60:63]
	ds_read_b128 v[186:189], v147 offset:32768
	v_mfma_f32_16x16x32_bf16 v[28:31], v[224:227], v[232:235], v[28:31]
	ds_read_b128 v[190:193], v147 offset:33792
	v_mfma_f32_16x16x32_bf16 v[12:15], v[228:231], v[232:235], v[12:15]
	ds_read_b128 v[194:197], v147 offset:34816
	s_waitcnt lgkmcnt(5)
	v_mfma_f32_16x16x32_bf16 v[84:87], v[216:219], v[236:239], v[84:87]
	ds_read_b128 v[202:205], v147 offset:35840
	ds_read_b128 v[232:235], v148 offset:49152
	v_mfma_f32_16x16x32_bf16 v[56:59], v[220:223], v[236:239], v[56:59]
	v_mfma_f32_16x16x32_bf16 v[24:27], v[224:227], v[236:239], v[24:27]
	v_mfma_f32_16x16x32_bf16 v[8:11], v[228:231], v[236:239], v[8:11]
	s_waitcnt lgkmcnt(6)
	v_mfma_f32_16x16x32_bf16 v[80:83], v[216:219], v[240:243], v[80:83]
	ds_read_b128 v[236:239], v148 offset:50176
	v_mfma_f32_16x16x32_bf16 v[52:55], v[220:223], v[240:243], v[52:55]
	v_mfma_f32_16x16x32_bf16 v[20:23], v[224:227], v[240:243], v[20:23]
	v_mfma_f32_16x16x32_bf16 v[4:7], v[228:231], v[240:243], v[4:7]
	s_waitcnt lgkmcnt(6)
	v_mfma_f32_16x16x32_bf16 v[72:75], v[216:219], v[244:247], v[72:75]
	ds_read_b128 v[240:243], v148 offset:51200
	v_mfma_f32_16x16x32_bf16 v[48:51], v[220:223], v[244:247], v[48:51]
	v_mfma_f32_16x16x32_bf16 v[16:19], v[224:227], v[244:247], v[16:19]
	v_mfma_f32_16x16x32_bf16 v[0:3], v[228:231], v[244:247], v[0:3]
	ds_read_b128 v[244:247], v148 offset:52224
	v_readfirstlane_b32 s11, v146
	v_lshl_add_u64 v[168:169], v[144:145], 0, s[62:63]
	s_mov_b32 m0, s11
	v_readfirstlane_b32 s11, v151
	s_waitcnt lgkmcnt(3)
	v_mfma_f32_16x16x32_bf16 v[124:127], v[186:189], v[232:235], v[124:127]
	v_lshl_add_u64 v[182:183], v[142:143], 0, s[62:63]
	v_mfma_f32_16x16x32_bf16 v[108:111], v[190:193], v[232:235], v[108:111]
	v_mfma_f32_16x16x32_bf16 v[88:91], v[194:197], v[232:235], v[88:91]
	s_waitcnt vmcnt(4)
	s_barrier
; #define BIG_SYNC(N)                                              \
;   asm volatile("s_waitcnt vmcnt(%0)" ::"n"(N) : "memory");       \
;   __builtin_amdgcn_s_barrier();                                  \
;   asm volatile("" ::: "memory");                                 \
;   __builtin_amdgcn_sched_barrier(0);
; template <int NK, bool BNT = false> ...
;     ...
;   auto kstep = [&](int T, int cur, int nxt, bool do_stage) {
;     const unsigned char* sa = smem + cur * BIG_STAGE;
;     bf16x8 af[4], bfr[4];
; #pragma unroll
;     for (int m = 0; m < 4; ++m) af[m] = *reinterpret_cast<const bf16x8*>(sa + aoff + m * 1024);
; #pragma unroll
;     for (int n = 0; n < 4; ++n) bfr[n] = *reinterpret_cast<const bf16x8*>(sa + boff + n * 1024);
;     __builtin_amdgcn_sched_barrier(0);
;     if (do_stage) stage(T + 3, nxt);
; #pragma unroll
;     for (int m = 0; m < 4; ++m)
; #pragma unroll
;       for (int n = 0; n < 4; ++n) acc[m][n] = __builtin_amdgcn_mfma_f32_16x16x32_bf16(af[m], bfr[n], acc[m][n], 0, 0, 0);
;     if (do_stage) {
; #pragma unroll
;       for (int q = 0; q < NG; ++q) {
;         __builtin_amdgcn_sched_group_barrier(0x008, 3, 0);
;         __builtin_amdgcn_sched_group_barrier(0x010, 1, 0);
;       }
;       __builtin_amdgcn_sched_group_barrier(0x008, 16 - 3 * NG, 0);
;     }
;     __builtin_amdgcn_sched_barrier(0);
; #pragma unroll
;     for (int n = 0; n < 4; ++n) bfr[n] = *reinterpret_cast<const bf16x8*>(sa + boff + (4 + n) * 1024);
; #pragma unroll
;     for (int m = 0; m < 4; ++m)
; #pragma unroll
;       for (int n = 0; n < 4; ++n)
;         acc[m][4 + n] = __builtin_amdgcn_mfma_f32_16x16x32_bf16(af[m], bfr[n], acc[m][4 + n], 0, 0, 0);
;     __builtin_amdgcn_sched_barrier(0);
;   };
;     ...
;   stage(0, 0);
;   stage(1, 1);
;   stage(2, 2);
;   for (int it = 0; it < NK / 4 - 1; ++it) {
;     const int t = it * 4;
;     BIG_SYNC(2 * NG); kstep(t, 0, 3, true);
;     BIG_SYNC(2 * NG); kstep(t + 1, 1, 0, true);
;     BIG_SYNC(2 * NG); kstep(t + 2, 2, 1, true);
;     BIG_SYNC(2 * NG); kstep(t + 3, 3, 2, true);
	global_load_lds_dwordx4 v[168:169], off
	v_lshl_add_u64 v[168:169], v[144:145], 0, s[0:1]
	s_mov_b32 m0, s11
	v_readfirstlane_b32 s11, v152
	v_mfma_f32_16x16x32_bf16 v[44:47], v[202:205], v[232:235], v[44:47]
	s_waitcnt lgkmcnt(2)
	v_mfma_f32_16x16x32_bf16 v[120:123], v[186:189], v[236:239], v[120:123]
	ds_read_b128 v[232:235], v148 offset:53248
	v_mfma_f32_16x16x32_bf16 v[104:107], v[190:193], v[236:239], v[104:107]
	global_load_lds_dwordx4 v[168:169], off
	s_mov_b32 m0, s11
	v_readfirstlane_b32 s11, v154
	v_lshl_add_u64 v[168:169], v[142:143], 0, s[0:1]
	v_mfma_f32_16x16x32_bf16 v[76:79], v[194:197], v[236:239], v[76:79]
	v_mfma_f32_16x16x32_bf16 v[40:43], v[202:205], v[236:239], v[40:43]
	s_waitcnt lgkmcnt(2)
	v_mfma_f32_16x16x32_bf16 v[116:119], v[186:189], v[240:243], v[116:119]
	ds_read_b128 v[236:239], v148 offset:54272
	global_load_lds_dwordx4 v[182:183], off
	s_mov_b32 m0, s11
	v_mfma_f32_16x16x32_bf16 v[100:103], v[190:193], v[240:243], v[100:103]
	v_mfma_f32_16x16x32_bf16 v[68:71], v[194:197], v[240:243], v[68:71]
	v_mfma_f32_16x16x32_bf16 v[36:39], v[202:205], v[240:243], v[36:39]
	global_load_lds_dwordx4 v[168:169], off
	s_waitcnt lgkmcnt(2)
	v_mfma_f32_16x16x32_bf16 v[112:115], v[186:189], v[244:247], v[112:115]
	ds_read_b128 v[240:243], v148 offset:55296
	v_mfma_f32_16x16x32_bf16 v[96:99], v[190:193], v[244:247], v[96:99]
	v_mfma_f32_16x16x32_bf16 v[64:67], v[194:197], v[244:247], v[64:67]
	v_mfma_f32_16x16x32_bf16 v[32:35], v[202:205], v[244:247], v[32:35]
	v_add_u32_e32 v167, 0x10000, v147
	v_or_b32_e32 v168, 0x10000, v149
	s_waitcnt lgkmcnt(2)
	v_mfma_f32_16x16x32_bf16 v[92:95], v[186:189], v[232:235], v[92:95]
	ds_read_b128 v[244:247], v148 offset:56320
	v_mfma_f32_16x16x32_bf16 v[60:63], v[190:193], v[232:235], v[60:63]
	ds_read_b128 v[216:219], v167
	v_mfma_f32_16x16x32_bf16 v[28:31], v[194:197], v[232:235], v[28:31]
	ds_read_b128 v[220:223], v167 offset:1024
	v_mfma_f32_16x16x32_bf16 v[12:15], v[202:205], v[232:235], v[12:15]
	ds_read_b128 v[224:227], v167 offset:2048
	s_waitcnt lgkmcnt(5)
	v_mfma_f32_16x16x32_bf16 v[84:87], v[186:189], v[236:239], v[84:87]
	ds_read_b128 v[228:231], v167 offset:3072
	ds_read_b128 v[232:235], v168
	v_mfma_f32_16x16x32_bf16 v[56:59], v[190:193], v[236:239], v[56:59]
	v_mfma_f32_16x16x32_bf16 v[24:27], v[194:197], v[236:239], v[24:27]
	v_mfma_f32_16x16x32_bf16 v[8:11], v[202:205], v[236:239], v[8:11]
	s_waitcnt lgkmcnt(6)
	v_mfma_f32_16x16x32_bf16 v[80:83], v[186:189], v[240:243], v[80:83]
	ds_read_b128 v[236:239], v168 offset:1024
	v_mfma_f32_16x16x32_bf16 v[52:55], v[190:193], v[240:243], v[52:55]
	v_mfma_f32_16x16x32_bf16 v[20:23], v[194:197], v[240:243], v[20:23]
	v_mfma_f32_16x16x32_bf16 v[4:7], v[202:205], v[240:243], v[4:7]
	s_waitcnt lgkmcnt(6)
	v_mfma_f32_16x16x32_bf16 v[72:75], v[186:189], v[244:247], v[72:75]
	ds_read_b128 v[240:243], v168 offset:2048
	v_mfma_f32_16x16x32_bf16 v[48:51], v[190:193], v[244:247], v[48:51]
	v_mfma_f32_16x16x32_bf16 v[16:19], v[194:197], v[244:247], v[16:19]
	v_mfma_f32_16x16x32_bf16 v[0:3], v[202:205], v[244:247], v[0:3]
	ds_read_b128 v[244:247], v168 offset:3072
	v_add_u32_e32 v167, 0x10000, v147
	v_or_b32_e32 v168, 0x10000, v149
	v_add_u32_e32 v169, 0x10400, v149
	v_add_u32_e32 v170, 0x10800, v149
	v_add_u32_e32 v172, 0x10c00, v149
	v_readfirstlane_b32 s11, v155
	v_lshl_add_u64 v[174:175], v[144:145], 0, s[2:3]
	s_mov_b32 m0, s11
	v_readfirstlane_b32 s11, v156
	s_waitcnt lgkmcnt(3)
	v_mfma_f32_16x16x32_bf16 v[124:127], v[216:219], v[232:235], v[124:127]
	v_lshl_add_u64 v[178:179], v[142:143], 0, s[2:3]
	v_mfma_f32_16x16x32_bf16 v[108:111], v[220:223], v[232:235], v[108:111]
	v_mfma_f32_16x16x32_bf16 v[88:91], v[224:227], v[232:235], v[88:91]
	s_waitcnt vmcnt(4)
	s_barrier
	global_load_lds_dwordx4 v[174:175], off
	v_lshl_add_u64 v[174:175], v[144:145], 0, s[52:53]
	s_mov_b32 m0, s11
	v_readfirstlane_b32 s11, v157
	v_mfma_f32_16x16x32_bf16 v[44:47], v[228:231], v[232:235], v[44:47]
	s_waitcnt lgkmcnt(2)
	v_mfma_f32_16x16x32_bf16 v[120:123], v[216:219], v[236:239], v[120:123]
	ds_read_b128 v[232:235], v168 offset:4096
	v_mfma_f32_16x16x32_bf16 v[104:107], v[220:223], v[236:239], v[104:107]
	global_load_lds_dwordx4 v[174:175], off
	s_mov_b32 m0, s11
	v_readfirstlane_b32 s11, v158
	v_lshl_add_u64 v[174:175], v[142:143], 0, s[52:53]
	v_mfma_f32_16x16x32_bf16 v[76:79], v[224:227], v[236:239], v[76:79]
	v_mfma_f32_16x16x32_bf16 v[40:43], v[228:231], v[236:239], v[40:43]
	s_waitcnt lgkmcnt(2)
	v_mfma_f32_16x16x32_bf16 v[116:119], v[216:219], v[240:243], v[116:119]
	ds_read_b128 v[236:239], v168 offset:5120
	global_load_lds_dwordx4 v[178:179], off
	s_mov_b32 m0, s11
	v_mfma_f32_16x16x32_bf16 v[100:103], v[220:223], v[240:243], v[100:103]
	v_mfma_f32_16x16x32_bf16 v[68:71], v[224:227], v[240:243], v[68:71]
	v_mfma_f32_16x16x32_bf16 v[36:39], v[228:231], v[240:243], v[36:39]
	global_load_lds_dwordx4 v[174:175], off
	s_waitcnt lgkmcnt(2)
	v_mfma_f32_16x16x32_bf16 v[112:115], v[216:219], v[244:247], v[112:115]
	ds_read_b128 v[240:243], v168 offset:6144
	v_mfma_f32_16x16x32_bf16 v[96:99], v[220:223], v[244:247], v[96:99]
	v_mfma_f32_16x16x32_bf16 v[64:67], v[224:227], v[244:247], v[64:67]
	v_mfma_f32_16x16x32_bf16 v[32:35], v[228:231], v[244:247], v[32:35]
	v_add_u32_e32 v173, 0x11000, v149
	v_add_u32_e32 v174, 0x11400, v149
	v_add_u32_e32 v175, 0x11800, v149
	v_add_u32_e32 v178, 0x11c00, v149
	v_add_u32_e32 v167, 0x10000, v147
	v_or_b32_e32 v168, 0x10000, v149
	s_waitcnt lgkmcnt(2)
; #define BIG_SYNC(N)                                              \
;   asm volatile("s_waitcnt vmcnt(%0)" ::"n"(N) : "memory");       \
;   __builtin_amdgcn_s_barrier();                                  \
;   asm volatile("" ::: "memory");                                 \
;   __builtin_amdgcn_sched_barrier(0);
; template <int NK, bool BNT = false> ...
;     ...
;   auto kstep = [&](int T, int cur, int nxt, bool do_stage) {
;     const unsigned char* sa = smem + cur * BIG_STAGE;
;     bf16x8 af[4], bfr[4];
; #pragma unroll
;     for (int m = 0; m < 4; ++m) af[m] = *reinterpret_cast<const bf16x8*>(sa + aoff + m * 1024);
; #pragma unroll
;     for (int n = 0; n < 4; ++n) bfr[n] = *reinterpret_cast<const bf16x8*>(sa + boff + n * 1024);
;     __builtin_amdgcn_sched_barrier(0);
;     if (do_stage) stage(T + 3, nxt);
; #pragma unroll
;     for (int m = 0; m < 4; ++m)
; #pragma unroll
;       for (int n = 0; n < 4; ++n) acc[m][n] = __builtin_amdgcn_mfma_f32_16x16x32_bf16(af[m], bfr[n], acc[m][n], 0, 0, 0);
;     if (do_stage) {
; #pragma unroll
;       for (int q = 0; q < NG; ++q) {
;         __builtin_amdgcn_sched_group_barrier(0x008, 3, 0);
;         __builtin_amdgcn_sched_group_barrier(0x010, 1, 0);
;       }
;       __builtin_amdgcn_sched_group_barrier(0x008, 16 - 3 * NG, 0);
;     }
;     __builtin_amdgcn_sched_barrier(0);
; #pragma unroll
;     for (int n = 0; n < 4; ++n) bfr[n] = *reinterpret_cast<const bf16x8*>(sa + boff + (4 + n) * 1024);
; #pragma unroll
;     for (int m = 0; m < 4; ++m)
; #pragma unroll
;       for (int n = 0; n < 4; ++n)
;         acc[m][4 + n] = __builtin_amdgcn_mfma_f32_16x16x32_bf16(af[m], bfr[n], acc[m][4 + n], 0, 0, 0);
;     __builtin_amdgcn_sched_barrier(0);
;   };
;     ...
;   stage(0, 0);
;   stage(1, 1);
;   stage(2, 2);
;   for (int it = 0; it < NK / 4 - 1; ++it) {
;     const int t = it * 4;
;     BIG_SYNC(2 * NG); kstep(t, 0, 3, true);
;     BIG_SYNC(2 * NG); kstep(t + 1, 1, 0, true);
;     BIG_SYNC(2 * NG); kstep(t + 2, 2, 1, true);
;     BIG_SYNC(2 * NG); kstep(t + 3, 3, 2, true);
	v_mfma_f32_16x16x32_bf16 v[92:95], v[216:219], v[232:235], v[92:95]
	ds_read_b128 v[244:247], v168 offset:7168
	v_mfma_f32_16x16x32_bf16 v[60:63], v[220:223], v[232:235], v[60:63]
	ds_read_b128 v[186:189], v167 offset:32768
	v_mfma_f32_16x16x32_bf16 v[28:31], v[224:227], v[232:235], v[28:31]
	ds_read_b128 v[190:193], v167 offset:33792
	v_mfma_f32_16x16x32_bf16 v[12:15], v[228:231], v[232:235], v[12:15]
	ds_read_b128 v[194:197], v167 offset:34816
	s_waitcnt lgkmcnt(5)
	v_mfma_f32_16x16x32_bf16 v[84:87], v[216:219], v[236:239], v[84:87]
	ds_read_b128 v[202:205], v167 offset:35840
	ds_read_b128 v[232:235], v168 offset:32768
	v_mfma_f32_16x16x32_bf16 v[56:59], v[220:223], v[236:239], v[56:59]
	v_mfma_f32_16x16x32_bf16 v[24:27], v[224:227], v[236:239], v[24:27]
	v_mfma_f32_16x16x32_bf16 v[8:11], v[228:231], v[236:239], v[8:11]
	s_waitcnt lgkmcnt(6)
	v_mfma_f32_16x16x32_bf16 v[80:83], v[216:219], v[240:243], v[80:83]
	ds_read_b128 v[236:239], v168 offset:33792
	v_mfma_f32_16x16x32_bf16 v[52:55], v[220:223], v[240:243], v[52:55]
	v_mfma_f32_16x16x32_bf16 v[20:23], v[224:227], v[240:243], v[20:23]
	v_mfma_f32_16x16x32_bf16 v[4:7], v[228:231], v[240:243], v[4:7]
	s_waitcnt lgkmcnt(6)
	v_mfma_f32_16x16x32_bf16 v[72:75], v[216:219], v[244:247], v[72:75]
	ds_read_b128 v[240:243], v168 offset:34816
	v_mfma_f32_16x16x32_bf16 v[48:51], v[220:223], v[244:247], v[48:51]
	v_mfma_f32_16x16x32_bf16 v[16:19], v[224:227], v[244:247], v[16:19]
	v_mfma_f32_16x16x32_bf16 v[0:3], v[228:231], v[244:247], v[0:3]
	ds_read_b128 v[244:247], v168 offset:35840
	v_add_u32_e32 v176, 0x18000, v147
	v_or_b32_e32 v179, 0x18000, v149
	v_add_u32_e32 v180, 0x18400, v149
	v_add_u32_e32 v181, 0x18800, v149
	v_add_u32_e32 v182, 0x18c00, v149
	v_readfirstlane_b32 s11, v159
	v_lshl_add_u64 v[248:249], v[144:145], 0, s[54:55]
	s_mov_b32 m0, s11
	v_readfirstlane_b32 s11, v160
	v_lshl_add_u64 v[144:145], v[144:145], 0, s[56:57]
	s_waitcnt lgkmcnt(3)
	v_mfma_f32_16x16x32_bf16 v[124:127], v[186:189], v[232:235], v[124:127]
	v_lshl_add_u64 v[250:251], v[142:143], 0, s[54:55]
	v_lshl_add_u64 v[142:143], v[142:143], 0, s[56:57]
	v_mfma_f32_16x16x32_bf16 v[108:111], v[190:193], v[232:235], v[108:111]
	v_mfma_f32_16x16x32_bf16 v[88:91], v[194:197], v[232:235], v[88:91]
	s_waitcnt vmcnt(4)
	s_barrier
	global_load_lds_dwordx4 v[248:249], off
	s_mov_b32 m0, s11
	v_readfirstlane_b32 s11, v161
	v_mfma_f32_16x16x32_bf16 v[44:47], v[202:205], v[232:235], v[44:47]
	s_waitcnt lgkmcnt(2)
	v_mfma_f32_16x16x32_bf16 v[120:123], v[186:189], v[236:239], v[120:123]
	ds_read_b128 v[232:235], v168 offset:36864
	v_mfma_f32_16x16x32_bf16 v[104:107], v[190:193], v[236:239], v[104:107]
	global_load_lds_dwordx4 v[144:145], off
	s_mov_b32 m0, s11
	v_readfirstlane_b32 s11, v162
	v_mfma_f32_16x16x32_bf16 v[76:79], v[194:197], v[236:239], v[76:79]
	v_mfma_f32_16x16x32_bf16 v[40:43], v[202:205], v[236:239], v[40:43]
	s_waitcnt lgkmcnt(2)
	v_mfma_f32_16x16x32_bf16 v[116:119], v[186:189], v[240:243], v[116:119]
	ds_read_b128 v[236:239], v168 offset:37888
	global_load_lds_dwordx4 v[250:251], off
	s_mov_b32 m0, s11
	v_mfma_f32_16x16x32_bf16 v[100:103], v[190:193], v[240:243], v[100:103]
	v_mfma_f32_16x16x32_bf16 v[68:71], v[194:197], v[240:243], v[68:71]
	v_mfma_f32_16x16x32_bf16 v[36:39], v[202:205], v[240:243], v[36:39]
	global_load_lds_dwordx4 v[142:143], off
	s_waitcnt lgkmcnt(2)
	v_mfma_f32_16x16x32_bf16 v[112:115], v[186:189], v[244:247], v[112:115]
	ds_read_b128 v[240:243], v168 offset:38912
	v_mfma_f32_16x16x32_bf16 v[96:99], v[190:193], v[244:247], v[96:99]
	v_mfma_f32_16x16x32_bf16 v[64:67], v[194:197], v[244:247], v[64:67]
	v_mfma_f32_16x16x32_bf16 v[32:35], v[202:205], v[244:247], v[32:35]
	v_add_u32_e32 v142, 0x19000, v149
	v_add_u32_e32 v143, 0x19400, v149
	v_add_u32_e32 v144, 0x19800, v149
	v_add_u32_e32 v145, 0x19c00, v149
	s_waitcnt lgkmcnt(2)
	v_mfma_f32_16x16x32_bf16 v[92:95], v[186:189], v[232:235], v[92:95]
	ds_read_b128 v[244:247], v168 offset:39936
	v_mfma_f32_16x16x32_bf16 v[60:63], v[190:193], v[232:235], v[60:63]
	ds_read_b128 v[216:219], v147
	v_mfma_f32_16x16x32_bf16 v[28:31], v[194:197], v[232:235], v[28:31]
	ds_read_b128 v[220:223], v147 offset:1024
	v_mfma_f32_16x16x32_bf16 v[12:15], v[202:205], v[232:235], v[12:15]
	ds_read_b128 v[224:227], v147 offset:2048
	s_waitcnt lgkmcnt(5)
	v_mfma_f32_16x16x32_bf16 v[84:87], v[186:189], v[236:239], v[84:87]
	ds_read_b128 v[228:231], v147 offset:3072
	ds_read_b128 v[232:235], v148 offset:16384
	v_mfma_f32_16x16x32_bf16 v[56:59], v[190:193], v[236:239], v[56:59]
	v_mfma_f32_16x16x32_bf16 v[24:27], v[194:197], v[236:239], v[24:27]
	v_mfma_f32_16x16x32_bf16 v[8:11], v[202:205], v[236:239], v[8:11]
	s_waitcnt lgkmcnt(6)
	v_mfma_f32_16x16x32_bf16 v[80:83], v[186:189], v[240:243], v[80:83]
	ds_read_b128 v[236:239], v148 offset:17408
	v_mfma_f32_16x16x32_bf16 v[52:55], v[190:193], v[240:243], v[52:55]
	v_mfma_f32_16x16x32_bf16 v[20:23], v[194:197], v[240:243], v[20:23]
	v_mfma_f32_16x16x32_bf16 v[4:7], v[202:205], v[240:243], v[4:7]
	s_waitcnt lgkmcnt(6)
	v_mfma_f32_16x16x32_bf16 v[72:75], v[186:189], v[244:247], v[72:75]
	ds_read_b128 v[240:243], v148 offset:18432
	v_mfma_f32_16x16x32_bf16 v[48:51], v[190:193], v[244:247], v[48:51]
	v_mfma_f32_16x16x32_bf16 v[16:19], v[194:197], v[244:247], v[16:19]
	v_mfma_f32_16x16x32_bf16 v[0:3], v[202:205], v[244:247], v[0:3]
	ds_read_b128 v[244:247], v148 offset:19456
	s_add_u32 s12, s12, 0x8000
	s_addc_u32 s13, s13, 0
	s_cmp_lg_u32 s12, 0x38000
	s_cbranch_scc1 .LBB0_290
; #define BIG_SYNC(N)                                              \
;   asm volatile("s_waitcnt vmcnt(%0)" ::"n"(N) : "memory");       \
;   __builtin_amdgcn_s_barrier();                                  \
;   asm volatile("" ::: "memory");                                 \
;   __builtin_amdgcn_sched_barrier(0);
; template <int NK, bool BNT = false> ...
;     ...
;   BIG_SYNC(2 * NG); kstep(NK - 4, 0, 3, true);
;   BIG_SYNC(2 * NG); kstep(NK - 3, 1, 0, false);
;   BIG_SYNC(NG);     kstep(NK - 2, 2, 0, false);
;   BIG_SYNC(0);      kstep(NK - 1, 3, 0, false);
	s_mov_b64 s[12:13], 0x3e000
	v_readfirstlane_b32 s11, v163
	v_lshl_add_u64 v[198:199], v[136:137], 0, s[12:13]
	v_lshl_add_u64 v[200:201], v[134:135], 0, s[12:13]
	s_mov_b32 m0, s11
	s_mov_b64 s[12:13], 0x7e000
	v_readfirstlane_b32 s11, v164
	v_lshl_add_u64 v[136:137], v[136:137], 0, s[12:13]
	s_waitcnt lgkmcnt(3)
	v_mfma_f32_16x16x32_bf16 v[124:127], v[216:219], v[232:235], v[124:127]
	v_lshl_add_u64 v[134:135], v[134:135], 0, s[12:13]
	v_mfma_f32_16x16x32_bf16 v[108:111], v[220:223], v[232:235], v[108:111]
	v_mfma_f32_16x16x32_bf16 v[88:91], v[224:227], v[232:235], v[88:91]
	s_waitcnt vmcnt(4)
	s_barrier
	global_load_lds_dwordx4 v[198:199], off
	s_mov_b32 m0, s11
	v_readfirstlane_b32 s11, v165
	v_mfma_f32_16x16x32_bf16 v[44:47], v[228:231], v[232:235], v[44:47]
	s_waitcnt lgkmcnt(2)
	v_mfma_f32_16x16x32_bf16 v[120:123], v[216:219], v[236:239], v[120:123]
	ds_read_b128 v[232:235], v148 offset:20480
	v_mfma_f32_16x16x32_bf16 v[104:107], v[220:223], v[236:239], v[104:107]
	global_load_lds_dwordx4 v[136:137], off
	s_mov_b32 m0, s11
	v_readfirstlane_b32 s11, v166
	v_mfma_f32_16x16x32_bf16 v[76:79], v[224:227], v[236:239], v[76:79]
	v_mfma_f32_16x16x32_bf16 v[40:43], v[228:231], v[236:239], v[40:43]
	s_waitcnt lgkmcnt(2)
	v_mfma_f32_16x16x32_bf16 v[116:119], v[216:219], v[240:243], v[116:119]
	ds_read_b128 v[236:239], v148 offset:21504
	global_load_lds_dwordx4 v[200:201], off
	s_mov_b32 m0, s11
	v_mfma_f32_16x16x32_bf16 v[100:103], v[220:223], v[240:243], v[100:103]
	v_mfma_f32_16x16x32_bf16 v[68:71], v[224:227], v[240:243], v[68:71]
	v_mfma_f32_16x16x32_bf16 v[36:39], v[228:231], v[240:243], v[36:39]
	global_load_lds_dwordx4 v[134:135], off
	s_waitcnt lgkmcnt(2)
	v_mfma_f32_16x16x32_bf16 v[112:115], v[216:219], v[244:247], v[112:115]
	ds_read_b128 v[240:243], v148 offset:22528
	v_mfma_f32_16x16x32_bf16 v[96:99], v[220:223], v[244:247], v[96:99]
	v_mfma_f32_16x16x32_bf16 v[64:67], v[224:227], v[244:247], v[64:67]
	v_mfma_f32_16x16x32_bf16 v[32:35], v[228:231], v[244:247], v[32:35]
	s_waitcnt lgkmcnt(2)
	v_mfma_f32_16x16x32_bf16 v[92:95], v[216:219], v[232:235], v[92:95]
	ds_read_b128 v[244:247], v148 offset:23552
	v_mfma_f32_16x16x32_bf16 v[60:63], v[220:223], v[232:235], v[60:63]
	ds_read_b128 v[186:189], v147 offset:32768
	v_mfma_f32_16x16x32_bf16 v[28:31], v[224:227], v[232:235], v[28:31]
	ds_read_b128 v[190:193], v147 offset:33792
	v_mfma_f32_16x16x32_bf16 v[12:15], v[228:231], v[232:235], v[12:15]
	ds_read_b128 v[194:197], v147 offset:34816
	s_waitcnt lgkmcnt(5)
	v_mfma_f32_16x16x32_bf16 v[84:87], v[216:219], v[236:239], v[84:87]
	ds_read_b128 v[202:205], v147 offset:35840
	ds_read_b128 v[232:235], v148 offset:49152
	v_mfma_f32_16x16x32_bf16 v[56:59], v[220:223], v[236:239], v[56:59]
	v_mfma_f32_16x16x32_bf16 v[24:27], v[224:227], v[236:239], v[24:27]
	v_mfma_f32_16x16x32_bf16 v[8:11], v[228:231], v[236:239], v[8:11]
	s_waitcnt lgkmcnt(6)
	v_mfma_f32_16x16x32_bf16 v[80:83], v[216:219], v[240:243], v[80:83]
	ds_read_b128 v[236:239], v148 offset:50176
	v_mfma_f32_16x16x32_bf16 v[52:55], v[220:223], v[240:243], v[52:55]
	v_mfma_f32_16x16x32_bf16 v[20:23], v[224:227], v[240:243], v[20:23]
	v_mfma_f32_16x16x32_bf16 v[4:7], v[228:231], v[240:243], v[4:7]
	s_waitcnt lgkmcnt(6)
	v_mfma_f32_16x16x32_bf16 v[72:75], v[216:219], v[244:247], v[72:75]
	ds_read_b128 v[240:243], v148 offset:51200
	v_mfma_f32_16x16x32_bf16 v[48:51], v[220:223], v[244:247], v[48:51]
	v_mfma_f32_16x16x32_bf16 v[16:19], v[224:227], v[244:247], v[16:19]
	v_mfma_f32_16x16x32_bf16 v[0:3], v[228:231], v[244:247], v[0:3]
	ds_read_b128 v[244:247], v148 offset:52224
	s_waitcnt lgkmcnt(3)
	v_mfma_f32_16x16x32_bf16 v[124:127], v[186:189], v[232:235], v[124:127]
	v_mfma_f32_16x16x32_bf16 v[108:111], v[190:193], v[232:235], v[108:111]
	v_mfma_f32_16x16x32_bf16 v[88:91], v[194:197], v[232:235], v[88:91]
	v_mfma_f32_16x16x32_bf16 v[44:47], v[202:205], v[232:235], v[44:47]
	s_waitcnt vmcnt(4)
	s_barrier
	s_waitcnt lgkmcnt(2)
	v_mfma_f32_16x16x32_bf16 v[120:123], v[186:189], v[236:239], v[120:123]
	ds_read_b128 v[232:235], v148 offset:53248
	v_mfma_f32_16x16x32_bf16 v[104:107], v[190:193], v[236:239], v[104:107]
	v_mfma_f32_16x16x32_bf16 v[76:79], v[194:197], v[236:239], v[76:79]
	v_mfma_f32_16x16x32_bf16 v[40:43], v[202:205], v[236:239], v[40:43]
	s_waitcnt lgkmcnt(2)
	v_mfma_f32_16x16x32_bf16 v[116:119], v[186:189], v[240:243], v[116:119]
	ds_read_b128 v[236:239], v148 offset:54272
	v_mfma_f32_16x16x32_bf16 v[100:103], v[190:193], v[240:243], v[100:103]
	v_mfma_f32_16x16x32_bf16 v[68:71], v[194:197], v[240:243], v[68:71]
	v_mfma_f32_16x16x32_bf16 v[36:39], v[202:205], v[240:243], v[36:39]
	s_waitcnt lgkmcnt(2)
	v_mfma_f32_16x16x32_bf16 v[112:115], v[186:189], v[244:247], v[112:115]
	ds_read_b128 v[240:243], v148 offset:55296
	v_mfma_f32_16x16x32_bf16 v[96:99], v[190:193], v[244:247], v[96:99]
	v_mfma_f32_16x16x32_bf16 v[64:67], v[194:197], v[244:247], v[64:67]
	v_mfma_f32_16x16x32_bf16 v[32:35], v[202:205], v[244:247], v[32:35]
	s_waitcnt lgkmcnt(2)
	v_mfma_f32_16x16x32_bf16 v[92:95], v[186:189], v[232:235], v[92:95]
	ds_read_b128 v[244:247], v148 offset:56320
	v_mfma_f32_16x16x32_bf16 v[60:63], v[190:193], v[232:235], v[60:63]
	v_mfma_f32_16x16x32_bf16 v[28:31], v[194:197], v[232:235], v[28:31]
	v_mfma_f32_16x16x32_bf16 v[12:15], v[202:205], v[232:235], v[12:15]
	s_waitcnt lgkmcnt(2)
	v_mfma_f32_16x16x32_bf16 v[84:87], v[186:189], v[236:239], v[84:87]
	v_mfma_f32_16x16x32_bf16 v[56:59], v[190:193], v[236:239], v[56:59]
	v_mfma_f32_16x16x32_bf16 v[24:27], v[194:197], v[236:239], v[24:27]
	v_mfma_f32_16x16x32_bf16 v[8:11], v[202:205], v[236:239], v[8:11]
	s_waitcnt lgkmcnt(1)
	v_mfma_f32_16x16x32_bf16 v[80:83], v[186:189], v[240:243], v[80:83]
	v_mfma_f32_16x16x32_bf16 v[52:55], v[190:193], v[240:243], v[52:55]
	v_mfma_f32_16x16x32_bf16 v[20:23], v[194:197], v[240:243], v[20:23]
	v_mfma_f32_16x16x32_bf16 v[4:7], v[202:205], v[240:243], v[4:7]
	s_waitcnt lgkmcnt(0)
	v_mfma_f32_16x16x32_bf16 v[72:75], v[186:189], v[244:247], v[72:75]
	v_mfma_f32_16x16x32_bf16 v[48:51], v[190:193], v[244:247], v[48:51]
	v_mfma_f32_16x16x32_bf16 v[16:19], v[194:197], v[244:247], v[16:19]
	v_mfma_f32_16x16x32_bf16 v[0:3], v[202:205], v[244:247], v[0:3]
	v_mov_b32_e32 v186, 0xf149f2ca
	v_mov_b32_e32 v187, 0x3c0881c4
	v_mov_b32_e32 v188, 0xbab64f3b
	v_mov_b32_e32 v189, 0x24800
	v_mov_b32_e32 v190, 1
	v_mov_b32_e32 v191, 0x24804
	v_mov_b32_e32 v192, 0xfcf
	v_mov_b32_e32 v193, 0x7cf
	v_mov_b32_e32 v194, 0xfdf
	v_mov_b32_e32 v195, 0x7df
	v_mov_b32_e32 v196, 0xfef
	v_mov_b32_e32 v197, 0x7ef
	v_mov_b32_e32 v198, 0xfff
	v_mov_b32_e32 v199, 0x7ff
	v_mov_b32_e32 v200, 0x20000
	v_mov_b32_e32 v201, 0xf8f
	v_mov_b32_e32 v202, 0x78f
	v_mov_b32_e32 v203, 0xf9f
	v_mov_b32_e32 v204, 0x79f
	v_mov_b32_e32 v205, 0xfaf
	s_waitcnt vmcnt(4)
	s_barrier
; __device__ __forceinline__ int widen_off(int fq) { return ((fq & 1) << 4) + ((fq >> 1) << 3); }
; #define BIG_SYNC(N)                                              \
;   asm volatile("s_waitcnt vmcnt(%0)" ::"n"(N) : "memory");       \
;   __builtin_amdgcn_s_barrier();                                  \
;   asm volatile("" ::: "memory");                                 \
;   __builtin_amdgcn_sched_barrier(0);
; template <int NK, bool BNT = false> ...
;     ...
; #pragma unroll
;     for (int n = 0; n < 4; ++n) bfr[n] = *reinterpret_cast<const bf16x8*>(sa + boff + (4 + n) * 1024);
; #pragma unroll
;     for (int m = 0; m < 4; ++m)
; #pragma unroll
;       for (int n = 0; n < 4; ++n)
;         acc[m][4 + n] = __builtin_amdgcn_mfma_f32_16x16x32_bf16(af[m], bfr[n], acc[m][4 + n], 0, 0, 0);
;     __builtin_amdgcn_sched_barrier(0);
;   };
;     ...
;   stage(0, 0);
;   stage(1, 1);
;   stage(2, 2);
;   for (int it = 0; it < NK / 4 - 1; ++it) {
;     const int t = it * 4;
;     BIG_SYNC(2 * NG); kstep(t, 0, 3, true);
;     BIG_SYNC(2 * NG); kstep(t + 1, 1, 0, true);
;     BIG_SYNC(2 * NG); kstep(t + 2, 2, 1, true);
;     BIG_SYNC(2 * NG); kstep(t + 3, 3, 2, true);
;   }
;   BIG_SYNC(2 * NG); kstep(NK - 4, 0, 3, true);
;   BIG_SYNC(2 * NG); kstep(NK - 3, 1, 0, false);
;   BIG_SYNC(NG);     kstep(NK - 2, 2, 0, false);
;   BIG_SYNC(0);      kstep(NK - 1, 3, 0, false);
; template <int MODE, int NSUB>
; __device__ __forceinline__ void epilogue(const Params& p, int layer, f32x4 (&acc)[4][NSUB], int tm, int tn, int g,
;                                          const float* s_rstd, const int tid_in) {
;     ...
;   } else if constexpr (MODE == EPI_UP) {
;     const int woff = widen_off(fq);
; #pragma unroll
;     for (int n = 0; n < NSUB; ++n) {
;       const int nl = wc * (NSUB * 16) + n * 16 + fr;
;       const int t = tn * (NSUB * 32) + nl;
;       const float rs = s_rstd[nl];
; #pragma unroll
	ds_read_b128 v[134:137], v167
	ds_read_b128 v[138:141], v167 offset:1024
	ds_read_b128 v[154:157], v167 offset:2048
	ds_read_b128 v[158:161], v167 offset:3072
	ds_read_b128 v[162:165], v168
	ds_read_b128 v[166:169], v169
	ds_read_b128 v[216:219], v170
	ds_read_b128 v[220:223], v172
	s_waitcnt lgkmcnt(0)
	v_mfma_f32_16x16x32_bf16 v[124:127], v[134:137], v[162:165], v[124:127]
	v_mfma_f32_16x16x32_bf16 v[120:123], v[134:137], v[166:169], v[120:123]
	v_mfma_f32_16x16x32_bf16 v[116:119], v[134:137], v[216:219], v[116:119]
	v_mfma_f32_16x16x32_bf16 v[112:115], v[134:137], v[220:223], v[112:115]
	v_mfma_f32_16x16x32_bf16 v[224:227], v[138:141], v[162:165], v[108:111]
	v_mfma_f32_16x16x32_bf16 v[104:107], v[138:141], v[166:169], v[104:107]
	v_mfma_f32_16x16x32_bf16 v[100:103], v[138:141], v[216:219], v[100:103]
	v_mfma_f32_16x16x32_bf16 v[96:99], v[138:141], v[220:223], v[96:99]
	v_mfma_f32_16x16x32_bf16 v[228:231], v[154:157], v[162:165], v[88:91]
	v_mfma_f32_16x16x32_bf16 v[232:235], v[154:157], v[166:169], v[76:79]
	v_mfma_f32_16x16x32_bf16 v[68:71], v[154:157], v[216:219], v[68:71]
	v_mfma_f32_16x16x32_bf16 v[64:67], v[154:157], v[220:223], v[64:67]
	v_mfma_f32_16x16x32_bf16 v[44:47], v[158:161], v[162:165], v[44:47]
	v_mfma_f32_16x16x32_bf16 v[40:43], v[158:161], v[166:169], v[40:43]
	v_mfma_f32_16x16x32_bf16 v[36:39], v[158:161], v[216:219], v[36:39]
	v_mfma_f32_16x16x32_bf16 v[32:35], v[158:161], v[220:223], v[32:35]
	ds_read_b128 v[76:79], v173
	ds_read_b128 v[88:91], v174
	s_waitcnt lgkmcnt(0)
	v_mfma_f32_16x16x32_bf16 v[162:165], v[134:137], v[76:79], v[92:95]
	s_nop 2
	ds_read_b128 v[92:95], v178
	v_mfma_f32_16x16x32_bf16 v[166:169], v[134:137], v[88:91], v[84:87]
	s_nop 2
	ds_read_b128 v[84:87], v175
	s_waitcnt lgkmcnt(0)
	v_mfma_f32_16x16x32_bf16 v[172:175], v[134:137], v[84:87], v[80:83]
	v_mfma_f32_16x16x32_bf16 v[134:137], v[134:137], v[92:95], v[72:75]
	v_mfma_f32_16x16x32_bf16 v[216:219], v[138:141], v[76:79], v[60:63]
	v_mfma_f32_16x16x32_bf16 v[220:223], v[138:141], v[88:91], v[56:59]
	v_mfma_f32_16x16x32_bf16 v[52:55], v[138:141], v[84:87], v[52:55]
	v_mfma_f32_16x16x32_bf16 v[48:51], v[138:141], v[92:95], v[48:51]
	v_mfma_f32_16x16x32_bf16 v[138:141], v[154:157], v[76:79], v[28:31]
	v_mfma_f32_16x16x32_bf16 v[236:239], v[154:157], v[88:91], v[24:27]
	v_mfma_f32_16x16x32_bf16 v[20:23], v[154:157], v[84:87], v[20:23]
	v_mfma_f32_16x16x32_bf16 v[16:19], v[154:157], v[92:95], v[16:19]
	v_mfma_f32_16x16x32_bf16 v[154:157], v[158:161], v[76:79], v[12:15]
	v_mfma_f32_16x16x32_bf16 v[240:243], v[158:161], v[88:91], v[8:11]
	v_mfma_f32_16x16x32_bf16 v[244:247], v[158:161], v[84:87], v[4:7]
	v_mfma_f32_16x16x32_bf16 v[0:3], v[158:161], v[92:95], v[0:3]
	s_waitcnt vmcnt(0)
	s_barrier
	s_nop 0
	ds_read_b128 v[4:7], v176
	ds_read_b128 v[8:11], v176 offset:1024
	ds_read_b128 v[158:161], v176 offset:2048
	ds_read_b128 v[248:251], v176 offset:3072
	ds_read_b128 v[12:15], v179
	ds_read_b128 v[24:27], v180
	ds_read_b128 v[28:31], v181
	ds_read_b128 v[56:59], v182
	s_waitcnt lgkmcnt(0)
	v_mfma_f32_16x16x32_bf16 v[124:127], v[4:7], v[12:15], v[124:127]
	v_mfma_f32_16x16x32_bf16 v[108:111], v[4:7], v[24:27], v[120:123]
	v_mfma_f32_16x16x32_bf16 v[92:95], v[4:7], v[28:31], v[116:119]
	v_mfma_f32_16x16x32_bf16 v[76:79], v[4:7], v[56:59], v[112:115]
	v_mfma_f32_16x16x32_bf16 v[112:115], v[8:11], v[12:15], v[224:227]
	v_mfma_f32_16x16x32_bf16 v[104:107], v[8:11], v[24:27], v[104:107]
	v_mfma_f32_16x16x32_bf16 v[88:91], v[8:11], v[28:31], v[100:103]
	v_mfma_f32_16x16x32_bf16 v[72:75], v[8:11], v[56:59], v[96:99]
	v_mfma_f32_16x16x32_bf16 v[120:123], v[158:161], v[12:15], v[228:231]
	v_mfma_f32_16x16x32_bf16 v[100:103], v[158:161], v[24:27], v[232:235]
	v_mfma_f32_16x16x32_bf16 v[84:87], v[158:161], v[28:31], v[68:71]
	v_mfma_f32_16x16x32_bf16 v[68:71], v[158:161], v[56:59], v[64:67]
	v_mfma_f32_16x16x32_bf16 v[178:181], v[248:251], v[12:15], v[44:47]
	v_mfma_f32_16x16x32_bf16 v[96:99], v[248:251], v[24:27], v[40:43]
	v_mfma_f32_16x16x32_bf16 v[80:83], v[248:251], v[28:31], v[36:39]
	v_mfma_f32_16x16x32_bf16 v[64:67], v[248:251], v[56:59], v[32:35]
	s_nop 2
	ds_read_b128 v[32:35], v142
	ds_read_b128 v[116:119], v143
	s_waitcnt lgkmcnt(0)
	v_mfma_f32_16x16x32_bf16 v[60:63], v[4:7], v[32:35], v[162:165]
	s_nop 2
	ds_read_b128 v[162:165], v144
	ds_read_b128 v[142:145], v145
	v_mfma_f32_16x16x32_bf16 v[44:47], v[4:7], v[116:119], v[166:169]
	s_waitcnt lgkmcnt(0)
	v_mfma_f32_16x16x32_bf16 v[28:31], v[4:7], v[162:165], v[172:175]
	v_mfma_f32_16x16x32_bf16 v[12:15], v[4:7], v[142:145], v[134:137]
	v_mfma_f32_16x16x32_bf16 v[56:59], v[8:11], v[32:35], v[216:219]
	v_mfma_f32_16x16x32_bf16 v[40:43], v[8:11], v[116:119], v[220:223]
	v_mfma_f32_16x16x32_bf16 v[24:27], v[8:11], v[162:165], v[52:55]
	v_mfma_f32_16x16x32_bf16 v[8:11], v[8:11], v[142:145], v[48:51]
	v_mfma_f32_16x16x32_bf16 v[52:55], v[158:161], v[32:35], v[138:141]
	v_mfma_f32_16x16x32_bf16 v[36:39], v[158:161], v[116:119], v[236:239]
	v_mfma_f32_16x16x32_bf16 v[20:23], v[158:161], v[162:165], v[20:23]
	v_mfma_f32_16x16x32_bf16 v[4:7], v[158:161], v[142:145], v[16:19]
	v_mfma_f32_16x16x32_bf16 v[48:51], v[248:251], v[32:35], v[154:157]
	v_mfma_f32_16x16x32_bf16 v[32:35], v[248:251], v[116:119], v[240:243]
	v_mfma_f32_16x16x32_bf16 v[16:19], v[248:251], v[162:165], v[244:247]
	v_mfma_f32_16x16x32_bf16 v[0:3], v[248:251], v[142:145], v[0:3]
	v_mov_b32_e32 v116, v215
	s_lshl_b32 s10, s10, 8
	v_and_b32_e32 v117, 16, v116
	v_lshrrev_b32_e32 v118, 2, v116
	v_and_or_b32 v136, v118, 8, v117
	v_lshlrev_b32_e32 v117, 1, v116
	v_and_b32_e32 v119, 15, v116
	v_and_b32_e32 v117, 0x80, v117
	v_lshl_or_b32 v134, s15, 8, v117
	v_or_b32_e32 v117, v117, v119
	v_ashrrev_i32_e32 v116, 1, v116
	v_lshlrev_b32_e32 v118, 2, v117
	v_and_b32_e32 v116, 0xffffffc0, v116
	v_add3_u32 v135, s10, v150, v116
	v_or_b32_e32 v116, 0x20000, v118
	ds_read_b32 v137, v116
	v_lshlrev_b32_e32 v152, 6, v119
	v_or_b32_e32 v119, 0x20040, v118
	v_readlane_b32 s64, v252, 4
	ds_read_b32 v119, v119
	s_waitcnt lgkmcnt(0)
; template <int MODE, int NSUB>
; __device__ __forceinline__ void epilogue(const Params& p, int layer, f32x4 (&acc)[4][NSUB], int tm, int tn, int g,
;                                          const float* s_rstd, const int tid_in) {
;     ...
;       for (int mp = 0; mp < 2; ++mp) {
;         bf16x4 pk[2];
; #pragma unroll
;         for (int h2 = 0; h2 < 2; ++h2) {
;           const int m = mp * 2 + h2;
;           float v[4];
; #pragma unroll
;           for (int j = 0; j < 4; ++j) {
;             float a = fmaxf(acc[m][n][j] * rs, 0.f);
;             v[j] = a * a;
;           }
;           pk[h2] = pack4(v[0], v[1], v[2], v[3]);
;         }
;         const int f = tm * 128 + wr * 64 + mp * 32 + woff;
;         __builtin_nontemporal_store(widen_pair(pk[0], pk[1]), reinterpret_cast<u32x4*>(p.hm + blk(t, f, 128)));
;       }
	v_mul_f32_e32 v116, v124, v137
	v_mul_f32_e32 v117, v125, v137
	v_mul_f32_e32 v124, v126, v137
	v_mul_f32_e32 v125, v127, v137
	v_mul_f32_e32 v112, v112, v137
	v_mul_f32_e32 v113, v113, v137
	v_max_f32_e32 v124, 0, v124
	v_max_f32_e32 v125, 0, v125
	v_max_f32_e32 v112, 0, v112
	v_max_f32_e32 v113, 0, v113
	v_mul_f32_e32 v114, v114, v137
	v_mul_f32_e32 v115, v115, v137
	v_pk_mul_f32 v[126:127], v[124:125], v[124:125]
	v_pk_mul_f32 v[112:113], v[112:113], v[112:113]
	v_max_f32_e32 v114, 0, v114
	v_max_f32_e32 v115, 0, v115
	v_cvt_pk_bf16_f32 v125, v126, v127
	v_pk_mul_f32 v[114:115], v[114:115], v[114:115]
	v_cvt_pk_bf16_f32 v126, v112, v113
	v_ashrrev_i32_e32 v112, 5, v135
	v_cvt_pk_bf16_f32 v127, v114, v115
	v_add_u32_e32 v114, v112, v134
	v_ashrrev_i32_e32 v115, 31, v114
	v_lshlrev_b64 v[112:113], 13, v[114:115]
	v_mul_f32_e32 v115, v120, v137
	v_max_f32_e32 v120, 0, v115
	v_mul_f32_e32 v115, v121, v137
	v_max_f32_e32 v121, 0, v115
	v_mul_f32_e32 v115, v122, v137
	v_max_f32_e32 v116, 0, v116
	v_max_f32_e32 v117, 0, v117
	v_max_f32_e32 v122, 0, v115
	v_mul_f32_e32 v115, v123, v137
	v_pk_mul_f32 v[116:117], v[116:117], v[116:117]
	v_readlane_b32 s78, v252, 18
	v_readlane_b32 s79, v252, 19
	v_max_f32_e32 v123, 0, v115
	v_cvt_pk_bf16_f32 v124, v116, v117
	v_lshl_add_u64 v[116:117], s[78:79], 0, v[112:113]
	v_pk_mul_f32 v[120:121], v[120:121], v[120:121]
	v_pk_mul_f32 v[122:123], v[122:123], v[122:123]
	v_mul_f32_e32 v115, v178, v137
	v_lshl_add_u64 v[134:135], v[116:117], 0, v[152:153]
	v_lshlrev_b32_e32 v112, 1, v136
	v_mov_b32_e32 v113, v153
	v_cvt_pk_bf16_f32 v120, v120, v121
	v_cvt_pk_bf16_f32 v121, v122, v123
	v_max_f32_e32 v122, 0, v115
	v_mul_f32_e32 v115, v179, v137
	v_permlane16_swap_b32_e32 v124, v126
	v_permlane16_swap_b32_e32 v125, v127
	v_lshl_add_u64 v[134:135], v[134:135], 0, v[112:113]
	v_max_f32_e32 v123, 0, v115
	v_mul_f32_e32 v115, v180, v137
	global_store_dwordx4 v[134:135], v[124:127], off nt
	v_add_u32_e32 v114, 1, v114
	v_mul_f32_e32 v108, v108, v119
	v_max_f32_e32 v124, 0, v115
	v_mul_f32_e32 v115, v181, v137
	v_mul_f32_e32 v109, v109, v119
	v_mul_f32_e32 v110, v110, v119
	v_mul_f32_e32 v111, v111, v119
	v_mul_f32_e32 v104, v104, v119
	v_mul_f32_e32 v105, v105, v119
	v_max_f32_e32 v125, 0, v115
	v_ashrrev_i32_e32 v115, 31, v114
	v_max_f32_e32 v108, 0, v108
	v_max_f32_e32 v109, 0, v109
	v_max_f32_e32 v110, 0, v110
	v_max_f32_e32 v111, 0, v111
	v_max_f32_e32 v104, 0, v104
	v_max_f32_e32 v105, 0, v105
	v_mul_f32_e32 v100, v100, v119
	v_mul_f32_e32 v101, v101, v119
	v_mul_f32_e32 v102, v102, v119
	v_mul_f32_e32 v103, v103, v119
	v_mul_f32_e32 v96, v96, v119
	v_mul_f32_e32 v97, v97, v119
	v_mul_f32_e32 v98, v98, v119
	v_mul_f32_e32 v99, v99, v119
	v_lshlrev_b64 v[114:115], 13, v[114:115]
	v_pk_mul_f32 v[108:109], v[108:109], v[108:109]
	v_pk_mul_f32 v[110:111], v[110:111], v[110:111]
	v_pk_mul_f32 v[104:105], v[104:105], v[104:105]
	v_max_f32_e32 v100, 0, v100
	v_max_f32_e32 v101, 0, v101
	v_max_f32_e32 v102, 0, v102
	v_max_f32_e32 v103, 0, v103
	v_max_f32_e32 v96, 0, v96
	v_max_f32_e32 v97, 0, v97
	v_max_f32_e32 v98, 0, v98
	v_max_f32_e32 v99, 0, v99
	v_lshl_add_u64 v[114:115], s[78:79], 0, v[114:115]
	v_cvt_pk_bf16_f32 v108, v108, v109
	v_cvt_pk_bf16_f32 v109, v110, v111
	v_cvt_pk_bf16_f32 v110, v104, v105
	v_or_b32_e32 v104, 0x400, v152
	v_mov_b32_e32 v105, v153
	v_pk_mul_f32 v[100:101], v[100:101], v[100:101]
	v_pk_mul_f32 v[102:103], v[102:103], v[102:103]
	v_pk_mul_f32 v[96:97], v[96:97], v[96:97]
	v_pk_mul_f32 v[98:99], v[98:99], v[98:99]
	v_cvt_pk_bf16_f32 v100, v100, v101
	v_cvt_pk_bf16_f32 v101, v102, v103
	v_cvt_pk_bf16_f32 v102, v96, v97
	v_cvt_pk_bf16_f32 v103, v98, v99
	v_lshl_add_u64 v[96:97], v[114:115], 0, v[104:105]
	v_permlane16_swap_b32_e32 v100, v102
	v_permlane16_swap_b32_e32 v101, v103
	v_lshl_add_u64 v[96:97], v[96:97], 0, v[112:113]
	global_store_dwordx4 v[96:97], v[100:103], off nt
	v_or_b32_e32 v96, 0x20080, v118
	ds_read_b32 v96, v96
	v_mul_f32_e32 v106, v106, v119
	v_mul_f32_e32 v107, v107, v119
	v_pk_mul_f32 v[122:123], v[122:123], v[122:123]
	v_pk_mul_f32 v[124:125], v[124:125], v[124:125]
	s_waitcnt lgkmcnt(0)
	v_mul_f32_e32 v92, v92, v96
	v_mul_f32_e32 v93, v93, v96
	v_mul_f32_e32 v94, v94, v96
	v_mul_f32_e32 v95, v95, v96
	v_mul_f32_e32 v88, v88, v96
	v_mul_f32_e32 v89, v89, v96
	v_max_f32_e32 v92, 0, v92
	v_max_f32_e32 v93, 0, v93
	v_max_f32_e32 v94, 0, v94
	v_max_f32_e32 v95, 0, v95
	v_max_f32_e32 v88, 0, v88
	v_max_f32_e32 v89, 0, v89
	v_mul_f32_e32 v84, v84, v96
	v_mul_f32_e32 v85, v85, v96
	v_mul_f32_e32 v86, v86, v96
	v_mul_f32_e32 v87, v87, v96
	v_mul_f32_e32 v80, v80, v96
	v_mul_f32_e32 v81, v81, v96
	v_mul_f32_e32 v82, v82, v96
	v_mul_f32_e32 v83, v83, v96
	v_pk_mul_f32 v[92:93], v[92:93], v[92:93]
	v_pk_mul_f32 v[94:95], v[94:95], v[94:95]
	v_pk_mul_f32 v[88:89], v[88:89], v[88:89]
	v_max_f32_e32 v84, 0, v84
	v_max_f32_e32 v85, 0, v85
	v_max_f32_e32 v86, 0, v86
	v_max_f32_e32 v87, 0, v87
	v_max_f32_e32 v80, 0, v80
	v_max_f32_e32 v81, 0, v81
	v_max_f32_e32 v82, 0, v82
	v_max_f32_e32 v83, 0, v83
	v_cvt_pk_bf16_f32 v92, v92, v93
	v_cvt_pk_bf16_f32 v93, v94, v95
	v_cvt_pk_bf16_f32 v94, v88, v89
	v_or_b32_e32 v88, 0x800, v152
	v_mov_b32_e32 v89, v153
	v_pk_mul_f32 v[84:85], v[84:85], v[84:85]
	v_pk_mul_f32 v[86:87], v[86:87], v[86:87]
	v_pk_mul_f32 v[80:81], v[80:81], v[80:81]
	v_pk_mul_f32 v[82:83], v[82:83], v[82:83]
	v_cvt_pk_bf16_f32 v84, v84, v85
	v_cvt_pk_bf16_f32 v85, v86, v87
	v_cvt_pk_bf16_f32 v86, v80, v81
	v_cvt_pk_bf16_f32 v87, v82, v83
	v_lshl_add_u64 v[80:81], v[114:115], 0, v[88:89]
	v_permlane16_swap_b32_e32 v84, v86
	v_permlane16_swap_b32_e32 v85, v87
	v_lshl_add_u64 v[80:81], v[80:81], 0, v[112:113]
	global_store_dwordx4 v[80:81], v[84:87], off nt
	v_or_b32_e32 v80, 0x200c0, v118
	ds_read_b32 v80, v80
	v_mul_f32_e32 v90, v90, v96
	v_mul_f32_e32 v91, v91, v96
	v_max_f32_e32 v106, 0, v106
	v_max_f32_e32 v107, 0, v107
	s_waitcnt lgkmcnt(0)
; template <int MODE, int NSUB>
; __device__ __forceinline__ void epilogue(const Params& p, int layer, f32x4 (&acc)[4][NSUB], int tm, int tn, int g,
;                                          const float* s_rstd, const int tid_in) {
;     ...
;       for (int mp = 0; mp < 2; ++mp) {
;         bf16x4 pk[2];
; #pragma unroll
;         for (int h2 = 0; h2 < 2; ++h2) {
;           const int m = mp * 2 + h2;
;           float v[4];
; #pragma unroll
;           for (int j = 0; j < 4; ++j) {
;             float a = fmaxf(acc[m][n][j] * rs, 0.f);
;             v[j] = a * a;
;           }
;           pk[h2] = pack4(v[0], v[1], v[2], v[3]);
;         }
;         const int f = tm * 128 + wr * 64 + mp * 32 + woff;
;         __builtin_nontemporal_store(widen_pair(pk[0], pk[1]), reinterpret_cast<u32x4*>(p.hm + blk(t, f, 128)));
;       }
	v_mul_f32_e32 v76, v76, v80
	v_mul_f32_e32 v77, v77, v80
	v_mul_f32_e32 v78, v78, v80
	v_mul_f32_e32 v79, v79, v80
	v_mul_f32_e32 v72, v72, v80
	v_mul_f32_e32 v73, v73, v80
	v_max_f32_e32 v76, 0, v76
	v_max_f32_e32 v77, 0, v77
	v_max_f32_e32 v78, 0, v78
	v_max_f32_e32 v79, 0, v79
	v_max_f32_e32 v72, 0, v72
	v_max_f32_e32 v73, 0, v73
	v_mul_f32_e32 v68, v68, v80
	v_mul_f32_e32 v69, v69, v80
	v_mul_f32_e32 v70, v70, v80
	v_mul_f32_e32 v71, v71, v80
	v_mul_f32_e32 v64, v64, v80
	v_mul_f32_e32 v65, v65, v80
	v_mul_f32_e32 v66, v66, v80
	v_mul_f32_e32 v67, v67, v80
	v_pk_mul_f32 v[76:77], v[76:77], v[76:77]
	v_pk_mul_f32 v[78:79], v[78:79], v[78:79]
	v_pk_mul_f32 v[72:73], v[72:73], v[72:73]
	v_max_f32_e32 v68, 0, v68
	v_max_f32_e32 v69, 0, v69
	v_max_f32_e32 v70, 0, v70
	v_max_f32_e32 v71, 0, v71
	v_max_f32_e32 v64, 0, v64
	v_max_f32_e32 v65, 0, v65
	v_max_f32_e32 v66, 0, v66
	v_max_f32_e32 v67, 0, v67
	v_cvt_pk_bf16_f32 v76, v76, v77
	v_cvt_pk_bf16_f32 v77, v78, v79
	v_cvt_pk_bf16_f32 v78, v72, v73
	v_or_b32_e32 v72, 0xc00, v152
	v_mov_b32_e32 v73, v153
	v_pk_mul_f32 v[68:69], v[68:69], v[68:69]
	v_pk_mul_f32 v[70:71], v[70:71], v[70:71]
	v_pk_mul_f32 v[64:65], v[64:65], v[64:65]
	v_pk_mul_f32 v[66:67], v[66:67], v[66:67]
	v_cvt_pk_bf16_f32 v68, v68, v69
	v_cvt_pk_bf16_f32 v69, v70, v71
	v_cvt_pk_bf16_f32 v70, v64, v65
	v_cvt_pk_bf16_f32 v71, v66, v67
	v_lshl_add_u64 v[64:65], v[114:115], 0, v[72:73]
	v_permlane16_swap_b32_e32 v68, v70
	v_permlane16_swap_b32_e32 v69, v71
	v_lshl_add_u64 v[64:65], v[64:65], 0, v[112:113]
	global_store_dwordx4 v[64:65], v[68:71], off nt
	v_or_b32_e32 v64, 0x20100, v118
	ds_read_b32 v64, v64
	v_mul_f32_e32 v74, v74, v80
	v_mul_f32_e32 v75, v75, v80
	v_max_f32_e32 v90, 0, v90
	v_max_f32_e32 v91, 0, v91
	s_waitcnt lgkmcnt(0)
	v_mul_f32_e32 v60, v60, v64
	v_mul_f32_e32 v61, v61, v64
	v_mul_f32_e32 v62, v62, v64
	v_mul_f32_e32 v63, v63, v64
	v_mul_f32_e32 v56, v56, v64
	v_mul_f32_e32 v57, v57, v64
	v_max_f32_e32 v60, 0, v60
	v_max_f32_e32 v61, 0, v61
	v_max_f32_e32 v62, 0, v62
	v_max_f32_e32 v63, 0, v63
	v_max_f32_e32 v56, 0, v56
	v_max_f32_e32 v57, 0, v57
	v_mul_f32_e32 v52, v52, v64
	v_mul_f32_e32 v53, v53, v64
	v_mul_f32_e32 v54, v54, v64
	v_mul_f32_e32 v55, v55, v64
	v_mul_f32_e32 v48, v48, v64
	v_mul_f32_e32 v49, v49, v64
	v_mul_f32_e32 v50, v50, v64
	v_mul_f32_e32 v51, v51, v64
	v_pk_mul_f32 v[60:61], v[60:61], v[60:61]
	v_pk_mul_f32 v[62:63], v[62:63], v[62:63]
	v_pk_mul_f32 v[56:57], v[56:57], v[56:57]
	v_max_f32_e32 v52, 0, v52
	v_max_f32_e32 v53, 0, v53
	v_max_f32_e32 v54, 0, v54
	v_max_f32_e32 v55, 0, v55
	v_max_f32_e32 v48, 0, v48
	v_max_f32_e32 v49, 0, v49
	v_max_f32_e32 v50, 0, v50
	v_max_f32_e32 v51, 0, v51
	v_cvt_pk_bf16_f32 v60, v60, v61
	v_cvt_pk_bf16_f32 v61, v62, v63
	v_cvt_pk_bf16_f32 v62, v56, v57
	v_or_b32_e32 v56, 0x1000, v152
	v_mov_b32_e32 v57, v153
	v_pk_mul_f32 v[52:53], v[52:53], v[52:53]
	v_pk_mul_f32 v[54:55], v[54:55], v[54:55]
	v_pk_mul_f32 v[48:49], v[48:49], v[48:49]
	v_pk_mul_f32 v[50:51], v[50:51], v[50:51]
	v_cvt_pk_bf16_f32 v52, v52, v53
	v_cvt_pk_bf16_f32 v53, v54, v55
	v_cvt_pk_bf16_f32 v54, v48, v49
	v_cvt_pk_bf16_f32 v55, v50, v51
	v_lshl_add_u64 v[48:49], v[114:115], 0, v[56:57]
	v_permlane16_swap_b32_e32 v52, v54
	v_permlane16_swap_b32_e32 v53, v55
	v_lshl_add_u64 v[48:49], v[48:49], 0, v[112:113]
	global_store_dwordx4 v[48:49], v[52:55], off nt
	v_or_b32_e32 v48, 0x20140, v118
	ds_read_b32 v48, v48
	v_mul_f32_e32 v58, v58, v64
	v_mul_f32_e32 v59, v59, v64
	v_max_f32_e32 v74, 0, v74
	v_max_f32_e32 v75, 0, v75
	s_waitcnt lgkmcnt(0)
	v_mul_f32_e32 v44, v44, v48
	v_mul_f32_e32 v45, v45, v48
	v_mul_f32_e32 v46, v46, v48
	v_mul_f32_e32 v47, v47, v48
	v_mul_f32_e32 v40, v40, v48
	v_mul_f32_e32 v41, v41, v48
	v_max_f32_e32 v44, 0, v44
	v_max_f32_e32 v45, 0, v45
	v_max_f32_e32 v46, 0, v46
	v_max_f32_e32 v47, 0, v47
	v_max_f32_e32 v40, 0, v40
	v_max_f32_e32 v41, 0, v41
	v_mul_f32_e32 v36, v36, v48
	v_mul_f32_e32 v37, v37, v48
	v_mul_f32_e32 v38, v38, v48
	v_mul_f32_e32 v39, v39, v48
	v_mul_f32_e32 v32, v32, v48
	v_mul_f32_e32 v33, v33, v48
	v_mul_f32_e32 v34, v34, v48
	v_mul_f32_e32 v35, v35, v48
	v_pk_mul_f32 v[44:45], v[44:45], v[44:45]
	v_pk_mul_f32 v[46:47], v[46:47], v[46:47]
	v_pk_mul_f32 v[40:41], v[40:41], v[40:41]
	v_max_f32_e32 v36, 0, v36
	v_max_f32_e32 v37, 0, v37
	v_max_f32_e32 v38, 0, v38
	v_max_f32_e32 v39, 0, v39
	v_max_f32_e32 v32, 0, v32
	v_max_f32_e32 v33, 0, v33
	v_max_f32_e32 v34, 0, v34
	v_max_f32_e32 v35, 0, v35
	v_cvt_pk_bf16_f32 v44, v44, v45
	v_cvt_pk_bf16_f32 v45, v46, v47
	v_cvt_pk_bf16_f32 v46, v40, v41
	v_or_b32_e32 v40, 0x1400, v152
	v_mov_b32_e32 v41, v153
	v_pk_mul_f32 v[36:37], v[36:37], v[36:37]
	v_pk_mul_f32 v[38:39], v[38:39], v[38:39]
	v_pk_mul_f32 v[32:33], v[32:33], v[32:33]
	v_pk_mul_f32 v[34:35], v[34:35], v[34:35]
	v_cvt_pk_bf16_f32 v36, v36, v37
	v_cvt_pk_bf16_f32 v37, v38, v39
	v_cvt_pk_bf16_f32 v38, v32, v33
	v_cvt_pk_bf16_f32 v39, v34, v35
	v_lshl_add_u64 v[32:33], v[114:115], 0, v[40:41]
	v_permlane16_swap_b32_e32 v36, v38
	v_permlane16_swap_b32_e32 v37, v39
	v_lshl_add_u64 v[32:33], v[32:33], 0, v[112:113]
	global_store_dwordx4 v[32:33], v[36:39], off nt
	v_or_b32_e32 v32, 0x20180, v118
	ds_read_b32 v32, v32
	v_mul_f32_e32 v42, v42, v48
	v_mul_f32_e32 v43, v43, v48
	v_max_f32_e32 v58, 0, v58
	v_max_f32_e32 v59, 0, v59
	s_waitcnt lgkmcnt(0)
; template <int MODE, int NSUB>
; __device__ __forceinline__ void epilogue(const Params& p, int layer, f32x4 (&acc)[4][NSUB], int tm, int tn, int g,
;                                          const float* s_rstd, const int tid_in) {
;     ...
; #pragma unroll
;       for (int mp = 0; mp < 2; ++mp) {
;         bf16x4 pk[2];
; #pragma unroll
;         for (int h2 = 0; h2 < 2; ++h2) {
;           const int m = mp * 2 + h2;
;           float v[4];
; #pragma unroll
;           for (int j = 0; j < 4; ++j) {
;             float a = fmaxf(acc[m][n][j] * rs, 0.f);
;             v[j] = a * a;
;           }
;           pk[h2] = pack4(v[0], v[1], v[2], v[3]);
;         }
;         const int f = tm * 128 + wr * 64 + mp * 32 + woff;
;         __builtin_nontemporal_store(widen_pair(pk[0], pk[1]), reinterpret_cast<u32x4*>(p.hm + blk(t, f, 128)));
;       }
;     }
; __global__ void __launch_bounds__(NTHREADS) fwd_megakernel(Params p) {
;     ...
;           for (int id = rvid; id < 16 * CHUNK_TT; id += Greal) {
;             int ftb, ttl;
;             tile_decode_fb(id, 16, 4, ftb, ttl);
;             compute_rstd(p.part, 16, 1.0f / 1024.f, (chunk * CHUNK_TT + ttl) * 256, 256, s_rstd_b, tid_full);
;             f32x4 acc[4][8];
;             gemm_big<32>(acc, W + (long)ftb * 256 * 1024, 128 * 1024, p.xb + (long)(chunk * CHUNK_TT + ttl) * 256 * 1024, 128 * 1024, smem_all, tid_full);
;             const int ft = ftb * 2 + (widf >> 2);
;             epilogue<EPI_UP, 8>(p, l, acc, ft, ttl, 0, s_rstd_b, tid_e);
;             __syncthreads();
	v_mul_f32_e32 v28, v28, v32
	v_mul_f32_e32 v29, v29, v32
	v_mul_f32_e32 v30, v30, v32
	v_mul_f32_e32 v31, v31, v32
	v_mul_f32_e32 v24, v24, v32
	v_mul_f32_e32 v25, v25, v32
	v_max_f32_e32 v28, 0, v28
	v_max_f32_e32 v29, 0, v29
	v_max_f32_e32 v30, 0, v30
	v_max_f32_e32 v31, 0, v31
	v_max_f32_e32 v24, 0, v24
	v_max_f32_e32 v25, 0, v25
	v_mul_f32_e32 v20, v20, v32
	v_mul_f32_e32 v21, v21, v32
	v_mul_f32_e32 v22, v22, v32
	v_mul_f32_e32 v23, v23, v32
	v_mul_f32_e32 v16, v16, v32
	v_mul_f32_e32 v17, v17, v32
	v_mul_f32_e32 v18, v18, v32
	v_mul_f32_e32 v19, v19, v32
	v_pk_mul_f32 v[28:29], v[28:29], v[28:29]
	v_pk_mul_f32 v[30:31], v[30:31], v[30:31]
	v_pk_mul_f32 v[24:25], v[24:25], v[24:25]
	v_max_f32_e32 v20, 0, v20
	v_max_f32_e32 v21, 0, v21
	v_max_f32_e32 v22, 0, v22
	v_max_f32_e32 v23, 0, v23
	v_max_f32_e32 v16, 0, v16
	v_max_f32_e32 v17, 0, v17
	v_max_f32_e32 v18, 0, v18
	v_max_f32_e32 v19, 0, v19
	v_cvt_pk_bf16_f32 v28, v28, v29
	v_cvt_pk_bf16_f32 v29, v30, v31
	v_cvt_pk_bf16_f32 v30, v24, v25
	v_or_b32_e32 v24, 0x1800, v152
	v_mov_b32_e32 v25, v153
	v_pk_mul_f32 v[20:21], v[20:21], v[20:21]
	v_pk_mul_f32 v[22:23], v[22:23], v[22:23]
	v_pk_mul_f32 v[16:17], v[16:17], v[16:17]
	v_pk_mul_f32 v[18:19], v[18:19], v[18:19]
	v_cvt_pk_bf16_f32 v20, v20, v21
	v_cvt_pk_bf16_f32 v21, v22, v23
	v_cvt_pk_bf16_f32 v22, v16, v17
	v_cvt_pk_bf16_f32 v23, v18, v19
	v_lshl_add_u64 v[16:17], v[114:115], 0, v[24:25]
	v_permlane16_swap_b32_e32 v20, v22
	v_permlane16_swap_b32_e32 v21, v23
	v_lshl_add_u64 v[16:17], v[16:17], 0, v[112:113]
	global_store_dwordx4 v[16:17], v[20:23], off nt
	v_or_b32_e32 v16, 0x201c0, v118
	ds_read_b32 v16, v16
	v_mul_f32_e32 v26, v26, v32
	v_mul_f32_e32 v27, v27, v32
	v_max_f32_e32 v42, 0, v42
	v_max_f32_e32 v43, 0, v43
	s_waitcnt lgkmcnt(0)
	v_mul_f32_e32 v12, v12, v16
	v_mul_f32_e32 v13, v13, v16
	v_mul_f32_e32 v14, v14, v16
	v_mul_f32_e32 v15, v15, v16
	v_mul_f32_e32 v8, v8, v16
	v_mul_f32_e32 v9, v9, v16
	v_mul_f32_e32 v10, v10, v16
	v_mul_f32_e32 v11, v11, v16
	v_mul_f32_e32 v4, v4, v16
	v_mul_f32_e32 v5, v5, v16
	v_mul_f32_e32 v6, v6, v16
	v_mul_f32_e32 v7, v7, v16
	v_mul_f32_e32 v0, v0, v16
	v_mul_f32_e32 v1, v1, v16
	v_mul_f32_e32 v2, v2, v16
	v_mul_f32_e32 v3, v3, v16
	v_max_f32_e32 v26, 0, v26
	v_max_f32_e32 v27, 0, v27
	v_max_f32_e32 v12, 0, v12
	v_max_f32_e32 v13, 0, v13
	v_max_f32_e32 v14, 0, v14
	v_max_f32_e32 v15, 0, v15
	v_max_f32_e32 v8, 0, v8
	v_max_f32_e32 v9, 0, v9
	v_max_f32_e32 v10, 0, v10
	v_max_f32_e32 v11, 0, v11
	v_max_f32_e32 v4, 0, v4
	v_max_f32_e32 v5, 0, v5
	v_max_f32_e32 v6, 0, v6
	v_max_f32_e32 v7, 0, v7
	v_max_f32_e32 v0, 0, v0
	v_max_f32_e32 v1, 0, v1
	v_max_f32_e32 v2, 0, v2
	v_max_f32_e32 v3, 0, v3
	v_cvt_pk_bf16_f32 v122, v122, v123
	v_cvt_pk_bf16_f32 v123, v124, v125
	v_lshl_add_u64 v[124:125], v[114:115], 0, v[152:153]
	v_pk_mul_f32 v[106:107], v[106:107], v[106:107]
	v_pk_mul_f32 v[90:91], v[90:91], v[90:91]
	v_pk_mul_f32 v[74:75], v[74:75], v[74:75]
	v_pk_mul_f32 v[58:59], v[58:59], v[58:59]
	v_pk_mul_f32 v[42:43], v[42:43], v[42:43]
	v_pk_mul_f32 v[26:27], v[26:27], v[26:27]
	v_pk_mul_f32 v[12:13], v[12:13], v[12:13]
	v_pk_mul_f32 v[14:15], v[14:15], v[14:15]
	v_pk_mul_f32 v[8:9], v[8:9], v[8:9]
	v_pk_mul_f32 v[10:11], v[10:11], v[10:11]
	v_or_b32_e32 v152, 0x1c00, v152
	v_pk_mul_f32 v[4:5], v[4:5], v[4:5]
	v_pk_mul_f32 v[6:7], v[6:7], v[6:7]
	v_pk_mul_f32 v[0:1], v[0:1], v[0:1]
	v_pk_mul_f32 v[2:3], v[2:3], v[2:3]
	v_cvt_pk_bf16_f32 v111, v106, v107
	v_lshl_add_u64 v[106:107], v[116:117], 0, v[104:105]
	v_cvt_pk_bf16_f32 v95, v90, v91
	v_lshl_add_u64 v[90:91], v[116:117], 0, v[88:89]
	v_cvt_pk_bf16_f32 v79, v74, v75
	v_lshl_add_u64 v[74:75], v[116:117], 0, v[72:73]
	v_cvt_pk_bf16_f32 v63, v58, v59
	v_lshl_add_u64 v[58:59], v[116:117], 0, v[56:57]
	v_cvt_pk_bf16_f32 v47, v42, v43
	v_lshl_add_u64 v[42:43], v[116:117], 0, v[40:41]
	v_cvt_pk_bf16_f32 v31, v26, v27
	v_lshl_add_u64 v[26:27], v[116:117], 0, v[24:25]
	v_cvt_pk_bf16_f32 v12, v12, v13
	v_cvt_pk_bf16_f32 v13, v14, v15
	v_cvt_pk_bf16_f32 v14, v8, v9
	v_cvt_pk_bf16_f32 v15, v10, v11
	v_lshl_add_u64 v[8:9], v[116:117], 0, v[152:153]
	v_cvt_pk_bf16_f32 v4, v4, v5
	v_cvt_pk_bf16_f32 v5, v6, v7
	v_cvt_pk_bf16_f32 v6, v0, v1
	v_cvt_pk_bf16_f32 v7, v2, v3
	v_lshl_add_u64 v[0:1], v[114:115], 0, v[152:153]
	s_add_i32 s9, s9, s26
	v_permlane16_swap_b32_e32 v120, v122
	v_permlane16_swap_b32_e32 v121, v123
	v_lshl_add_u64 v[124:125], v[124:125], 0, v[112:113]
	v_permlane16_swap_b32_e32 v108, v110
	v_permlane16_swap_b32_e32 v109, v111
	v_lshl_add_u64 v[106:107], v[106:107], 0, v[112:113]
	v_permlane16_swap_b32_e32 v92, v94
	v_permlane16_swap_b32_e32 v93, v95
	v_lshl_add_u64 v[90:91], v[90:91], 0, v[112:113]
	v_permlane16_swap_b32_e32 v76, v78
	v_permlane16_swap_b32_e32 v77, v79
	v_lshl_add_u64 v[74:75], v[74:75], 0, v[112:113]
	v_permlane16_swap_b32_e32 v60, v62
	v_permlane16_swap_b32_e32 v61, v63
	v_lshl_add_u64 v[58:59], v[58:59], 0, v[112:113]
	v_permlane16_swap_b32_e32 v44, v46
	v_permlane16_swap_b32_e32 v45, v47
	v_lshl_add_u64 v[42:43], v[42:43], 0, v[112:113]
	v_permlane16_swap_b32_e32 v28, v30
	v_permlane16_swap_b32_e32 v29, v31
	v_lshl_add_u64 v[26:27], v[26:27], 0, v[112:113]
	v_permlane16_swap_b32_e32 v12, v14
	v_permlane16_swap_b32_e32 v13, v15
	v_lshl_add_u64 v[8:9], v[8:9], 0, v[112:113]
	v_permlane16_swap_b32_e32 v4, v6
	v_permlane16_swap_b32_e32 v5, v7
	v_lshl_add_u64 v[0:1], v[0:1], 0, v[112:113]
	s_cmpk_gt_i32 s9, 0x13ff
	v_readlane_b32 s65, v252, 5
	v_readlane_b32 s66, v252, 6
	v_readlane_b32 s67, v252, 7
	v_readlane_b32 s68, v252, 8
	v_readlane_b32 s69, v252, 9
	v_readlane_b32 s70, v252, 10
	v_readlane_b32 s71, v252, 11
	v_readlane_b32 s72, v252, 12
	v_readlane_b32 s73, v252, 13
	v_readlane_b32 s74, v252, 14
	v_readlane_b32 s75, v252, 15
	v_readlane_b32 s76, v252, 16
	v_readlane_b32 s77, v252, 17
	global_store_dwordx4 v[124:125], v[120:123], off nt
	global_store_dwordx4 v[106:107], v[108:111], off nt
	global_store_dwordx4 v[90:91], v[92:95], off nt
	global_store_dwordx4 v[74:75], v[76:79], off nt
	global_store_dwordx4 v[58:59], v[60:63], off nt
	global_store_dwordx4 v[42:43], v[44:47], off nt
	global_store_dwordx4 v[26:27], v[28:31], off nt
	global_store_dwordx4 v[8:9], v[12:15], off nt
	global_store_dwordx4 v[0:1], v[4:7], off nt
	s_barrier
	s_cbranch_scc0 .LBB0_287

; #define BIG_SYNC(N)                                              \
;   asm volatile("s_waitcnt vmcnt(%0)" ::"n"(N) : "memory");       \
;   __builtin_amdgcn_s_barrier();                                  \
;   asm volatile("" ::: "memory");                                 \
;   __builtin_amdgcn_sched_barrier(0);
; template <int NK, bool BNT = false> ...
;     ...
;   auto kstep = [&](int T, int cur, int nxt, bool do_stage) {
;     const unsigned char* sa = smem + cur * BIG_STAGE;
;     bf16x8 af[4], bfr[4];
; #pragma unroll
;     for (int m = 0; m < 4; ++m) af[m] = *reinterpret_cast<const bf16x8*>(sa + aoff + m * 1024);
; #pragma unroll
;     for (int n = 0; n < 4; ++n) bfr[n] = *reinterpret_cast<const bf16x8*>(sa + boff + n * 1024);
;     __builtin_amdgcn_sched_barrier(0);
;     if (do_stage) stage(T + 3, nxt);
; #pragma unroll
;     for (int m = 0; m < 4; ++m)
; #pragma unroll
;       for (int n = 0; n < 4; ++n) acc[m][n] = __builtin_amdgcn_mfma_f32_16x16x32_bf16(af[m], bfr[n], acc[m][n], 0, 0, 0);
;     if (do_stage) {
; #pragma unroll
;       for (int q = 0; q < NG; ++q) {
;         __builtin_amdgcn_sched_group_barrier(0x008, 3, 0);
;         __builtin_amdgcn_sched_group_barrier(0x010, 1, 0);
;       }
;       __builtin_amdgcn_sched_group_barrier(0x008, 16 - 3 * NG, 0);
;     }
;     __builtin_amdgcn_sched_barrier(0);
; #pragma unroll
;     for (int n = 0; n < 4; ++n) bfr[n] = *reinterpret_cast<const bf16x8*>(sa + boff + (4 + n) * 1024);
; #pragma unroll
;     for (int m = 0; m < 4; ++m)
; #pragma unroll
;       for (int n = 0; n < 4; ++n)
;         acc[m][4 + n] = __builtin_amdgcn_mfma_f32_16x16x32_bf16(af[m], bfr[n], acc[m][4 + n], 0, 0, 0);
;     __builtin_amdgcn_sched_barrier(0);
;   };
;     ...
;   stage(0, 0);
;   stage(1, 1);
;   stage(2, 2);
;   for (int it = 0; it < NK / 4 - 1; ++it) {
;     const int t = it * 4;
;     BIG_SYNC(2 * NG); kstep(t, 0, 3, true);
;     BIG_SYNC(2 * NG); kstep(t + 1, 1, 0, true);
;     BIG_SYNC(2 * NG); kstep(t + 2, 2, 1, true);
;     BIG_SYNC(2 * NG); kstep(t + 3, 3, 2, true);
;   }
.LBB0_302:
	v_add_u32_e32 v163, 0x18000, v147
	v_lshl_add_u64 v[144:145], v[138:139], 0, s[6:7]
	v_readfirstlane_b32 s5, v163
	v_lshl_add_u64 v[164:165], v[144:145], 0, s[60:61]
	s_mov_b32 m0, s5
	s_waitcnt lgkmcnt(3)
	v_mfma_f32_16x16x32_bf16 v[56:59], v[216:219], v[232:235], v[56:59]
	v_lshl_add_u64 v[142:143], v[140:141], 0, s[6:7]
	v_lshl_add_u64 v[168:169], v[144:145], 0, s[80:81]
	v_lshl_add_u64 v[166:167], v[142:143], 0, s[60:61]
	v_mfma_f32_16x16x32_bf16 v[100:103], v[220:223], v[232:235], v[100:103]
	v_mfma_f32_16x16x32_bf16 v[104:107], v[224:227], v[232:235], v[104:107]
	s_waitcnt vmcnt(4)
	s_barrier
	global_load_lds_dwordx4 v[164:165], off
	v_add_u32_e32 v164, 0x1a000, v147
	v_add_u32_e32 v165, 0x1c000, v147
	v_readfirstlane_b32 s5, v164
	s_mov_b32 m0, s5
	v_readfirstlane_b32 s5, v165
	v_mfma_f32_16x16x32_bf16 v[112:115], v[228:231], v[232:235], v[112:115]
	s_waitcnt lgkmcnt(2)
	v_mfma_f32_16x16x32_bf16 v[64:67], v[216:219], v[236:239], v[64:67]
	ds_read_b128 v[232:235], v149 offset:20480
	v_mfma_f32_16x16x32_bf16 v[80:83], v[220:223], v[236:239], v[80:83]
	global_load_lds_dwordx4 v[168:169], off
	s_mov_b32 m0, s5
	v_mfma_f32_16x16x32_bf16 v[96:99], v[224:227], v[236:239], v[96:99]
	v_lshl_add_u64 v[168:169], v[142:143], 0, s[80:81]
	v_mfma_f32_16x16x32_bf16 v[116:119], v[228:231], v[236:239], v[116:119]
	s_waitcnt lgkmcnt(2)
	v_mfma_f32_16x16x32_bf16 v[52:55], v[216:219], v[240:243], v[52:55]
	ds_read_b128 v[236:239], v149 offset:21504
	global_load_lds_dwordx4 v[166:167], off
	v_add_u32_e32 v166, 0x1e000, v147
	v_mfma_f32_16x16x32_bf16 v[68:71], v[220:223], v[240:243], v[68:71]
	v_readfirstlane_b32 s5, v166
	s_mov_b32 m0, s5
	v_mfma_f32_16x16x32_bf16 v[108:111], v[224:227], v[240:243], v[108:111]
	v_mfma_f32_16x16x32_bf16 v[120:123], v[228:231], v[240:243], v[120:123]
	global_load_lds_dwordx4 v[168:169], off
	s_waitcnt lgkmcnt(2)
	v_mfma_f32_16x16x32_bf16 v[48:51], v[216:219], v[244:247], v[48:51]
	ds_read_b128 v[240:243], v149 offset:22528
	v_mfma_f32_16x16x32_bf16 v[72:75], v[220:223], v[244:247], v[72:75]
	v_mfma_f32_16x16x32_bf16 v[88:91], v[224:227], v[244:247], v[88:91]
	v_mfma_f32_16x16x32_bf16 v[124:127], v[228:231], v[244:247], v[124:127]
	s_waitcnt lgkmcnt(2)
	v_mfma_f32_16x16x32_bf16 v[0:3], v[216:219], v[232:235], v[0:3]
	ds_read_b128 v[244:247], v149 offset:23552
	v_mfma_f32_16x16x32_bf16 v[16:19], v[220:223], v[232:235], v[16:19]
	ds_read_b128 v[186:189], v148 offset:32768
	v_mfma_f32_16x16x32_bf16 v[32:35], v[224:227], v[232:235], v[32:35]
	ds_read_b128 v[190:193], v148 offset:33792
	v_mfma_f32_16x16x32_bf16 v[60:63], v[228:231], v[232:235], v[60:63]
	ds_read_b128 v[194:197], v148 offset:34816
	s_waitcnt lgkmcnt(5)
	v_mfma_f32_16x16x32_bf16 v[4:7], v[216:219], v[236:239], v[4:7]
	ds_read_b128 v[202:205], v148 offset:35840
	ds_read_b128 v[232:235], v149 offset:49152
	v_mfma_f32_16x16x32_bf16 v[20:23], v[220:223], v[236:239], v[20:23]
	v_mfma_f32_16x16x32_bf16 v[36:39], v[224:227], v[236:239], v[36:39]
	v_mfma_f32_16x16x32_bf16 v[76:79], v[228:231], v[236:239], v[76:79]
	s_waitcnt lgkmcnt(6)
	v_mfma_f32_16x16x32_bf16 v[8:11], v[216:219], v[240:243], v[8:11]
	ds_read_b128 v[236:239], v149 offset:50176
	v_mfma_f32_16x16x32_bf16 v[24:27], v[220:223], v[240:243], v[24:27]
	v_mfma_f32_16x16x32_bf16 v[40:43], v[224:227], v[240:243], v[40:43]
	v_mfma_f32_16x16x32_bf16 v[84:87], v[228:231], v[240:243], v[84:87]
	s_waitcnt lgkmcnt(6)
	v_mfma_f32_16x16x32_bf16 v[12:15], v[216:219], v[244:247], v[12:15]
	ds_read_b128 v[240:243], v149 offset:51200
	v_mfma_f32_16x16x32_bf16 v[28:31], v[220:223], v[244:247], v[28:31]
	v_mfma_f32_16x16x32_bf16 v[44:47], v[224:227], v[244:247], v[44:47]
	v_mfma_f32_16x16x32_bf16 v[92:95], v[228:231], v[244:247], v[92:95]
	ds_read_b128 v[244:247], v149 offset:52224
	v_readfirstlane_b32 s5, v147
	v_lshl_add_u64 v[168:169], v[144:145], 0, s[62:63]
	s_mov_b32 m0, s5
	v_readfirstlane_b32 s5, v146
	s_waitcnt lgkmcnt(3)
	v_mfma_f32_16x16x32_bf16 v[56:59], v[186:189], v[232:235], v[56:59]
	v_lshl_add_u64 v[182:183], v[142:143], 0, s[62:63]
	v_mfma_f32_16x16x32_bf16 v[100:103], v[190:193], v[232:235], v[100:103]
	v_mfma_f32_16x16x32_bf16 v[104:107], v[194:197], v[232:235], v[104:107]
	s_waitcnt vmcnt(4)
	s_barrier
	global_load_lds_dwordx4 v[168:169], off
	v_lshl_add_u64 v[168:169], v[144:145], 0, s[0:1]
	s_mov_b32 m0, s5
	v_readfirstlane_b32 s5, v152
	v_mfma_f32_16x16x32_bf16 v[112:115], v[202:205], v[232:235], v[112:115]
	s_waitcnt lgkmcnt(2)
	v_mfma_f32_16x16x32_bf16 v[64:67], v[186:189], v[236:239], v[64:67]
	ds_read_b128 v[232:235], v149 offset:53248
	v_mfma_f32_16x16x32_bf16 v[80:83], v[190:193], v[236:239], v[80:83]
	global_load_lds_dwordx4 v[168:169], off
	s_mov_b32 m0, s5
	v_readfirstlane_b32 s5, v154
	v_lshl_add_u64 v[168:169], v[142:143], 0, s[0:1]
	v_mfma_f32_16x16x32_bf16 v[96:99], v[194:197], v[236:239], v[96:99]
	v_mfma_f32_16x16x32_bf16 v[116:119], v[202:205], v[236:239], v[116:119]
	s_waitcnt lgkmcnt(2)
	v_mfma_f32_16x16x32_bf16 v[52:55], v[186:189], v[240:243], v[52:55]
	ds_read_b128 v[236:239], v149 offset:54272
	global_load_lds_dwordx4 v[182:183], off
	s_mov_b32 m0, s5
	v_mfma_f32_16x16x32_bf16 v[68:71], v[190:193], v[240:243], v[68:71]
	v_mfma_f32_16x16x32_bf16 v[108:111], v[194:197], v[240:243], v[108:111]
	v_mfma_f32_16x16x32_bf16 v[120:123], v[202:205], v[240:243], v[120:123]
	global_load_lds_dwordx4 v[168:169], off
	s_waitcnt lgkmcnt(2)
	v_mfma_f32_16x16x32_bf16 v[48:51], v[186:189], v[244:247], v[48:51]
	ds_read_b128 v[240:243], v149 offset:55296
	v_mfma_f32_16x16x32_bf16 v[72:75], v[190:193], v[244:247], v[72:75]
	v_mfma_f32_16x16x32_bf16 v[88:91], v[194:197], v[244:247], v[88:91]
	v_mfma_f32_16x16x32_bf16 v[124:127], v[202:205], v[244:247], v[124:127]
	v_add_u32_e32 v167, 0x10000, v148
	v_or_b32_e32 v168, 0x10000, v150
	s_waitcnt lgkmcnt(2)
; #define BIG_SYNC(N)                                              \
;   asm volatile("s_waitcnt vmcnt(%0)" ::"n"(N) : "memory");       \
;   __builtin_amdgcn_s_barrier();                                  \
;   asm volatile("" ::: "memory");                                 \
;   __builtin_amdgcn_sched_barrier(0);
; template <int NK, bool BNT = false> ...
;     ...
;   auto kstep = [&](int T, int cur, int nxt, bool do_stage) {
;     const unsigned char* sa = smem + cur * BIG_STAGE;
;     bf16x8 af[4], bfr[4];
; #pragma unroll
;     for (int m = 0; m < 4; ++m) af[m] = *reinterpret_cast<const bf16x8*>(sa + aoff + m * 1024);
; #pragma unroll
;     for (int n = 0; n < 4; ++n) bfr[n] = *reinterpret_cast<const bf16x8*>(sa + boff + n * 1024);
;     __builtin_amdgcn_sched_barrier(0);
;     if (do_stage) stage(T + 3, nxt);
; #pragma unroll
;     for (int m = 0; m < 4; ++m)
; #pragma unroll
;       for (int n = 0; n < 4; ++n) acc[m][n] = __builtin_amdgcn_mfma_f32_16x16x32_bf16(af[m], bfr[n], acc[m][n], 0, 0, 0);
;     if (do_stage) {
; #pragma unroll
;       for (int q = 0; q < NG; ++q) {
;         __builtin_amdgcn_sched_group_barrier(0x008, 3, 0);
;         __builtin_amdgcn_sched_group_barrier(0x010, 1, 0);
;       }
;       __builtin_amdgcn_sched_group_barrier(0x008, 16 - 3 * NG, 0);
;     }
;     __builtin_amdgcn_sched_barrier(0);
; #pragma unroll
;     for (int n = 0; n < 4; ++n) bfr[n] = *reinterpret_cast<const bf16x8*>(sa + boff + (4 + n) * 1024);
; #pragma unroll
;     for (int m = 0; m < 4; ++m)
; #pragma unroll
;       for (int n = 0; n < 4; ++n)
;         acc[m][4 + n] = __builtin_amdgcn_mfma_f32_16x16x32_bf16(af[m], bfr[n], acc[m][4 + n], 0, 0, 0);
;     __builtin_amdgcn_sched_barrier(0);
;   };
;     ...
;   stage(0, 0);
;   stage(1, 1);
;   stage(2, 2);
;   for (int it = 0; it < NK / 4 - 1; ++it) {
;     const int t = it * 4;
;     BIG_SYNC(2 * NG); kstep(t, 0, 3, true);
;     BIG_SYNC(2 * NG); kstep(t + 1, 1, 0, true);
;     BIG_SYNC(2 * NG); kstep(t + 2, 2, 1, true);
;     BIG_SYNC(2 * NG); kstep(t + 3, 3, 2, true);
;   }
	v_mfma_f32_16x16x32_bf16 v[0:3], v[186:189], v[232:235], v[0:3]
	ds_read_b128 v[244:247], v149 offset:56320
	v_mfma_f32_16x16x32_bf16 v[16:19], v[190:193], v[232:235], v[16:19]
	ds_read_b128 v[216:219], v167
	v_mfma_f32_16x16x32_bf16 v[32:35], v[194:197], v[232:235], v[32:35]
	ds_read_b128 v[220:223], v167 offset:1024
	v_mfma_f32_16x16x32_bf16 v[60:63], v[202:205], v[232:235], v[60:63]
	ds_read_b128 v[224:227], v167 offset:2048
	s_waitcnt lgkmcnt(5)
	v_mfma_f32_16x16x32_bf16 v[4:7], v[186:189], v[236:239], v[4:7]
	ds_read_b128 v[228:231], v167 offset:3072
	ds_read_b128 v[232:235], v168
	v_mfma_f32_16x16x32_bf16 v[20:23], v[190:193], v[236:239], v[20:23]
	v_mfma_f32_16x16x32_bf16 v[36:39], v[194:197], v[236:239], v[36:39]
	v_mfma_f32_16x16x32_bf16 v[76:79], v[202:205], v[236:239], v[76:79]
	s_waitcnt lgkmcnt(6)
	v_mfma_f32_16x16x32_bf16 v[8:11], v[186:189], v[240:243], v[8:11]
	ds_read_b128 v[236:239], v168 offset:1024
	v_mfma_f32_16x16x32_bf16 v[24:27], v[190:193], v[240:243], v[24:27]
	v_mfma_f32_16x16x32_bf16 v[40:43], v[194:197], v[240:243], v[40:43]
	v_mfma_f32_16x16x32_bf16 v[84:87], v[202:205], v[240:243], v[84:87]
	s_waitcnt lgkmcnt(6)
	v_mfma_f32_16x16x32_bf16 v[12:15], v[186:189], v[244:247], v[12:15]
	ds_read_b128 v[240:243], v168 offset:2048
	v_mfma_f32_16x16x32_bf16 v[28:31], v[190:193], v[244:247], v[28:31]
	v_mfma_f32_16x16x32_bf16 v[44:47], v[194:197], v[244:247], v[44:47]
	v_mfma_f32_16x16x32_bf16 v[92:95], v[202:205], v[244:247], v[92:95]
	ds_read_b128 v[244:247], v168 offset:3072
	v_add_u32_e32 v167, 0x10000, v148
	v_or_b32_e32 v168, 0x10000, v150
	v_add_u32_e32 v169, 0x10400, v150
	v_add_u32_e32 v170, 0x10800, v150
	v_add_u32_e32 v172, 0x10c00, v150
	v_readfirstlane_b32 s5, v155
	v_lshl_add_u64 v[174:175], v[144:145], 0, s[2:3]
	s_mov_b32 m0, s5
	v_readfirstlane_b32 s5, v156
	s_waitcnt lgkmcnt(3)
	v_mfma_f32_16x16x32_bf16 v[56:59], v[216:219], v[232:235], v[56:59]
	v_lshl_add_u64 v[178:179], v[142:143], 0, s[2:3]
	v_mfma_f32_16x16x32_bf16 v[100:103], v[220:223], v[232:235], v[100:103]
	v_mfma_f32_16x16x32_bf16 v[104:107], v[224:227], v[232:235], v[104:107]
	s_waitcnt vmcnt(4)
	s_barrier
	global_load_lds_dwordx4 v[174:175], off
	v_lshl_add_u64 v[174:175], v[144:145], 0, s[52:53]
	s_mov_b32 m0, s5
	v_readfirstlane_b32 s5, v157
	v_mfma_f32_16x16x32_bf16 v[112:115], v[228:231], v[232:235], v[112:115]
	s_waitcnt lgkmcnt(2)
	v_mfma_f32_16x16x32_bf16 v[64:67], v[216:219], v[236:239], v[64:67]
	ds_read_b128 v[232:235], v168 offset:4096
	v_mfma_f32_16x16x32_bf16 v[80:83], v[220:223], v[236:239], v[80:83]
	global_load_lds_dwordx4 v[174:175], off
	s_mov_b32 m0, s5
	v_readfirstlane_b32 s5, v158
	v_lshl_add_u64 v[174:175], v[142:143], 0, s[52:53]
	v_mfma_f32_16x16x32_bf16 v[96:99], v[224:227], v[236:239], v[96:99]
	v_mfma_f32_16x16x32_bf16 v[116:119], v[228:231], v[236:239], v[116:119]
	s_waitcnt lgkmcnt(2)
	v_mfma_f32_16x16x32_bf16 v[52:55], v[216:219], v[240:243], v[52:55]
	ds_read_b128 v[236:239], v168 offset:5120
	global_load_lds_dwordx4 v[178:179], off
	s_mov_b32 m0, s5
	v_mfma_f32_16x16x32_bf16 v[68:71], v[220:223], v[240:243], v[68:71]
	v_mfma_f32_16x16x32_bf16 v[108:111], v[224:227], v[240:243], v[108:111]
	v_mfma_f32_16x16x32_bf16 v[120:123], v[228:231], v[240:243], v[120:123]
	global_load_lds_dwordx4 v[174:175], off
	s_waitcnt lgkmcnt(2)
	v_mfma_f32_16x16x32_bf16 v[48:51], v[216:219], v[244:247], v[48:51]
	ds_read_b128 v[240:243], v168 offset:6144
	v_mfma_f32_16x16x32_bf16 v[72:75], v[220:223], v[244:247], v[72:75]
	v_mfma_f32_16x16x32_bf16 v[88:91], v[224:227], v[244:247], v[88:91]
	v_mfma_f32_16x16x32_bf16 v[124:127], v[228:231], v[244:247], v[124:127]
	v_add_u32_e32 v173, 0x11000, v150
	v_add_u32_e32 v174, 0x11400, v150
	v_add_u32_e32 v175, 0x11800, v150
	v_add_u32_e32 v178, 0x11c00, v150
	v_add_u32_e32 v167, 0x10000, v148
	v_or_b32_e32 v168, 0x10000, v150
	s_waitcnt lgkmcnt(2)
	v_mfma_f32_16x16x32_bf16 v[0:3], v[216:219], v[232:235], v[0:3]
	ds_read_b128 v[244:247], v168 offset:7168
	v_mfma_f32_16x16x32_bf16 v[16:19], v[220:223], v[232:235], v[16:19]
	ds_read_b128 v[186:189], v167 offset:32768
	v_mfma_f32_16x16x32_bf16 v[32:35], v[224:227], v[232:235], v[32:35]
	ds_read_b128 v[190:193], v167 offset:33792
	v_mfma_f32_16x16x32_bf16 v[60:63], v[228:231], v[232:235], v[60:63]
	ds_read_b128 v[194:197], v167 offset:34816
	s_waitcnt lgkmcnt(5)
	v_mfma_f32_16x16x32_bf16 v[4:7], v[216:219], v[236:239], v[4:7]
	ds_read_b128 v[202:205], v167 offset:35840
	ds_read_b128 v[232:235], v168 offset:32768
	v_mfma_f32_16x16x32_bf16 v[20:23], v[220:223], v[236:239], v[20:23]
	v_mfma_f32_16x16x32_bf16 v[36:39], v[224:227], v[236:239], v[36:39]
	v_mfma_f32_16x16x32_bf16 v[76:79], v[228:231], v[236:239], v[76:79]
	s_waitcnt lgkmcnt(6)
	v_mfma_f32_16x16x32_bf16 v[8:11], v[216:219], v[240:243], v[8:11]
	ds_read_b128 v[236:239], v168 offset:33792
	v_mfma_f32_16x16x32_bf16 v[24:27], v[220:223], v[240:243], v[24:27]
	v_mfma_f32_16x16x32_bf16 v[40:43], v[224:227], v[240:243], v[40:43]
	v_mfma_f32_16x16x32_bf16 v[84:87], v[228:231], v[240:243], v[84:87]
	s_waitcnt lgkmcnt(6)
	v_mfma_f32_16x16x32_bf16 v[12:15], v[216:219], v[244:247], v[12:15]
	ds_read_b128 v[240:243], v168 offset:34816
	v_mfma_f32_16x16x32_bf16 v[28:31], v[220:223], v[244:247], v[28:31]
	v_mfma_f32_16x16x32_bf16 v[44:47], v[224:227], v[244:247], v[44:47]
	v_mfma_f32_16x16x32_bf16 v[92:95], v[228:231], v[244:247], v[92:95]
	ds_read_b128 v[244:247], v168 offset:35840
	v_add_u32_e32 v176, 0x18000, v148
	v_or_b32_e32 v179, 0x18000, v150
	v_add_u32_e32 v180, 0x18400, v150
	v_add_u32_e32 v181, 0x18800, v150
	v_add_u32_e32 v182, 0x18c00, v150
	v_readfirstlane_b32 s5, v159
	v_lshl_add_u64 v[248:249], v[144:145], 0, s[54:55]
	s_mov_b32 m0, s5
	v_readfirstlane_b32 s5, v160
	v_lshl_add_u64 v[144:145], v[144:145], 0, s[56:57]
	s_waitcnt lgkmcnt(3)
	v_mfma_f32_16x16x32_bf16 v[56:59], v[186:189], v[232:235], v[56:59]
	v_lshl_add_u64 v[250:251], v[142:143], 0, s[54:55]
	v_lshl_add_u64 v[142:143], v[142:143], 0, s[56:57]
	v_mfma_f32_16x16x32_bf16 v[100:103], v[190:193], v[232:235], v[100:103]
	v_mfma_f32_16x16x32_bf16 v[104:107], v[194:197], v[232:235], v[104:107]
	s_waitcnt vmcnt(4)
	s_barrier
; #define BIG_SYNC(N)                                              \
;   asm volatile("s_waitcnt vmcnt(%0)" ::"n"(N) : "memory");       \
;   __builtin_amdgcn_s_barrier();                                  \
;   asm volatile("" ::: "memory");                                 \
;   __builtin_amdgcn_sched_barrier(0);
; template <int NK, bool BNT = false> ...
;     ...
;   auto kstep = [&](int T, int cur, int nxt, bool do_stage) {
;     const unsigned char* sa = smem + cur * BIG_STAGE;
;     bf16x8 af[4], bfr[4];
; #pragma unroll
;     for (int m = 0; m < 4; ++m) af[m] = *reinterpret_cast<const bf16x8*>(sa + aoff + m * 1024);
; #pragma unroll
;     for (int n = 0; n < 4; ++n) bfr[n] = *reinterpret_cast<const bf16x8*>(sa + boff + n * 1024);
;     __builtin_amdgcn_sched_barrier(0);
;     if (do_stage) stage(T + 3, nxt);
; #pragma unroll
;     for (int m = 0; m < 4; ++m)
; #pragma unroll
;       for (int n = 0; n < 4; ++n) acc[m][n] = __builtin_amdgcn_mfma_f32_16x16x32_bf16(af[m], bfr[n], acc[m][n], 0, 0, 0);
;     if (do_stage) {
; #pragma unroll
;       for (int q = 0; q < NG; ++q) {
;         __builtin_amdgcn_sched_group_barrier(0x008, 3, 0);
;         __builtin_amdgcn_sched_group_barrier(0x010, 1, 0);
;       }
;       __builtin_amdgcn_sched_group_barrier(0x008, 16 - 3 * NG, 0);
;     }
;     __builtin_amdgcn_sched_barrier(0);
; #pragma unroll
;     for (int n = 0; n < 4; ++n) bfr[n] = *reinterpret_cast<const bf16x8*>(sa + boff + (4 + n) * 1024);
; #pragma unroll
;     for (int m = 0; m < 4; ++m)
; #pragma unroll
;       for (int n = 0; n < 4; ++n)
;         acc[m][4 + n] = __builtin_amdgcn_mfma_f32_16x16x32_bf16(af[m], bfr[n], acc[m][4 + n], 0, 0, 0);
;     __builtin_amdgcn_sched_barrier(0);
;   };
;     ...
;   stage(0, 0);
;   stage(1, 1);
;   stage(2, 2);
;   for (int it = 0; it < NK / 4 - 1; ++it) {
;     const int t = it * 4;
;     BIG_SYNC(2 * NG); kstep(t, 0, 3, true);
;     BIG_SYNC(2 * NG); kstep(t + 1, 1, 0, true);
;     BIG_SYNC(2 * NG); kstep(t + 2, 2, 1, true);
;     BIG_SYNC(2 * NG); kstep(t + 3, 3, 2, true);
;   }
;   BIG_SYNC(2 * NG); kstep(NK - 4, 0, 3, true);
	global_load_lds_dwordx4 v[248:249], off
	s_mov_b32 m0, s5
	v_readfirstlane_b32 s5, v161
	v_mfma_f32_16x16x32_bf16 v[112:115], v[202:205], v[232:235], v[112:115]
	s_waitcnt lgkmcnt(2)
	v_mfma_f32_16x16x32_bf16 v[64:67], v[186:189], v[236:239], v[64:67]
	ds_read_b128 v[232:235], v168 offset:36864
	v_mfma_f32_16x16x32_bf16 v[80:83], v[190:193], v[236:239], v[80:83]
	global_load_lds_dwordx4 v[144:145], off
	s_mov_b32 m0, s5
	v_readfirstlane_b32 s5, v162
	v_mfma_f32_16x16x32_bf16 v[96:99], v[194:197], v[236:239], v[96:99]
	v_mfma_f32_16x16x32_bf16 v[116:119], v[202:205], v[236:239], v[116:119]
	s_waitcnt lgkmcnt(2)
	v_mfma_f32_16x16x32_bf16 v[52:55], v[186:189], v[240:243], v[52:55]
	ds_read_b128 v[236:239], v168 offset:37888
	global_load_lds_dwordx4 v[250:251], off
	s_mov_b32 m0, s5
	v_mfma_f32_16x16x32_bf16 v[68:71], v[190:193], v[240:243], v[68:71]
	v_mfma_f32_16x16x32_bf16 v[108:111], v[194:197], v[240:243], v[108:111]
	v_mfma_f32_16x16x32_bf16 v[120:123], v[202:205], v[240:243], v[120:123]
	global_load_lds_dwordx4 v[142:143], off
	s_waitcnt lgkmcnt(2)
	v_mfma_f32_16x16x32_bf16 v[48:51], v[186:189], v[244:247], v[48:51]
	ds_read_b128 v[240:243], v168 offset:38912
	v_mfma_f32_16x16x32_bf16 v[72:75], v[190:193], v[244:247], v[72:75]
	v_mfma_f32_16x16x32_bf16 v[88:91], v[194:197], v[244:247], v[88:91]
	v_mfma_f32_16x16x32_bf16 v[124:127], v[202:205], v[244:247], v[124:127]
	v_add_u32_e32 v142, 0x19000, v150
	v_add_u32_e32 v143, 0x19400, v150
	v_add_u32_e32 v144, 0x19800, v150
	v_add_u32_e32 v145, 0x19c00, v150
	s_waitcnt lgkmcnt(2)
	v_mfma_f32_16x16x32_bf16 v[0:3], v[186:189], v[232:235], v[0:3]
	ds_read_b128 v[244:247], v168 offset:39936
	v_mfma_f32_16x16x32_bf16 v[16:19], v[190:193], v[232:235], v[16:19]
	ds_read_b128 v[216:219], v148
	v_mfma_f32_16x16x32_bf16 v[32:35], v[194:197], v[232:235], v[32:35]
	ds_read_b128 v[220:223], v148 offset:1024
	v_mfma_f32_16x16x32_bf16 v[60:63], v[202:205], v[232:235], v[60:63]
	ds_read_b128 v[224:227], v148 offset:2048
	s_waitcnt lgkmcnt(5)
	v_mfma_f32_16x16x32_bf16 v[4:7], v[186:189], v[236:239], v[4:7]
	ds_read_b128 v[228:231], v148 offset:3072
	ds_read_b128 v[232:235], v149 offset:16384
	v_mfma_f32_16x16x32_bf16 v[20:23], v[190:193], v[236:239], v[20:23]
	v_mfma_f32_16x16x32_bf16 v[36:39], v[194:197], v[236:239], v[36:39]
	v_mfma_f32_16x16x32_bf16 v[76:79], v[202:205], v[236:239], v[76:79]
	s_waitcnt lgkmcnt(6)
	v_mfma_f32_16x16x32_bf16 v[8:11], v[186:189], v[240:243], v[8:11]
	ds_read_b128 v[236:239], v149 offset:17408
	v_mfma_f32_16x16x32_bf16 v[24:27], v[190:193], v[240:243], v[24:27]
	v_mfma_f32_16x16x32_bf16 v[40:43], v[194:197], v[240:243], v[40:43]
	v_mfma_f32_16x16x32_bf16 v[84:87], v[202:205], v[240:243], v[84:87]
	s_waitcnt lgkmcnt(6)
	v_mfma_f32_16x16x32_bf16 v[12:15], v[186:189], v[244:247], v[12:15]
	ds_read_b128 v[240:243], v149 offset:18432
	v_mfma_f32_16x16x32_bf16 v[28:31], v[190:193], v[244:247], v[28:31]
	v_mfma_f32_16x16x32_bf16 v[44:47], v[194:197], v[244:247], v[44:47]
	v_mfma_f32_16x16x32_bf16 v[92:95], v[202:205], v[244:247], v[92:95]
	ds_read_b128 v[244:247], v149 offset:19456
	s_add_u32 s6, s6, 0x8000
	s_addc_u32 s7, s7, 0
	s_cmp_lg_u32 s6, 0x38000
	s_cbranch_scc1 .LBB0_302
	s_sext_i32_i8 s4, s4
	s_mov_b64 s[6:7], 0x3e000
	v_readfirstlane_b32 s5, v163
	v_lshl_add_u64 v[198:199], v[136:137], 0, s[6:7]
	v_lshl_add_u64 v[200:201], v[134:135], 0, s[6:7]
	s_mov_b32 m0, s5
	s_mov_b64 s[6:7], 0x7e000
	v_readfirstlane_b32 s5, v164
	v_lshl_add_u64 v[136:137], v[136:137], 0, s[6:7]
	s_waitcnt lgkmcnt(3)
	v_mfma_f32_16x16x32_bf16 v[56:59], v[216:219], v[232:235], v[56:59]
	v_lshl_add_u64 v[134:135], v[134:135], 0, s[6:7]
	v_mfma_f32_16x16x32_bf16 v[100:103], v[220:223], v[232:235], v[100:103]
	v_mfma_f32_16x16x32_bf16 v[104:107], v[224:227], v[232:235], v[104:107]
	s_waitcnt vmcnt(4)
	s_barrier
	global_load_lds_dwordx4 v[198:199], off
	s_mov_b32 m0, s5
	v_readfirstlane_b32 s5, v165
	v_mfma_f32_16x16x32_bf16 v[112:115], v[228:231], v[232:235], v[112:115]
	s_waitcnt lgkmcnt(2)
	v_mfma_f32_16x16x32_bf16 v[64:67], v[216:219], v[236:239], v[64:67]
	ds_read_b128 v[232:235], v149 offset:20480
	v_mfma_f32_16x16x32_bf16 v[80:83], v[220:223], v[236:239], v[80:83]
	global_load_lds_dwordx4 v[136:137], off
	s_mov_b32 m0, s5
	v_readfirstlane_b32 s5, v166
	v_mfma_f32_16x16x32_bf16 v[96:99], v[224:227], v[236:239], v[96:99]
	v_mfma_f32_16x16x32_bf16 v[116:119], v[228:231], v[236:239], v[116:119]
	s_waitcnt lgkmcnt(2)
	v_mfma_f32_16x16x32_bf16 v[52:55], v[216:219], v[240:243], v[52:55]
	ds_read_b128 v[236:239], v149 offset:21504
	global_load_lds_dwordx4 v[200:201], off
	s_mov_b32 m0, s5
	v_mfma_f32_16x16x32_bf16 v[68:71], v[220:223], v[240:243], v[68:71]
	v_mfma_f32_16x16x32_bf16 v[108:111], v[224:227], v[240:243], v[108:111]
	v_mfma_f32_16x16x32_bf16 v[120:123], v[228:231], v[240:243], v[120:123]
	global_load_lds_dwordx4 v[134:135], off
	s_waitcnt lgkmcnt(2)
	v_mfma_f32_16x16x32_bf16 v[48:51], v[216:219], v[244:247], v[48:51]
	ds_read_b128 v[240:243], v149 offset:22528
	v_mfma_f32_16x16x32_bf16 v[72:75], v[220:223], v[244:247], v[72:75]
	v_mfma_f32_16x16x32_bf16 v[88:91], v[224:227], v[244:247], v[88:91]
	v_mfma_f32_16x16x32_bf16 v[124:127], v[228:231], v[244:247], v[124:127]
	s_waitcnt lgkmcnt(2)
	v_mfma_f32_16x16x32_bf16 v[0:3], v[216:219], v[232:235], v[0:3]
	ds_read_b128 v[244:247], v149 offset:23552
	v_mfma_f32_16x16x32_bf16 v[16:19], v[220:223], v[232:235], v[16:19]
	ds_read_b128 v[186:189], v148 offset:32768
	v_mfma_f32_16x16x32_bf16 v[32:35], v[224:227], v[232:235], v[32:35]
	ds_read_b128 v[190:193], v148 offset:33792
	v_mfma_f32_16x16x32_bf16 v[60:63], v[228:231], v[232:235], v[60:63]
	ds_read_b128 v[194:197], v148 offset:34816
	s_waitcnt lgkmcnt(5)
; #define BIG_SYNC(N)                                              \
;   asm volatile("s_waitcnt vmcnt(%0)" ::"n"(N) : "memory");       \
;   __builtin_amdgcn_s_barrier();                                  \
;   asm volatile("" ::: "memory");                                 \
;   __builtin_amdgcn_sched_barrier(0);
; template <int NK, bool BNT = false> ...
;     ...
;   auto kstep = [&](int T, int cur, int nxt, bool do_stage) {
;     const unsigned char* sa = smem + cur * BIG_STAGE;
;     bf16x8 af[4], bfr[4];
; #pragma unroll
;     for (int m = 0; m < 4; ++m) af[m] = *reinterpret_cast<const bf16x8*>(sa + aoff + m * 1024);
; #pragma unroll
;     for (int n = 0; n < 4; ++n) bfr[n] = *reinterpret_cast<const bf16x8*>(sa + boff + n * 1024);
;     __builtin_amdgcn_sched_barrier(0);
;     if (do_stage) stage(T + 3, nxt);
; #pragma unroll
;     for (int m = 0; m < 4; ++m)
; #pragma unroll
;       for (int n = 0; n < 4; ++n) acc[m][n] = __builtin_amdgcn_mfma_f32_16x16x32_bf16(af[m], bfr[n], acc[m][n], 0, 0, 0);
;     if (do_stage) {
; #pragma unroll
;       for (int q = 0; q < NG; ++q) {
;         __builtin_amdgcn_sched_group_barrier(0x008, 3, 0);
;         __builtin_amdgcn_sched_group_barrier(0x010, 1, 0);
;       }
;       __builtin_amdgcn_sched_group_barrier(0x008, 16 - 3 * NG, 0);
;     }
;     __builtin_amdgcn_sched_barrier(0);
; #pragma unroll
;     for (int n = 0; n < 4; ++n) bfr[n] = *reinterpret_cast<const bf16x8*>(sa + boff + (4 + n) * 1024);
; #pragma unroll
;     for (int m = 0; m < 4; ++m)
; #pragma unroll
;       for (int n = 0; n < 4; ++n)
;         acc[m][4 + n] = __builtin_amdgcn_mfma_f32_16x16x32_bf16(af[m], bfr[n], acc[m][4 + n], 0, 0, 0);
;     __builtin_amdgcn_sched_barrier(0);
;   };
;     ...
;   stage(0, 0);
;   stage(1, 1);
;   stage(2, 2);
;   for (int it = 0; it < NK / 4 - 1; ++it) {
;     const int t = it * 4;
;     BIG_SYNC(2 * NG); kstep(t, 0, 3, true);
;     BIG_SYNC(2 * NG); kstep(t + 1, 1, 0, true);
;     BIG_SYNC(2 * NG); kstep(t + 2, 2, 1, true);
;     BIG_SYNC(2 * NG); kstep(t + 3, 3, 2, true);
;   }
;   BIG_SYNC(2 * NG); kstep(NK - 4, 0, 3, true);
;   BIG_SYNC(2 * NG); kstep(NK - 3, 1, 0, false);
;   BIG_SYNC(NG);     kstep(NK - 2, 2, 0, false);
;   BIG_SYNC(0);      kstep(NK - 1, 3, 0, false);
	v_mfma_f32_16x16x32_bf16 v[4:7], v[216:219], v[236:239], v[4:7]
	ds_read_b128 v[202:205], v148 offset:35840
	ds_read_b128 v[232:235], v149 offset:49152
	v_mfma_f32_16x16x32_bf16 v[20:23], v[220:223], v[236:239], v[20:23]
	v_mfma_f32_16x16x32_bf16 v[36:39], v[224:227], v[236:239], v[36:39]
	v_mfma_f32_16x16x32_bf16 v[76:79], v[228:231], v[236:239], v[76:79]
	s_waitcnt lgkmcnt(6)
	v_mfma_f32_16x16x32_bf16 v[8:11], v[216:219], v[240:243], v[8:11]
	ds_read_b128 v[236:239], v149 offset:50176
	v_mfma_f32_16x16x32_bf16 v[24:27], v[220:223], v[240:243], v[24:27]
	v_mfma_f32_16x16x32_bf16 v[40:43], v[224:227], v[240:243], v[40:43]
	v_mfma_f32_16x16x32_bf16 v[84:87], v[228:231], v[240:243], v[84:87]
	s_waitcnt lgkmcnt(6)
	v_mfma_f32_16x16x32_bf16 v[12:15], v[216:219], v[244:247], v[12:15]
	ds_read_b128 v[240:243], v149 offset:51200
	v_mfma_f32_16x16x32_bf16 v[28:31], v[220:223], v[244:247], v[28:31]
	v_mfma_f32_16x16x32_bf16 v[44:47], v[224:227], v[244:247], v[44:47]
	v_mfma_f32_16x16x32_bf16 v[92:95], v[228:231], v[244:247], v[92:95]
	ds_read_b128 v[244:247], v149 offset:52224
	s_waitcnt lgkmcnt(3)
	v_mfma_f32_16x16x32_bf16 v[56:59], v[186:189], v[232:235], v[56:59]
	v_mfma_f32_16x16x32_bf16 v[100:103], v[190:193], v[232:235], v[100:103]
	v_mfma_f32_16x16x32_bf16 v[104:107], v[194:197], v[232:235], v[104:107]
	v_mfma_f32_16x16x32_bf16 v[112:115], v[202:205], v[232:235], v[112:115]
	s_waitcnt vmcnt(4)
	s_barrier
	s_waitcnt lgkmcnt(2)
	v_mfma_f32_16x16x32_bf16 v[64:67], v[186:189], v[236:239], v[64:67]
	ds_read_b128 v[232:235], v149 offset:53248
	v_mfma_f32_16x16x32_bf16 v[80:83], v[190:193], v[236:239], v[80:83]
	v_mfma_f32_16x16x32_bf16 v[96:99], v[194:197], v[236:239], v[96:99]
	v_mfma_f32_16x16x32_bf16 v[116:119], v[202:205], v[236:239], v[116:119]
	s_waitcnt lgkmcnt(2)
	v_mfma_f32_16x16x32_bf16 v[52:55], v[186:189], v[240:243], v[52:55]
	ds_read_b128 v[236:239], v149 offset:54272
	v_mfma_f32_16x16x32_bf16 v[68:71], v[190:193], v[240:243], v[68:71]
	v_mfma_f32_16x16x32_bf16 v[108:111], v[194:197], v[240:243], v[108:111]
	v_mfma_f32_16x16x32_bf16 v[120:123], v[202:205], v[240:243], v[120:123]
	s_waitcnt lgkmcnt(2)
	v_mfma_f32_16x16x32_bf16 v[48:51], v[186:189], v[244:247], v[48:51]
	ds_read_b128 v[240:243], v149 offset:55296
	v_mfma_f32_16x16x32_bf16 v[72:75], v[190:193], v[244:247], v[72:75]
	v_mfma_f32_16x16x32_bf16 v[88:91], v[194:197], v[244:247], v[88:91]
	v_mfma_f32_16x16x32_bf16 v[124:127], v[202:205], v[244:247], v[124:127]
	s_waitcnt lgkmcnt(2)
	v_mfma_f32_16x16x32_bf16 v[0:3], v[186:189], v[232:235], v[0:3]
	ds_read_b128 v[244:247], v149 offset:56320
	v_mfma_f32_16x16x32_bf16 v[16:19], v[190:193], v[232:235], v[16:19]
	v_mfma_f32_16x16x32_bf16 v[32:35], v[194:197], v[232:235], v[32:35]
	v_mfma_f32_16x16x32_bf16 v[60:63], v[202:205], v[232:235], v[60:63]
	s_waitcnt lgkmcnt(2)
	v_mfma_f32_16x16x32_bf16 v[4:7], v[186:189], v[236:239], v[4:7]
	v_mfma_f32_16x16x32_bf16 v[20:23], v[190:193], v[236:239], v[20:23]
	v_mfma_f32_16x16x32_bf16 v[36:39], v[194:197], v[236:239], v[36:39]
	v_mfma_f32_16x16x32_bf16 v[76:79], v[202:205], v[236:239], v[76:79]
	s_waitcnt lgkmcnt(1)
	v_mfma_f32_16x16x32_bf16 v[8:11], v[186:189], v[240:243], v[8:11]
	v_mfma_f32_16x16x32_bf16 v[24:27], v[190:193], v[240:243], v[24:27]
	v_mfma_f32_16x16x32_bf16 v[40:43], v[194:197], v[240:243], v[40:43]
	v_mfma_f32_16x16x32_bf16 v[84:87], v[202:205], v[240:243], v[84:87]
	s_waitcnt lgkmcnt(0)
	v_mfma_f32_16x16x32_bf16 v[12:15], v[186:189], v[244:247], v[12:15]
	v_mfma_f32_16x16x32_bf16 v[28:31], v[190:193], v[244:247], v[28:31]
	v_mfma_f32_16x16x32_bf16 v[44:47], v[194:197], v[244:247], v[44:47]
	v_mfma_f32_16x16x32_bf16 v[92:95], v[202:205], v[244:247], v[92:95]
	v_mov_b32_e32 v186, 0xf149f2ca
	v_mov_b32_e32 v187, 0x3c0881c4
	v_mov_b32_e32 v188, 0xbab64f3b
	v_mov_b32_e32 v189, 0x24800
	v_mov_b32_e32 v190, 1
	v_mov_b32_e32 v191, 0x24804
	v_mov_b32_e32 v192, 0xfcf
	v_mov_b32_e32 v193, 0x7cf
	v_mov_b32_e32 v194, 0xfdf
	v_mov_b32_e32 v195, 0x7df
	v_mov_b32_e32 v196, 0xfef
	v_mov_b32_e32 v197, 0x7ef
	v_mov_b32_e32 v198, 0xfff
	v_mov_b32_e32 v199, 0x7ff
	v_mov_b32_e32 v200, 0x20000
	v_mov_b32_e32 v201, 0xf8f
	v_mov_b32_e32 v202, 0x78f
	v_mov_b32_e32 v203, 0xf9f
	v_mov_b32_e32 v204, 0x79f
	v_mov_b32_e32 v205, 0xfaf
	s_waitcnt vmcnt(4)
	s_barrier
; template <int NK, bool BNT = false> ...
;     ...
;   auto kstep = [&](int T, int cur, int nxt, bool do_stage) {
;     const unsigned char* sa = smem + cur * BIG_STAGE;
;     bf16x8 af[4], bfr[4];
; #pragma unroll
;     for (int m = 0; m < 4; ++m) af[m] = *reinterpret_cast<const bf16x8*>(sa + aoff + m * 1024);
; #pragma unroll
;     for (int n = 0; n < 4; ++n) bfr[n] = *reinterpret_cast<const bf16x8*>(sa + boff + n * 1024);
;     __builtin_amdgcn_sched_barrier(0);
;     if (do_stage) stage(T + 3, nxt);
; #pragma unroll
;     for (int m = 0; m < 4; ++m)
; #pragma unroll
;       for (int n = 0; n < 4; ++n) acc[m][n] = __builtin_amdgcn_mfma_f32_16x16x32_bf16(af[m], bfr[n], acc[m][n], 0, 0, 0);
;     if (do_stage) {
; #pragma unroll
;       for (int q = 0; q < NG; ++q) {
;         __builtin_amdgcn_sched_group_barrier(0x008, 3, 0);
;         __builtin_amdgcn_sched_group_barrier(0x010, 1, 0);
;       }
;       __builtin_amdgcn_sched_group_barrier(0x008, 16 - 3 * NG, 0);
;     }
;     __builtin_amdgcn_sched_barrier(0);
; #pragma unroll
;     for (int n = 0; n < 4; ++n) bfr[n] = *reinterpret_cast<const bf16x8*>(sa + boff + (4 + n) * 1024);
; #pragma unroll
;     for (int m = 0; m < 4; ++m)
; #pragma unroll
;       for (int n = 0; n < 4; ++n)
;         acc[m][4 + n] = __builtin_amdgcn_mfma_f32_16x16x32_bf16(af[m], bfr[n], acc[m][4 + n], 0, 0, 0);
;     __builtin_amdgcn_sched_barrier(0);
;   };
;     ...
;   stage(0, 0);
;   stage(1, 1);
;   stage(2, 2);
;   for (int it = 0; it < NK / 4 - 1; ++it) {
;     const int t = it * 4;
;     BIG_SYNC(2 * NG); kstep(t, 0, 3, true);
;     BIG_SYNC(2 * NG); kstep(t + 1, 1, 0, true);
;     BIG_SYNC(2 * NG); kstep(t + 2, 2, 1, true);
;     BIG_SYNC(2 * NG); kstep(t + 3, 3, 2, true);
;   }
;   BIG_SYNC(2 * NG); kstep(NK - 4, 0, 3, true);
;   BIG_SYNC(2 * NG); kstep(NK - 3, 1, 0, false);
;   BIG_SYNC(NG);     kstep(NK - 2, 2, 0, false);
;   BIG_SYNC(0);      kstep(NK - 1, 3, 0, false);
; template <int MODE, int NSUB>
; __device__ __forceinline__ void epilogue(const Params& p, int layer, f32x4 (&acc)[4][NSUB], int tm, int tn, int g,
;                                          const float* s_rstd, const int tid_in) {
;     ...
;   if constexpr (MODE == EPI_G1) {
;     const int ft = tm;
; #pragma unroll
;     for (int n = 0; n < NSUB; ++n) {
;       const int nl = wc * (NSUB * 16) + n * 16 + fr;
;       const int t = tn * (NSUB * 32) + nl;
	ds_read_b128 v[134:137], v167
	ds_read_b128 v[138:141], v167 offset:1024
	ds_read_b128 v[154:157], v167 offset:2048
	ds_read_b128 v[158:161], v167 offset:3072
	ds_read_b128 v[162:165], v168
	ds_read_b128 v[166:169], v169
	ds_read_b128 v[216:219], v170
	ds_read_b128 v[220:223], v172
	s_waitcnt lgkmcnt(0)
	v_mfma_f32_16x16x32_bf16 v[56:59], v[134:137], v[162:165], v[56:59]
	v_mfma_f32_16x16x32_bf16 v[64:67], v[134:137], v[166:169], v[64:67]
	v_mfma_f32_16x16x32_bf16 v[52:55], v[134:137], v[216:219], v[52:55]
	v_mfma_f32_16x16x32_bf16 v[48:51], v[134:137], v[220:223], v[48:51]
	v_mfma_f32_16x16x32_bf16 v[100:103], v[138:141], v[162:165], v[100:103]
	v_mfma_f32_16x16x32_bf16 v[80:83], v[138:141], v[166:169], v[80:83]
	v_mfma_f32_16x16x32_bf16 v[68:71], v[138:141], v[216:219], v[68:71]
	v_mfma_f32_16x16x32_bf16 v[72:75], v[138:141], v[220:223], v[72:75]
	v_mfma_f32_16x16x32_bf16 v[96:99], v[154:157], v[166:169], v[96:99]
	v_mfma_f32_16x16x32_bf16 v[112:115], v[158:161], v[162:165], v[112:115]
	v_mfma_f32_16x16x32_bf16 v[224:227], v[154:157], v[162:165], v[104:107]
	v_mfma_f32_16x16x32_bf16 v[228:231], v[154:157], v[216:219], v[108:111]
	v_mfma_f32_16x16x32_bf16 v[232:235], v[154:157], v[220:223], v[88:91]
	v_mfma_f32_16x16x32_bf16 v[162:165], v[158:161], v[166:169], v[116:119]
	v_mfma_f32_16x16x32_bf16 v[166:169], v[158:161], v[216:219], v[120:123]
	v_mfma_f32_16x16x32_bf16 v[216:219], v[158:161], v[220:223], v[124:127]
	ds_read_b128 v[88:91], v173
	ds_read_b128 v[104:107], v174
	ds_read_b128 v[108:111], v175
	ds_read_b128 v[116:119], v178
	s_waitcnt lgkmcnt(0)
	v_mfma_f32_16x16x32_bf16 v[0:3], v[134:137], v[88:91], v[0:3]
	v_mfma_f32_16x16x32_bf16 v[4:7], v[134:137], v[104:107], v[4:7]
	v_mfma_f32_16x16x32_bf16 v[8:11], v[134:137], v[108:111], v[8:11]
	v_mfma_f32_16x16x32_bf16 v[12:15], v[134:137], v[116:119], v[12:15]
	v_mfma_f32_16x16x32_bf16 v[16:19], v[138:141], v[88:91], v[16:19]
	v_mfma_f32_16x16x32_bf16 v[20:23], v[138:141], v[104:107], v[20:23]
	v_mfma_f32_16x16x32_bf16 v[24:27], v[138:141], v[108:111], v[24:27]
	v_mfma_f32_16x16x32_bf16 v[134:137], v[138:141], v[116:119], v[28:31]
	v_mfma_f32_16x16x32_bf16 v[32:35], v[154:157], v[88:91], v[32:35]
	v_mfma_f32_16x16x32_bf16 v[36:39], v[154:157], v[104:107], v[36:39]
	v_mfma_f32_16x16x32_bf16 v[138:141], v[154:157], v[108:111], v[40:43]
	v_mfma_f32_16x16x32_bf16 v[154:157], v[154:157], v[116:119], v[44:47]
	v_mfma_f32_16x16x32_bf16 v[172:175], v[158:161], v[88:91], v[60:63]
	v_mfma_f32_16x16x32_bf16 v[220:223], v[158:161], v[104:107], v[76:79]
	v_mfma_f32_16x16x32_bf16 v[236:239], v[158:161], v[108:111], v[84:87]
	v_mfma_f32_16x16x32_bf16 v[158:161], v[158:161], v[116:119], v[92:95]
	s_waitcnt vmcnt(0)
	s_barrier
	ds_read_b128 v[40:43], v176
	ds_read_b128 v[28:31], v179
	ds_read_b128 v[44:47], v180
	ds_read_b128 v[60:63], v181
	ds_read_b128 v[240:243], v176 offset:1024
	ds_read_b128 v[244:247], v176 offset:2048
	ds_read_b128 v[248:251], v176 offset:3072
	ds_read_b128 v[178:181], v182
	s_waitcnt lgkmcnt(0)
	v_mfma_f32_16x16x32_bf16 v[124:127], v[40:43], v[28:31], v[56:59]
	v_mfma_f32_16x16x32_bf16 v[108:111], v[40:43], v[44:47], v[64:67]
	v_mfma_f32_16x16x32_bf16 v[92:95], v[40:43], v[60:63], v[52:55]
	v_mfma_f32_16x16x32_bf16 v[76:79], v[40:43], v[178:181], v[48:51]
	v_mfma_f32_16x16x32_bf16 v[120:123], v[240:243], v[28:31], v[100:103]
	v_mfma_f32_16x16x32_bf16 v[104:107], v[240:243], v[44:47], v[80:83]
	v_mfma_f32_16x16x32_bf16 v[88:91], v[240:243], v[60:63], v[68:71]
	v_mfma_f32_16x16x32_bf16 v[72:75], v[240:243], v[178:181], v[72:75]
	v_mfma_f32_16x16x32_bf16 v[116:119], v[244:247], v[28:31], v[224:227]
	v_mfma_f32_16x16x32_bf16 v[100:103], v[244:247], v[44:47], v[96:99]
	v_mfma_f32_16x16x32_bf16 v[84:87], v[244:247], v[60:63], v[228:231]
	v_mfma_f32_16x16x32_bf16 v[68:71], v[244:247], v[178:181], v[232:235]
	v_mfma_f32_16x16x32_bf16 v[112:115], v[248:251], v[28:31], v[112:115]
	v_mfma_f32_16x16x32_bf16 v[96:99], v[248:251], v[44:47], v[162:165]
	v_mfma_f32_16x16x32_bf16 v[80:83], v[248:251], v[60:63], v[166:169]
	v_mfma_f32_16x16x32_bf16 v[64:67], v[248:251], v[178:181], v[216:219]
	ds_read_b128 v[48:51], v142
	ds_read_b128 v[162:165], v143
	s_waitcnt lgkmcnt(0)
	v_mfma_f32_16x16x32_bf16 v[60:63], v[40:43], v[48:51], v[0:3]
	s_nop 2
	ds_read_b128 v[0:3], v144
	ds_read_b128 v[142:145], v145
	v_mfma_f32_16x16x32_bf16 v[44:47], v[40:43], v[162:165], v[4:7]
	s_waitcnt lgkmcnt(0)
	v_mfma_f32_16x16x32_bf16 v[28:31], v[40:43], v[0:3], v[8:11]
	v_mfma_f32_16x16x32_bf16 v[12:15], v[40:43], v[142:145], v[12:15]
	v_mfma_f32_16x16x32_bf16 v[56:59], v[240:243], v[48:51], v[16:19]
	v_mfma_f32_16x16x32_bf16 v[40:43], v[240:243], v[162:165], v[20:23]
	v_mfma_f32_16x16x32_bf16 v[24:27], v[240:243], v[0:3], v[24:27]
	v_mfma_f32_16x16x32_bf16 v[8:11], v[240:243], v[142:145], v[134:137]
	v_mfma_f32_16x16x32_bf16 v[52:55], v[244:247], v[48:51], v[32:35]
	v_mfma_f32_16x16x32_bf16 v[36:39], v[244:247], v[162:165], v[36:39]
	v_mfma_f32_16x16x32_bf16 v[20:23], v[244:247], v[0:3], v[138:141]
	v_mfma_f32_16x16x32_bf16 v[4:7], v[244:247], v[142:145], v[154:157]
	v_mfma_f32_16x16x32_bf16 v[48:51], v[248:251], v[48:51], v[172:175]
	v_mfma_f32_16x16x32_bf16 v[32:35], v[248:251], v[162:165], v[220:223]
	v_mfma_f32_16x16x32_bf16 v[16:19], v[248:251], v[0:3], v[236:239]
	v_mfma_f32_16x16x32_bf16 v[0:3], v[248:251], v[142:145], v[158:161]
	v_mov_b32_e32 v141, v215
	v_lshl_add_u32 v142, s4, 1, v151
	v_and_b32_e32 v140, 15, v141
	v_lshlrev_b32_e32 v134, 1, v141
	v_and_or_b32 v155, v134, s34, v140
	v_lshl_or_b32 v139, v155, 2, v200
	v_and_b32_e32 v134, 16, v141
	v_lshrrev_b32_e32 v138, 2, v141
	ds_read_b32 v146, v139
	v_ashrrev_i32_e32 v136, 7, v141
	v_and_or_b32 v134, v138, 8, v134
	v_lshlrev_b32_e32 v138, 7, v142
	v_lshl_add_u32 v138, v136, 6, v138
	v_bfe_u32 v137, v141, 4, 2
	v_add_u32_e32 v154, 0xfffffe00, v138
	v_or_b32_e32 v138, v138, v134
	v_cmp_lt_i32_e64 s[14:15], 1, v142
	v_cmp_lt_u32_e64 s[12:13], 3, v142
	v_cmp_lt_u32_e64 s[10:11], 5, v142
	v_cmp_ne_u32_e64 s[8:9], 6, v142
	v_cmp_gt_u32_e64 s[6:7], s34, v141
	v_lshlrev_b32_e32 v135, 2, v137
	v_cmp_eq_u32_e64 s[4:5], 0, v137
	v_ashrrev_i32_e32 v137, 31, v136
	v_lshlrev_b32_e32 v152, 1, v142
	v_add_u32_e32 v138, 0xffffff00, v138
	v_or_b32_e32 v144, s48, v155
	s_and_saveexec_b64 s[18:19], s[14:15]
	s_xor_b64 s[36:37], exec, s[18:19]
	s_cbranch_execz .LBB0_323
; __device__ __forceinline__ int widen_off(int fq) { return ((fq & 1) << 4) + ((fq >> 1) << 3); }
; template <int MODE, int NSUB>
; __device__ __forceinline__ void epilogue(const Params& p, int layer, f32x4 (&acc)[4][NSUB], int tm, int tn, int g,
;                                          const float* s_rstd, const int tid_in) {
;     ...
;       } else {
;         if (wr == 0) {
;           const int pos = tok_pos(t);
;           float o1[4], o2[4];
; #pragma unroll
;           for (int j = 0; j < 4; ++j) {
;             float2 cs = p.rope[pos * 16 + fq * 4 + j];
;             float x1 = acc[0][n][j] * rs, x2 = acc[1][n][j] * rs;
;             o1[j] = x1 * cs.x - x2 * cs.y;
;             o2[j] = x1 * cs.y + x2 * cs.x;
;           }
;           const u32x4 w = widen_pair(pack4(o1[0], o1[1], o1[2], o1[3]), pack4(o2[0], o2[1], o2[2], o2[3]));
; #pragma unroll
;           for (int hh = 0; hh < 8; ++hh)
;             __builtin_nontemporal_store(w, reinterpret_cast<u32x4*>(p.Kb + ((long)hh * NT + t) * 96 + 64 + widen_off(fq)));
;         }
	s_and_saveexec_b64 s[18:19], s[12:13]
	s_xor_b64 s[38:39], exec, s[18:19]
	s_cbranch_execz .LBB0_320
	s_and_saveexec_b64 s[18:19], s[10:11]
	s_xor_b64 s[40:41], exec, s[18:19]
	s_cbranch_execz .LBB0_315
	s_and_saveexec_b64 s[18:19], s[8:9]
	s_xor_b64 s[42:43], exec, s[18:19]
	s_cbranch_execz .LBB0_310
	s_and_saveexec_b64 s[44:45], s[6:7]
	s_cbranch_execz .LBB0_309
	s_mov_b32 s17, 0x10000
	v_cmp_gt_i32_e32 vcc, s17, v144
	v_lshlrev_b32_e32 v113, 3, v135
	v_readlane_b32 s64, v254, 51
	v_cndmask_b32_e32 v112, v201, v202, vcc
	v_and_b32_e32 v112, v112, v144
	v_lshl_or_b32 v116, v112, 7, v113
	v_readlane_b32 s70, v254, 57
	v_readlane_b32 s71, v254, 58
	s_nop 4
	global_load_dwordx4 v[112:115], v116, s[70:71] offset:16
	s_nop 0
	global_load_dwordx4 v[116:119], v116, s[70:71]
	v_mov_b32_e32 v161, v121
	v_mov_b32_e32 v121, v125
	v_mov_b32_e32 v160, v124
	s_waitcnt lgkmcnt(0)
	v_pk_mul_f32 v[120:121], v[120:121], v[146:147] op_sel_hi:[1,0]
	v_pk_mul_f32 v[160:161], v[160:161], v[146:147] op_sel_hi:[1,0]
	v_readlane_b32 s65, v254, 52
	v_readlane_b32 s66, v254, 53
	v_readlane_b32 s67, v254, 54
	v_readlane_b32 s68, v254, 55
	v_readlane_b32 s69, v254, 56
	v_readlane_b32 s72, v254, 59
	v_readlane_b32 s73, v254, 60
	v_readlane_b32 s74, v254, 61
	v_readlane_b32 s75, v254, 62
	v_readlane_b32 s76, v254, 63
	v_readlane_b32 s77, v252, 0
	v_readlane_b32 s78, v252, 1
	v_readlane_b32 s79, v252, 2
	v_readlane_b32 s64, v252, 4
	v_readlane_b32 s68, v252, 8
	v_readlane_b32 s69, v252, 9
	s_movk_i32 s17, 0xc0
	v_readlane_b32 s65, v252, 5
	v_readlane_b32 s66, v252, 6
	v_readlane_b32 s67, v252, 7
	v_readlane_b32 s70, v252, 10
	v_readlane_b32 s71, v252, 11
	v_readlane_b32 s72, v252, 12
	v_readlane_b32 s73, v252, 13
	v_readlane_b32 s74, v252, 14
	v_readlane_b32 s75, v252, 15
	v_readlane_b32 s76, v252, 16
	v_readlane_b32 s77, v252, 17
	v_readlane_b32 s78, v252, 18
	v_readlane_b32 s79, v252, 19
	s_waitcnt vmcnt(0)
	v_mov_b32_e32 v159, v114
	v_mov_b32_e32 v124, v116
	v_mov_b32_e32 v125, v119
	v_mov_b32_e32 v156, v117
	v_mov_b32_e32 v157, v118
	v_pk_mul_f32 v[124:125], v[120:121], v[124:125]
	v_mov_b32_e32 v163, v118
	v_pk_fma_f32 v[124:125], v[160:161], v[156:157], v[124:125]
	v_mov_b32_e32 v157, v121
	v_mov_b32_e32 v121, v161
	v_mov_b32_e32 v118, v117
	v_mov_b32_e32 v162, v116
	v_pk_mul_f32 v[116:117], v[120:121], v[118:119]
	v_mov_b32_e32 v118, v126
	v_mov_b32_e32 v119, v123
	v_mov_b32_e32 v123, v127
	v_mov_b32_e32 v156, v160
	v_pk_mul_f32 v[118:119], v[118:119], v[146:147] op_sel_hi:[1,0]
	v_pk_mul_f32 v[120:121], v[122:123], v[146:147] op_sel_hi:[1,0]
	v_mov_b32_e32 v122, v112
	v_mov_b32_e32 v123, v115
	v_pk_fma_f32 v[116:117], v[156:157], v[162:163], v[116:117] neg_lo:[0,0,1] neg_hi:[0,0,1]
	v_pk_mul_f32 v[122:123], v[120:121], v[122:123]
	v_mov_b32_e32 v127, v121
	v_mov_b32_e32 v157, v114
	v_mov_b32_e32 v121, v119
	v_mov_b32_e32 v114, v113
	v_mov_b32_e32 v158, v113
	v_mov_b32_e32 v126, v118
	v_mov_b32_e32 v156, v112
	v_pk_mul_f32 v[112:113], v[120:121], v[114:115]
	v_pk_fma_f32 v[122:123], v[118:119], v[158:159], v[122:123]
	v_pk_fma_f32 v[114:115], v[126:127], v[156:157], v[112:113] neg_lo:[0,0,1] neg_hi:[0,0,1]
	v_cvt_pk_bf16_f32 v112, v116, v117
	v_mov_b64_e32 v[116:117], s[68:69]
	v_mad_i64_i32 v[116:117], s[18:19], v144, s17, v[116:117]
	v_lshlrev_b32_e32 v118, 1, v134
	v_mov_b32_e32 v119, v153
	v_lshl_add_u64 v[116:117], v[116:117], 0, v[118:119]
	s_mov_b32 s17, 0xf00000
	v_cvt_pk_bf16_f32 v113, v114, v115
	v_cvt_pk_bf16_f32 v114, v124, v125
	v_cvt_pk_bf16_f32 v115, v122, v123
	v_add_co_u32_e32 v118, vcc, s17, v116
	v_permlane16_swap_b32_e32 v112, v114
	v_permlane16_swap_b32_e32 v113, v115
	v_addc_co_u32_e32 v119, vcc, 0, v117, vcc
	s_mov_b32 s17, 0x1e00000
	global_store_dwordx4 v[118:119], v[112:115], off offset:128 nt
	v_add_co_u32_e32 v118, vcc, s17, v116
	s_mov_b32 s17, 0x2d00000
	s_nop 0
	v_addc_co_u32_e32 v119, vcc, 0, v117, vcc
	global_store_dwordx4 v[118:119], v[112:115], off offset:128 nt
	v_add_co_u32_e32 v118, vcc, s17, v116
	global_store_dwordx4 v[116:117], v[112:115], off offset:128 nt
	s_nop 0
	v_addc_co_u32_e32 v119, vcc, 0, v117, vcc
	global_store_dwordx4 v[118:119], v[112:115], off offset:128 nt
	v_add_co_u32_e32 v118, vcc, 0x3c00000, v116
	s_nop 1
	v_addc_co_u32_e32 v119, vcc, 0, v117, vcc
	global_store_dwordx4 v[118:119], v[112:115], off offset:128 nt
	v_add_co_u32_e32 v118, vcc, 0x4b00000, v116
	s_nop 1
	v_addc_co_u32_e32 v119, vcc, 0, v117, vcc
	global_store_dwordx4 v[118:119], v[112:115], off offset:128 nt
	v_add_co_u32_e32 v118, vcc, 0x5a00000, v116
	s_nop 1
	v_addc_co_u32_e32 v119, vcc, 0, v117, vcc
	v_add_co_u32_e32 v116, vcc, 0x6900000, v116
	global_store_dwordx4 v[118:119], v[112:115], off offset:128 nt
	s_nop 0
	v_addc_co_u32_e32 v117, vcc, 0, v117, vcc
	global_store_dwordx4 v[116:117], v[112:115], off offset:128 nt
